# v16 + GEMM K-loops: loading half issues its ds_read/LDS-DMA burst at priority 2 (above the MFMA half), drops to 0 before its waits
# baseline (speedup 1.0000x reference)
.LBB0_849:
	ds_read_b128 v[146:149], v155
	ds_read_b128 v[160:163], v155 offset:1024
	ds_read_b128 v[164:167], v155 offset:2048
	ds_read_b128 v[168:171], v155 offset:3072
	ds_read_b128 v[172:175], v156
	ds_read_b128 v[176:179], v156 offset:1024
	ds_read_b128 v[180:183], v156 offset:2048
	ds_read_b128 v[184:187], v156 offset:3072
	s_add_u32 s74, s72, 0xfff80080
	s_addc_u32 s75, s73, -1
	s_cmp_eq_u32 s85, 28
	s_cselect_b32 s77, s63, s75
	s_cselect_b32 s76, s69, s74
	s_cselect_b32 s75, s57, s84
	s_cselect_b32 s74, s71, s83
	v_lshl_add_u64 v[220:221], s[72:73], 0, v[138:139]
	s_add_i32 m0, s3, 0xc000
	ds_read_b128 v[188:191], v157
	ds_read_b128 v[192:195], v157 offset:1024
	ds_read_b128 v[196:199], v157 offset:2048
	ds_read_b128 v[200:203], v157 offset:3072
	ds_read_b128 v[204:207], v157 offset:4096
	ds_read_b128 v[208:211], v157 offset:5120
	ds_read_b128 v[212:215], v157 offset:6144
	ds_read_b128 v[216:219], v157 offset:7168
	global_load_lds_dwordx4 v[220:221], off
	v_lshl_add_u64 v[220:221], s[72:73], 0, v[140:141]
	s_add_i32 m0, s3, 0xe000
	s_nop 0
	global_load_lds_dwordx4 v[220:221], off
	s_waitcnt vmcnt(8)
	s_waitcnt lgkmcnt(0)
	s_barrier
	s_setprio 1
	s_waitcnt lgkmcnt(0)
	v_mfma_f32_16x16x32_bf16 v[124:127], v[146:149], v[188:191], v[124:127]
	v_mfma_f32_16x16x32_bf16 v[120:123], v[164:167], v[188:191], v[120:123]
	v_mfma_f32_16x16x32_bf16 v[108:111], v[146:149], v[196:199], v[108:111]
	v_mfma_f32_16x16x32_bf16 v[104:107], v[164:167], v[196:199], v[104:107]
	v_mfma_f32_16x16x32_bf16 v[92:95], v[146:149], v[204:207], v[92:95]
	v_mfma_f32_16x16x32_bf16 v[88:91], v[164:167], v[204:207], v[88:91]
	v_mfma_f32_16x16x32_bf16 v[76:79], v[146:149], v[212:215], v[76:79]
	v_mfma_f32_16x16x32_bf16 v[72:75], v[164:167], v[212:215], v[72:75]
	v_mfma_f32_16x16x32_bf16 v[124:127], v[160:163], v[192:195], v[124:127]
	v_mfma_f32_16x16x32_bf16 v[120:123], v[168:171], v[192:195], v[120:123]
	v_mfma_f32_16x16x32_bf16 v[108:111], v[160:163], v[200:203], v[108:111]
	v_mfma_f32_16x16x32_bf16 v[104:107], v[168:171], v[200:203], v[104:107]
	v_mfma_f32_16x16x32_bf16 v[92:95], v[160:163], v[208:211], v[92:95]
	v_mfma_f32_16x16x32_bf16 v[88:91], v[168:171], v[208:211], v[88:91]
	v_mfma_f32_16x16x32_bf16 v[76:79], v[160:163], v[216:219], v[76:79]
	v_mfma_f32_16x16x32_bf16 v[72:75], v[168:171], v[216:219], v[72:75]
	v_mfma_f32_16x16x32_bf16 v[116:119], v[172:175], v[188:191], v[116:119]
	v_mfma_f32_16x16x32_bf16 v[112:115], v[180:183], v[188:191], v[112:115]
	v_mfma_f32_16x16x32_bf16 v[100:103], v[172:175], v[196:199], v[100:103]
	v_mfma_f32_16x16x32_bf16 v[96:99], v[180:183], v[196:199], v[96:99]
	v_mfma_f32_16x16x32_bf16 v[84:87], v[172:175], v[204:207], v[84:87]
	v_mfma_f32_16x16x32_bf16 v[80:83], v[180:183], v[204:207], v[80:83]
	v_mfma_f32_16x16x32_bf16 v[68:71], v[172:175], v[212:215], v[68:71]
	v_mfma_f32_16x16x32_bf16 v[64:67], v[180:183], v[212:215], v[64:67]
	v_mfma_f32_16x16x32_bf16 v[116:119], v[176:179], v[192:195], v[116:119]
	v_mfma_f32_16x16x32_bf16 v[112:115], v[184:187], v[192:195], v[112:115]
	v_mfma_f32_16x16x32_bf16 v[100:103], v[176:179], v[200:203], v[100:103]
	v_mfma_f32_16x16x32_bf16 v[96:99], v[184:187], v[200:203], v[96:99]
	v_mfma_f32_16x16x32_bf16 v[84:87], v[176:179], v[208:211], v[84:87]
	v_mfma_f32_16x16x32_bf16 v[80:83], v[184:187], v[208:211], v[80:83]
	v_mfma_f32_16x16x32_bf16 v[68:71], v[176:179], v[216:219], v[68:71]
	v_mfma_f32_16x16x32_bf16 v[64:67], v[184:187], v[216:219], v[64:67]
	s_setprio 0
	s_barrier
	s_setprio 2
	s_add_i32 s86, s79, s94
	v_lshl_add_u64 v[220:221], s[74:75], 0, v[130:131]
	s_mov_b32 m0, s86
	ds_read_b128 v[188:191], v157 offset:16384
	ds_read_b128 v[192:195], v157 offset:17408
	ds_read_b128 v[196:199], v157 offset:18432
	ds_read_b128 v[200:203], v157 offset:19456
	ds_read_b128 v[204:207], v157 offset:20480
	ds_read_b128 v[208:211], v157 offset:21504
	ds_read_b128 v[212:215], v157 offset:22528
	ds_read_b128 v[216:219], v157 offset:23552
	global_load_lds_dwordx4 v[220:221], off
	s_add_i32 m0, s86, 0x2000
	s_add_u32 s86, s74, 0x80000
	v_lshl_add_u64 v[222:223], s[74:75], 0, v[134:135]
	s_addc_u32 s87, s75, 0
	s_add_i32 s88, s81, s94
	global_load_lds_dwordx4 v[222:223], off
	v_lshl_add_u64 v[224:225], s[86:87], 0, v[130:131]
	s_mov_b32 m0, s88
	v_lshl_add_u64 v[226:227], s[76:77], 0, v[132:133]
	global_load_lds_dwordx4 v[224:225], off
	v_lshl_add_u64 v[224:225], s[86:87], 0, v[134:135]
	s_add_i32 m0, s88, 0x2000
	s_nop 0
	global_load_lds_dwordx4 v[224:225], off
	v_lshl_add_u64 v[224:225], s[76:77], 0, v[128:129]
	s_mov_b32 m0, s3
	s_nop 0
	global_load_lds_dwordx4 v[224:225], off
	s_mov_b32 m0, s6
	s_nop 0
	global_load_lds_dwordx4 v[226:227], off
	s_setprio 0
	s_waitcnt vmcnt(8)
	s_waitcnt lgkmcnt(0)
	s_barrier
	s_setprio 1
	s_waitcnt lgkmcnt(0)
	v_mfma_f32_16x16x32_bf16 v[60:63], v[146:149], v[188:191], v[60:63]
	v_mfma_f32_16x16x32_bf16 v[56:59], v[164:167], v[188:191], v[56:59]
	v_mfma_f32_16x16x32_bf16 v[44:47], v[146:149], v[196:199], v[44:47]
	v_mfma_f32_16x16x32_bf16 v[40:43], v[164:167], v[196:199], v[40:43]
	v_mfma_f32_16x16x32_bf16 v[28:31], v[146:149], v[204:207], v[28:31]
	v_mfma_f32_16x16x32_bf16 v[24:27], v[164:167], v[204:207], v[24:27]
	v_mfma_f32_16x16x32_bf16 v[12:15], v[146:149], v[212:215], v[12:15]
	v_mfma_f32_16x16x32_bf16 v[8:11], v[164:167], v[212:215], v[8:11]
	v_mfma_f32_16x16x32_bf16 v[60:63], v[160:163], v[192:195], v[60:63]
	v_mfma_f32_16x16x32_bf16 v[56:59], v[168:171], v[192:195], v[56:59]
	v_mfma_f32_16x16x32_bf16 v[44:47], v[160:163], v[200:203], v[44:47]
	v_mfma_f32_16x16x32_bf16 v[40:43], v[168:171], v[200:203], v[40:43]
	v_mfma_f32_16x16x32_bf16 v[28:31], v[160:163], v[208:211], v[28:31]
	v_mfma_f32_16x16x32_bf16 v[24:27], v[168:171], v[208:211], v[24:27]
	v_mfma_f32_16x16x32_bf16 v[12:15], v[160:163], v[216:219], v[12:15]
	v_mfma_f32_16x16x32_bf16 v[8:11], v[168:171], v[216:219], v[8:11]
	v_mfma_f32_16x16x32_bf16 v[52:55], v[172:175], v[188:191], v[52:55]
	v_mfma_f32_16x16x32_bf16 v[48:51], v[180:183], v[188:191], v[48:51]
	v_mfma_f32_16x16x32_bf16 v[36:39], v[172:175], v[196:199], v[36:39]
	v_mfma_f32_16x16x32_bf16 v[32:35], v[180:183], v[196:199], v[32:35]
	v_mfma_f32_16x16x32_bf16 v[20:23], v[172:175], v[204:207], v[20:23]
	v_mfma_f32_16x16x32_bf16 v[16:19], v[180:183], v[204:207], v[16:19]
	v_mfma_f32_16x16x32_bf16 v[4:7], v[172:175], v[212:215], v[4:7]
	v_mfma_f32_16x16x32_bf16 v[0:3], v[180:183], v[212:215], v[0:3]
	v_mfma_f32_16x16x32_bf16 v[52:55], v[176:179], v[192:195], v[52:55]
	v_mfma_f32_16x16x32_bf16 v[48:51], v[184:187], v[192:195], v[48:51]
	v_mfma_f32_16x16x32_bf16 v[36:39], v[176:179], v[200:203], v[36:39]
	v_mfma_f32_16x16x32_bf16 v[32:35], v[184:187], v[200:203], v[32:35]
	v_mfma_f32_16x16x32_bf16 v[20:23], v[176:179], v[208:211], v[20:23]
	v_mfma_f32_16x16x32_bf16 v[16:19], v[184:187], v[208:211], v[16:19]
	v_mfma_f32_16x16x32_bf16 v[4:7], v[176:179], v[216:219], v[4:7]
	v_mfma_f32_16x16x32_bf16 v[0:3], v[184:187], v[216:219], v[0:3]
	s_setprio 0
	s_barrier
	s_setprio 2
	s_add_i32 s86, 0, 0x18000
	v_add_u32_e32 v159, s86, v151
	s_add_i32 s87, 0, 0x1c000
	ds_read_b128 v[146:149], v159
	ds_read_b128 v[160:163], v159 offset:1024
	ds_read_b128 v[164:167], v159 offset:2048
	ds_read_b128 v[168:171], v159 offset:3072
	v_add_u32_e32 v159, s87, v151
	ds_read_b128 v[172:175], v159
	ds_read_b128 v[176:179], v159 offset:1024
	ds_read_b128 v[180:183], v159 offset:2048
	ds_read_b128 v[184:187], v159 offset:3072
	s_add_u32 s76, s76, 0x80000
	s_addc_u32 s77, s77, 0
	s_mov_b32 m0, s7
	v_lshl_add_u64 v[228:229], s[76:77], 0, v[128:129]
	ds_read_b128 v[188:191], v157 offset:32768
	ds_read_b128 v[192:195], v157 offset:33792
	ds_read_b128 v[196:199], v157 offset:34816
	ds_read_b128 v[200:203], v157 offset:35840
	ds_read_b128 v[204:207], v157 offset:36864
	ds_read_b128 v[208:211], v157 offset:37888
	ds_read_b128 v[212:215], v157 offset:38912
	ds_read_b128 v[216:219], v157 offset:39936
	global_load_lds_dwordx4 v[228:229], off
	v_lshl_add_u64 v[228:229], s[76:77], 0, v[132:133]
	s_mov_b32 m0, s29
	s_nop 0
	global_load_lds_dwordx4 v[228:229], off
	s_setprio 0
	s_waitcnt vmcnt(8)
	s_waitcnt lgkmcnt(0)
	s_barrier
	s_setprio 1
	s_waitcnt lgkmcnt(0)
	v_mfma_f32_16x16x32_bf16 v[124:127], v[146:149], v[188:191], v[124:127]
	v_mfma_f32_16x16x32_bf16 v[120:123], v[164:167], v[188:191], v[120:123]
	v_mfma_f32_16x16x32_bf16 v[108:111], v[146:149], v[196:199], v[108:111]
	v_mfma_f32_16x16x32_bf16 v[104:107], v[164:167], v[196:199], v[104:107]
	v_mfma_f32_16x16x32_bf16 v[92:95], v[146:149], v[204:207], v[92:95]
	v_mfma_f32_16x16x32_bf16 v[88:91], v[164:167], v[204:207], v[88:91]
	v_mfma_f32_16x16x32_bf16 v[76:79], v[146:149], v[212:215], v[76:79]
	v_mfma_f32_16x16x32_bf16 v[72:75], v[164:167], v[212:215], v[72:75]
	v_mfma_f32_16x16x32_bf16 v[124:127], v[160:163], v[192:195], v[124:127]
	v_mfma_f32_16x16x32_bf16 v[120:123], v[168:171], v[192:195], v[120:123]
	v_mfma_f32_16x16x32_bf16 v[108:111], v[160:163], v[200:203], v[108:111]
	v_mfma_f32_16x16x32_bf16 v[104:107], v[168:171], v[200:203], v[104:107]
	v_mfma_f32_16x16x32_bf16 v[92:95], v[160:163], v[208:211], v[92:95]
	v_mfma_f32_16x16x32_bf16 v[88:91], v[168:171], v[208:211], v[88:91]
	v_mfma_f32_16x16x32_bf16 v[76:79], v[160:163], v[216:219], v[76:79]
	v_mfma_f32_16x16x32_bf16 v[72:75], v[168:171], v[216:219], v[72:75]
	v_mfma_f32_16x16x32_bf16 v[116:119], v[172:175], v[188:191], v[116:119]
	v_mfma_f32_16x16x32_bf16 v[112:115], v[180:183], v[188:191], v[112:115]
	v_mfma_f32_16x16x32_bf16 v[100:103], v[172:175], v[196:199], v[100:103]
	v_mfma_f32_16x16x32_bf16 v[96:99], v[180:183], v[196:199], v[96:99]
	v_mfma_f32_16x16x32_bf16 v[84:87], v[172:175], v[204:207], v[84:87]
	v_mfma_f32_16x16x32_bf16 v[80:83], v[180:183], v[204:207], v[80:83]
	v_mfma_f32_16x16x32_bf16 v[68:71], v[172:175], v[212:215], v[68:71]
	v_mfma_f32_16x16x32_bf16 v[64:67], v[180:183], v[212:215], v[64:67]
	v_mfma_f32_16x16x32_bf16 v[116:119], v[176:179], v[192:195], v[116:119]
	v_mfma_f32_16x16x32_bf16 v[112:115], v[184:187], v[192:195], v[112:115]
	v_mfma_f32_16x16x32_bf16 v[100:103], v[176:179], v[200:203], v[100:103]
	v_mfma_f32_16x16x32_bf16 v[96:99], v[184:187], v[200:203], v[96:99]
	v_mfma_f32_16x16x32_bf16 v[84:87], v[176:179], v[208:211], v[84:87]
	v_mfma_f32_16x16x32_bf16 v[80:83], v[184:187], v[208:211], v[80:83]
	v_mfma_f32_16x16x32_bf16 v[68:71], v[176:179], v[216:219], v[68:71]
	v_mfma_f32_16x16x32_bf16 v[64:67], v[184:187], v[216:219], v[64:67]
	s_setprio 0
	s_barrier
	s_setprio 2
	s_add_i32 s76, s86, s94
	v_lshl_add_u64 v[220:221], v[220:221], 0, s[18:19]
	s_mov_b32 m0, s76
	ds_read_b128 v[188:191], v157 offset:49152
	ds_read_b128 v[192:195], v157 offset:50176
	ds_read_b128 v[196:199], v157 offset:51200
	ds_read_b128 v[200:203], v157 offset:52224
	ds_read_b128 v[204:207], v157 offset:53248
	ds_read_b128 v[208:211], v157 offset:54272
	ds_read_b128 v[212:215], v157 offset:55296
	ds_read_b128 v[216:219], v157 offset:56320
	global_load_lds_dwordx4 v[220:221], off
	s_add_i32 m0, s76, 0x2000
	s_add_u32 s74, s74, 0x80080
	v_lshl_add_u64 v[220:221], v[222:223], 0, s[18:19]
	s_addc_u32 s75, s75, 0
	s_add_i32 s76, s87, s94
	global_load_lds_dwordx4 v[220:221], off
	v_lshl_add_u64 v[220:221], s[74:75], 0, v[130:131]
	s_mov_b32 m0, s76
	s_nop 0
	global_load_lds_dwordx4 v[220:221], off
	v_lshl_add_u64 v[220:221], s[74:75], 0, v[134:135]
	s_add_i32 m0, s76, 0x2000
	s_nop 0
	global_load_lds_dwordx4 v[220:221], off
	v_lshl_add_u64 v[220:221], v[224:225], 0, s[18:19]
	s_mov_b32 m0, s34
	s_nop 0
	global_load_lds_dwordx4 v[220:221], off
	v_lshl_add_u64 v[220:221], v[226:227], 0, s[18:19]
	s_mov_b32 m0, s35
	s_nop 0
	global_load_lds_dwordx4 v[220:221], off
	s_setprio 0
	s_waitcnt vmcnt(8)
	s_waitcnt lgkmcnt(0)
	s_barrier
	s_setprio 1
	s_waitcnt lgkmcnt(0)
	v_mfma_f32_16x16x32_bf16 v[60:63], v[146:149], v[188:191], v[60:63]
	v_mfma_f32_16x16x32_bf16 v[56:59], v[164:167], v[188:191], v[56:59]
	v_mfma_f32_16x16x32_bf16 v[44:47], v[146:149], v[196:199], v[44:47]
	v_mfma_f32_16x16x32_bf16 v[40:43], v[164:167], v[196:199], v[40:43]
	v_mfma_f32_16x16x32_bf16 v[28:31], v[146:149], v[204:207], v[28:31]
	v_mfma_f32_16x16x32_bf16 v[24:27], v[164:167], v[204:207], v[24:27]
	v_mfma_f32_16x16x32_bf16 v[12:15], v[146:149], v[212:215], v[12:15]
	v_mfma_f32_16x16x32_bf16 v[8:11], v[164:167], v[212:215], v[8:11]
	v_mfma_f32_16x16x32_bf16 v[60:63], v[160:163], v[192:195], v[60:63]
	v_mfma_f32_16x16x32_bf16 v[56:59], v[168:171], v[192:195], v[56:59]
	v_mfma_f32_16x16x32_bf16 v[44:47], v[160:163], v[200:203], v[44:47]
	v_mfma_f32_16x16x32_bf16 v[40:43], v[168:171], v[200:203], v[40:43]
	v_mfma_f32_16x16x32_bf16 v[28:31], v[160:163], v[208:211], v[28:31]
	v_mfma_f32_16x16x32_bf16 v[24:27], v[168:171], v[208:211], v[24:27]
	v_mfma_f32_16x16x32_bf16 v[12:15], v[160:163], v[216:219], v[12:15]
	v_mfma_f32_16x16x32_bf16 v[8:11], v[168:171], v[216:219], v[8:11]
	v_mfma_f32_16x16x32_bf16 v[52:55], v[172:175], v[188:191], v[52:55]
	v_mfma_f32_16x16x32_bf16 v[48:51], v[180:183], v[188:191], v[48:51]
	v_mfma_f32_16x16x32_bf16 v[36:39], v[172:175], v[196:199], v[36:39]
	v_mfma_f32_16x16x32_bf16 v[32:35], v[180:183], v[196:199], v[32:35]
	v_mfma_f32_16x16x32_bf16 v[20:23], v[172:175], v[204:207], v[20:23]
	v_mfma_f32_16x16x32_bf16 v[16:19], v[180:183], v[204:207], v[16:19]
	v_mfma_f32_16x16x32_bf16 v[4:7], v[172:175], v[212:215], v[4:7]
	v_mfma_f32_16x16x32_bf16 v[0:3], v[180:183], v[212:215], v[0:3]
	v_mfma_f32_16x16x32_bf16 v[52:55], v[176:179], v[192:195], v[52:55]
	v_mfma_f32_16x16x32_bf16 v[48:51], v[184:187], v[192:195], v[48:51]
	v_mfma_f32_16x16x32_bf16 v[36:39], v[176:179], v[200:203], v[36:39]
	v_mfma_f32_16x16x32_bf16 v[32:35], v[184:187], v[200:203], v[32:35]
	v_mfma_f32_16x16x32_bf16 v[20:23], v[176:179], v[208:211], v[20:23]
	v_mfma_f32_16x16x32_bf16 v[16:19], v[184:187], v[208:211], v[16:19]
	v_mfma_f32_16x16x32_bf16 v[4:7], v[176:179], v[216:219], v[4:7]
	v_mfma_f32_16x16x32_bf16 v[0:3], v[184:187], v[216:219], v[0:3]
	s_setprio 0
	s_barrier
	s_setprio 2
	s_add_i32 s85, s85, 2
	s_add_u32 s72, s72, 0x100
	s_addc_u32 s73, s73, 0
	s_add_u32 s83, s83, 0x100
	s_addc_u32 s84, s84, 0
	s_cmp_gt_u32 s85, 29
	s_cbranch_scc0 .LBB0_849
	s_setprio 0
	s_and_b64 vcc, exec, s[20:21]
	s_cbranch_vccz .LBB0_852
	s_barrier

.LBB0_946:
	ds_read_b128 v[148:151], v143
	ds_read_b128 v[152:155], v143 offset:1024
	ds_read_b128 v[156:159], v143 offset:2048
	ds_read_b128 v[160:163], v143 offset:3072
	ds_read_b128 v[164:167], v144
	ds_read_b128 v[168:171], v144 offset:1024
	ds_read_b128 v[172:175], v144 offset:2048
	ds_read_b128 v[176:179], v144 offset:3072
	s_add_u32 s18, s14, s16
	s_addc_u32 s19, s15, s17
	s_add_u32 s18, s18, 0x7498100
	s_addc_u32 s19, s19, 0
	s_add_u32 s20, s24, s16
	s_addc_u32 s21, s25, s17
	s_add_u32 s69, s20, 0x1308100
	s_addc_u32 s70, s21, 0
	s_cmpk_eq_i32 s16, 0xf00
	s_cselect_b32 s21, s11, s19
	s_cselect_b32 s20, s10, s18
	s_cselect_b32 s19, s9, s70
	s_cselect_b32 s18, s8, s69
	s_mov_b32 m0, s46
	v_lshl_add_u64 v[212:213], v[136:137], 0, s[16:17]
	ds_read_b128 v[180:183], v145
	ds_read_b128 v[184:187], v145 offset:1024
	ds_read_b128 v[188:191], v145 offset:2048
	ds_read_b128 v[192:195], v145 offset:3072
	ds_read_b128 v[196:199], v145 offset:4096
	ds_read_b128 v[200:203], v145 offset:5120
	ds_read_b128 v[204:207], v145 offset:6144
	ds_read_b128 v[208:211], v145 offset:7168
	global_load_lds_dwordx4 v[212:213], off
	v_lshl_add_u64 v[212:213], v[138:139], 0, s[16:17]
	s_mov_b32 m0, s56
	s_nop 0
	global_load_lds_dwordx4 v[212:213], off
	s_waitcnt vmcnt(8)
	s_waitcnt lgkmcnt(0)
	s_barrier
	s_setprio 1
	s_waitcnt lgkmcnt(0)
	v_mfma_f32_16x16x32_bf16 v[124:127], v[148:151], v[180:183], v[124:127]
	v_mfma_f32_16x16x32_bf16 v[120:123], v[156:159], v[180:183], v[120:123]
	v_mfma_f32_16x16x32_bf16 v[108:111], v[148:151], v[188:191], v[108:111]
	v_mfma_f32_16x16x32_bf16 v[104:107], v[156:159], v[188:191], v[104:107]
	v_mfma_f32_16x16x32_bf16 v[92:95], v[148:151], v[196:199], v[92:95]
	v_mfma_f32_16x16x32_bf16 v[88:91], v[156:159], v[196:199], v[88:91]
	v_mfma_f32_16x16x32_bf16 v[76:79], v[148:151], v[204:207], v[76:79]
	v_mfma_f32_16x16x32_bf16 v[72:75], v[156:159], v[204:207], v[72:75]
	v_mfma_f32_16x16x32_bf16 v[124:127], v[152:155], v[184:187], v[124:127]
	v_mfma_f32_16x16x32_bf16 v[120:123], v[160:163], v[184:187], v[120:123]
	v_mfma_f32_16x16x32_bf16 v[108:111], v[152:155], v[192:195], v[108:111]
	v_mfma_f32_16x16x32_bf16 v[104:107], v[160:163], v[192:195], v[104:107]
	v_mfma_f32_16x16x32_bf16 v[92:95], v[152:155], v[200:203], v[92:95]
	v_mfma_f32_16x16x32_bf16 v[88:91], v[160:163], v[200:203], v[88:91]
	v_mfma_f32_16x16x32_bf16 v[76:79], v[152:155], v[208:211], v[76:79]
	v_mfma_f32_16x16x32_bf16 v[72:75], v[160:163], v[208:211], v[72:75]
	v_mfma_f32_16x16x32_bf16 v[116:119], v[164:167], v[180:183], v[116:119]
	v_mfma_f32_16x16x32_bf16 v[112:115], v[172:175], v[180:183], v[112:115]
	v_mfma_f32_16x16x32_bf16 v[100:103], v[164:167], v[188:191], v[100:103]
	v_mfma_f32_16x16x32_bf16 v[96:99], v[172:175], v[188:191], v[96:99]
	v_mfma_f32_16x16x32_bf16 v[84:87], v[164:167], v[196:199], v[84:87]
	v_mfma_f32_16x16x32_bf16 v[80:83], v[172:175], v[196:199], v[80:83]
	v_mfma_f32_16x16x32_bf16 v[68:71], v[164:167], v[204:207], v[68:71]
	v_mfma_f32_16x16x32_bf16 v[64:67], v[172:175], v[204:207], v[64:67]
	v_mfma_f32_16x16x32_bf16 v[116:119], v[168:171], v[184:187], v[116:119]
	v_mfma_f32_16x16x32_bf16 v[112:115], v[176:179], v[184:187], v[112:115]
	v_mfma_f32_16x16x32_bf16 v[100:103], v[168:171], v[192:195], v[100:103]
	v_mfma_f32_16x16x32_bf16 v[96:99], v[176:179], v[192:195], v[96:99]
	v_mfma_f32_16x16x32_bf16 v[84:87], v[168:171], v[200:203], v[84:87]
	v_mfma_f32_16x16x32_bf16 v[80:83], v[176:179], v[200:203], v[80:83]
	v_mfma_f32_16x16x32_bf16 v[68:71], v[168:171], v[208:211], v[68:71]
	v_mfma_f32_16x16x32_bf16 v[64:67], v[176:179], v[208:211], v[64:67]
	s_setprio 0
	s_barrier
	s_setprio 2
	s_mov_b32 m0, s57
	v_lshl_add_u64 v[212:213], s[18:19], 0, v[132:133]
	s_add_u32 s70, s18, 0x80000
	ds_read_b128 v[180:183], v145 offset:16384
	ds_read_b128 v[184:187], v145 offset:17408
	ds_read_b128 v[188:191], v145 offset:18432
	ds_read_b128 v[192:195], v145 offset:19456
	ds_read_b128 v[196:199], v145 offset:20480
	ds_read_b128 v[200:203], v145 offset:21504
	ds_read_b128 v[204:207], v145 offset:22528
	ds_read_b128 v[208:211], v145 offset:23552
	global_load_lds_dwordx4 v[212:213], off
	v_lshl_add_u64 v[214:215], s[18:19], 0, v[128:129]
	s_mov_b32 m0, s62
	s_addc_u32 s71, s19, 0
	global_load_lds_dwordx4 v[214:215], off
	v_lshl_add_u64 v[216:217], s[70:71], 0, v[132:133]
	s_mov_b32 m0, s63
	v_lshl_add_u64 v[218:219], s[20:21], 0, v[130:131]
	global_load_lds_dwordx4 v[216:217], off
	v_lshl_add_u64 v[216:217], s[70:71], 0, v[128:129]
	s_mov_b32 m0, s64
	s_nop 0
	global_load_lds_dwordx4 v[216:217], off
	v_lshl_add_u64 v[216:217], s[20:21], 0, v[134:135]
	s_mov_b32 m0, s3
	s_nop 0
	global_load_lds_dwordx4 v[216:217], off
	s_mov_b32 m0, s6
	s_nop 0
	global_load_lds_dwordx4 v[218:219], off
	s_setprio 0
	s_waitcnt vmcnt(8)
	s_waitcnt lgkmcnt(0)
	s_barrier
	s_setprio 1
	s_waitcnt lgkmcnt(0)
	v_mfma_f32_16x16x32_bf16 v[60:63], v[148:151], v[180:183], v[60:63]
	v_mfma_f32_16x16x32_bf16 v[56:59], v[156:159], v[180:183], v[56:59]
	v_mfma_f32_16x16x32_bf16 v[44:47], v[148:151], v[188:191], v[44:47]
	v_mfma_f32_16x16x32_bf16 v[40:43], v[156:159], v[188:191], v[40:43]
	v_mfma_f32_16x16x32_bf16 v[28:31], v[148:151], v[196:199], v[28:31]
	v_mfma_f32_16x16x32_bf16 v[24:27], v[156:159], v[196:199], v[24:27]
	v_mfma_f32_16x16x32_bf16 v[12:15], v[148:151], v[204:207], v[12:15]
	v_mfma_f32_16x16x32_bf16 v[8:11], v[156:159], v[204:207], v[8:11]
	v_mfma_f32_16x16x32_bf16 v[60:63], v[152:155], v[184:187], v[60:63]
	v_mfma_f32_16x16x32_bf16 v[56:59], v[160:163], v[184:187], v[56:59]
	v_mfma_f32_16x16x32_bf16 v[44:47], v[152:155], v[192:195], v[44:47]
	v_mfma_f32_16x16x32_bf16 v[40:43], v[160:163], v[192:195], v[40:43]
	v_mfma_f32_16x16x32_bf16 v[28:31], v[152:155], v[200:203], v[28:31]
	v_mfma_f32_16x16x32_bf16 v[24:27], v[160:163], v[200:203], v[24:27]
	v_mfma_f32_16x16x32_bf16 v[12:15], v[152:155], v[208:211], v[12:15]
	v_mfma_f32_16x16x32_bf16 v[8:11], v[160:163], v[208:211], v[8:11]
	v_mfma_f32_16x16x32_bf16 v[52:55], v[164:167], v[180:183], v[52:55]
	v_mfma_f32_16x16x32_bf16 v[48:51], v[172:175], v[180:183], v[48:51]
	v_mfma_f32_16x16x32_bf16 v[36:39], v[164:167], v[188:191], v[36:39]
	v_mfma_f32_16x16x32_bf16 v[32:35], v[172:175], v[188:191], v[32:35]
	v_mfma_f32_16x16x32_bf16 v[20:23], v[164:167], v[196:199], v[20:23]
	v_mfma_f32_16x16x32_bf16 v[16:19], v[172:175], v[196:199], v[16:19]
	v_mfma_f32_16x16x32_bf16 v[4:7], v[164:167], v[204:207], v[4:7]
	v_mfma_f32_16x16x32_bf16 v[0:3], v[172:175], v[204:207], v[0:3]
	v_mfma_f32_16x16x32_bf16 v[52:55], v[168:171], v[184:187], v[52:55]
	v_mfma_f32_16x16x32_bf16 v[48:51], v[176:179], v[184:187], v[48:51]
	v_mfma_f32_16x16x32_bf16 v[36:39], v[168:171], v[192:195], v[36:39]
	v_mfma_f32_16x16x32_bf16 v[32:35], v[176:179], v[192:195], v[32:35]
	v_mfma_f32_16x16x32_bf16 v[20:23], v[168:171], v[200:203], v[20:23]
	v_mfma_f32_16x16x32_bf16 v[16:19], v[176:179], v[200:203], v[16:19]
	v_mfma_f32_16x16x32_bf16 v[4:7], v[168:171], v[208:211], v[4:7]
	v_mfma_f32_16x16x32_bf16 v[0:3], v[176:179], v[208:211], v[0:3]
	s_setprio 0
	s_barrier
	s_setprio 2
	ds_read_b128 v[148:151], v146
	ds_read_b128 v[152:155], v146 offset:1024
	ds_read_b128 v[156:159], v146 offset:2048
	ds_read_b128 v[160:163], v146 offset:3072
	ds_read_b128 v[164:167], v147
	ds_read_b128 v[168:171], v147 offset:1024
	ds_read_b128 v[172:175], v147 offset:2048
	ds_read_b128 v[176:179], v147 offset:3072
	s_add_u32 s20, s20, 0x80000
	s_addc_u32 s21, s21, 0
	s_mov_b32 m0, s7
	v_lshl_add_u64 v[220:221], s[20:21], 0, v[134:135]
	ds_read_b128 v[180:183], v145 offset:32768
	ds_read_b128 v[184:187], v145 offset:33792
	ds_read_b128 v[188:191], v145 offset:34816
	ds_read_b128 v[192:195], v145 offset:35840
	ds_read_b128 v[196:199], v145 offset:36864
	ds_read_b128 v[200:203], v145 offset:37888
	ds_read_b128 v[204:207], v145 offset:38912
	ds_read_b128 v[208:211], v145 offset:39936
	global_load_lds_dwordx4 v[220:221], off
	v_lshl_add_u64 v[220:221], s[20:21], 0, v[130:131]
	s_mov_b32 m0, s29
	s_nop 0
	global_load_lds_dwordx4 v[220:221], off
	s_setprio 0
	s_waitcnt vmcnt(8)
	s_waitcnt lgkmcnt(0)
	s_barrier
	s_setprio 1
	s_waitcnt lgkmcnt(0)
	v_mfma_f32_16x16x32_bf16 v[124:127], v[148:151], v[180:183], v[124:127]
	v_mfma_f32_16x16x32_bf16 v[120:123], v[156:159], v[180:183], v[120:123]
	v_mfma_f32_16x16x32_bf16 v[108:111], v[148:151], v[188:191], v[108:111]
	v_mfma_f32_16x16x32_bf16 v[104:107], v[156:159], v[188:191], v[104:107]
	v_mfma_f32_16x16x32_bf16 v[92:95], v[148:151], v[196:199], v[92:95]
	v_mfma_f32_16x16x32_bf16 v[88:91], v[156:159], v[196:199], v[88:91]
	v_mfma_f32_16x16x32_bf16 v[76:79], v[148:151], v[204:207], v[76:79]
	v_mfma_f32_16x16x32_bf16 v[72:75], v[156:159], v[204:207], v[72:75]
	v_mfma_f32_16x16x32_bf16 v[124:127], v[152:155], v[184:187], v[124:127]
	v_mfma_f32_16x16x32_bf16 v[120:123], v[160:163], v[184:187], v[120:123]
	v_mfma_f32_16x16x32_bf16 v[108:111], v[152:155], v[192:195], v[108:111]
	v_mfma_f32_16x16x32_bf16 v[104:107], v[160:163], v[192:195], v[104:107]
	v_mfma_f32_16x16x32_bf16 v[92:95], v[152:155], v[200:203], v[92:95]
	v_mfma_f32_16x16x32_bf16 v[88:91], v[160:163], v[200:203], v[88:91]
	v_mfma_f32_16x16x32_bf16 v[76:79], v[152:155], v[208:211], v[76:79]
	v_mfma_f32_16x16x32_bf16 v[72:75], v[160:163], v[208:211], v[72:75]
	v_mfma_f32_16x16x32_bf16 v[116:119], v[164:167], v[180:183], v[116:119]
	v_mfma_f32_16x16x32_bf16 v[112:115], v[172:175], v[180:183], v[112:115]
	v_mfma_f32_16x16x32_bf16 v[100:103], v[164:167], v[188:191], v[100:103]
	v_mfma_f32_16x16x32_bf16 v[96:99], v[172:175], v[188:191], v[96:99]
	v_mfma_f32_16x16x32_bf16 v[84:87], v[164:167], v[196:199], v[84:87]
	v_mfma_f32_16x16x32_bf16 v[80:83], v[172:175], v[196:199], v[80:83]
	v_mfma_f32_16x16x32_bf16 v[68:71], v[164:167], v[204:207], v[68:71]
	v_mfma_f32_16x16x32_bf16 v[64:67], v[172:175], v[204:207], v[64:67]
	v_mfma_f32_16x16x32_bf16 v[116:119], v[168:171], v[184:187], v[116:119]
	v_mfma_f32_16x16x32_bf16 v[112:115], v[176:179], v[184:187], v[112:115]
	v_mfma_f32_16x16x32_bf16 v[100:103], v[168:171], v[192:195], v[100:103]
	v_mfma_f32_16x16x32_bf16 v[96:99], v[176:179], v[192:195], v[96:99]
	v_mfma_f32_16x16x32_bf16 v[84:87], v[168:171], v[200:203], v[84:87]
	v_mfma_f32_16x16x32_bf16 v[80:83], v[176:179], v[200:203], v[80:83]
	v_mfma_f32_16x16x32_bf16 v[68:71], v[168:171], v[208:211], v[68:71]
	v_mfma_f32_16x16x32_bf16 v[64:67], v[176:179], v[208:211], v[64:67]
	s_setprio 0
	s_barrier
	s_setprio 2
	s_mov_b32 m0, s65
	v_lshl_add_u64 v[212:213], v[212:213], 0, s[12:13]
	s_add_u32 s18, s18, 0x80080
	ds_read_b128 v[180:183], v145 offset:49152
	ds_read_b128 v[184:187], v145 offset:50176
	ds_read_b128 v[188:191], v145 offset:51200
	ds_read_b128 v[192:195], v145 offset:52224
	ds_read_b128 v[196:199], v145 offset:53248
	ds_read_b128 v[200:203], v145 offset:54272
	ds_read_b128 v[204:207], v145 offset:55296
	ds_read_b128 v[208:211], v145 offset:56320
	global_load_lds_dwordx4 v[212:213], off
	v_lshl_add_u64 v[212:213], v[214:215], 0, s[12:13]
	s_mov_b32 m0, s66
	s_addc_u32 s19, s19, 0
	global_load_lds_dwordx4 v[212:213], off
	v_lshl_add_u64 v[212:213], s[18:19], 0, v[132:133]
	s_mov_b32 m0, s67
	s_nop 0
	global_load_lds_dwordx4 v[212:213], off
	v_lshl_add_u64 v[212:213], s[18:19], 0, v[128:129]
	s_mov_b32 m0, s68
	s_nop 0
	global_load_lds_dwordx4 v[212:213], off
	v_lshl_add_u64 v[212:213], v[216:217], 0, s[12:13]
	s_mov_b32 m0, s30
	s_nop 0
	global_load_lds_dwordx4 v[212:213], off
	v_lshl_add_u64 v[212:213], v[218:219], 0, s[12:13]
	s_mov_b32 m0, s34
	s_nop 0
	global_load_lds_dwordx4 v[212:213], off
	s_setprio 0
	s_waitcnt vmcnt(8)
	s_waitcnt lgkmcnt(0)
	s_barrier
	s_setprio 1
	s_waitcnt lgkmcnt(0)
	v_mfma_f32_16x16x32_bf16 v[60:63], v[148:151], v[180:183], v[60:63]
	v_mfma_f32_16x16x32_bf16 v[56:59], v[156:159], v[180:183], v[56:59]
	v_mfma_f32_16x16x32_bf16 v[44:47], v[148:151], v[188:191], v[44:47]
	v_mfma_f32_16x16x32_bf16 v[40:43], v[156:159], v[188:191], v[40:43]
	v_mfma_f32_16x16x32_bf16 v[28:31], v[148:151], v[196:199], v[28:31]
	v_mfma_f32_16x16x32_bf16 v[24:27], v[156:159], v[196:199], v[24:27]
	v_mfma_f32_16x16x32_bf16 v[12:15], v[148:151], v[204:207], v[12:15]
	v_mfma_f32_16x16x32_bf16 v[8:11], v[156:159], v[204:207], v[8:11]
	v_mfma_f32_16x16x32_bf16 v[60:63], v[152:155], v[184:187], v[60:63]
	v_mfma_f32_16x16x32_bf16 v[56:59], v[160:163], v[184:187], v[56:59]
	v_mfma_f32_16x16x32_bf16 v[44:47], v[152:155], v[192:195], v[44:47]
	v_mfma_f32_16x16x32_bf16 v[40:43], v[160:163], v[192:195], v[40:43]
	v_mfma_f32_16x16x32_bf16 v[28:31], v[152:155], v[200:203], v[28:31]
	v_mfma_f32_16x16x32_bf16 v[24:27], v[160:163], v[200:203], v[24:27]
	v_mfma_f32_16x16x32_bf16 v[12:15], v[152:155], v[208:211], v[12:15]
	v_mfma_f32_16x16x32_bf16 v[8:11], v[160:163], v[208:211], v[8:11]
	v_mfma_f32_16x16x32_bf16 v[52:55], v[164:167], v[180:183], v[52:55]
	v_mfma_f32_16x16x32_bf16 v[48:51], v[172:175], v[180:183], v[48:51]
	v_mfma_f32_16x16x32_bf16 v[36:39], v[164:167], v[188:191], v[36:39]
	v_mfma_f32_16x16x32_bf16 v[32:35], v[172:175], v[188:191], v[32:35]
	v_mfma_f32_16x16x32_bf16 v[20:23], v[164:167], v[196:199], v[20:23]
	v_mfma_f32_16x16x32_bf16 v[16:19], v[172:175], v[196:199], v[16:19]
	v_mfma_f32_16x16x32_bf16 v[4:7], v[164:167], v[204:207], v[4:7]
	v_mfma_f32_16x16x32_bf16 v[0:3], v[172:175], v[204:207], v[0:3]
	v_mfma_f32_16x16x32_bf16 v[52:55], v[168:171], v[184:187], v[52:55]
	v_mfma_f32_16x16x32_bf16 v[48:51], v[176:179], v[184:187], v[48:51]
	v_mfma_f32_16x16x32_bf16 v[36:39], v[168:171], v[192:195], v[36:39]
	v_mfma_f32_16x16x32_bf16 v[32:35], v[176:179], v[192:195], v[32:35]
	v_mfma_f32_16x16x32_bf16 v[20:23], v[168:171], v[200:203], v[20:23]
	v_mfma_f32_16x16x32_bf16 v[16:19], v[176:179], v[200:203], v[16:19]
	v_mfma_f32_16x16x32_bf16 v[4:7], v[168:171], v[208:211], v[4:7]
	v_mfma_f32_16x16x32_bf16 v[0:3], v[176:179], v[208:211], v[0:3]
	s_setprio 0
	s_barrier
	s_setprio 2
	s_add_i32 s35, s35, 2
	s_add_u32 s16, s16, 0x100
	s_addc_u32 s17, s17, 0
	s_cmp_gt_u32 s35, 29
	s_cbranch_scc0 .LBB0_946
	s_setprio 0
	s_cmpk_lt_u32 s80, 0x100
	s_cbranch_scc0 .LBB0_949
	s_barrier

.LBB0_1693:
	ds_read_b128 v[140:143], v149
	ds_read_b128 v[152:155], v149 offset:1024
	ds_read_b128 v[156:159], v149 offset:2048
	ds_read_b128 v[160:163], v149 offset:3072
	ds_read_b128 v[164:167], v150
	ds_read_b128 v[168:171], v150 offset:1024
	ds_read_b128 v[172:175], v150 offset:2048
	ds_read_b128 v[176:179], v150 offset:3072
	s_add_u32 s76, s74, 0xfff80080
	s_addc_u32 s77, s75, -1
	s_cmp_eq_u32 s86, 28
	s_cselect_b32 s79, s67, s77
	s_cselect_b32 s78, s73, s76
	s_cselect_b32 s77, s65, s85
	s_cselect_b32 s76, s83, s84
	v_lshl_add_u64 v[212:213], s[74:75], 0, v[132:133]
	s_add_i32 m0, s6, 0xc000
	ds_read_b128 v[180:183], v151
	ds_read_b128 v[184:187], v151 offset:1024
	ds_read_b128 v[188:191], v151 offset:2048
	ds_read_b128 v[192:195], v151 offset:3072
	ds_read_b128 v[196:199], v151 offset:4096
	ds_read_b128 v[200:203], v151 offset:5120
	ds_read_b128 v[204:207], v151 offset:6144
	ds_read_b128 v[208:211], v151 offset:7168
	global_load_lds_dwordx4 v[212:213], off
	v_lshl_add_u64 v[212:213], s[74:75], 0, v[134:135]
	s_add_i32 m0, s6, 0xe000
	s_nop 0
	global_load_lds_dwordx4 v[212:213], off
	s_waitcnt vmcnt(8)
	s_waitcnt lgkmcnt(0)
	s_barrier
	s_setprio 1
	s_waitcnt lgkmcnt(0)
	v_mfma_f32_16x16x32_bf16 v[124:127], v[140:143], v[180:183], v[124:127]
	v_mfma_f32_16x16x32_bf16 v[120:123], v[156:159], v[180:183], v[120:123]
	v_mfma_f32_16x16x32_bf16 v[108:111], v[140:143], v[188:191], v[108:111]
	v_mfma_f32_16x16x32_bf16 v[104:107], v[156:159], v[188:191], v[104:107]
	v_mfma_f32_16x16x32_bf16 v[92:95], v[140:143], v[196:199], v[92:95]
	v_mfma_f32_16x16x32_bf16 v[88:91], v[156:159], v[196:199], v[88:91]
	v_mfma_f32_16x16x32_bf16 v[76:79], v[140:143], v[204:207], v[76:79]
	v_mfma_f32_16x16x32_bf16 v[72:75], v[156:159], v[204:207], v[72:75]
	v_mfma_f32_16x16x32_bf16 v[124:127], v[152:155], v[184:187], v[124:127]
	v_mfma_f32_16x16x32_bf16 v[120:123], v[160:163], v[184:187], v[120:123]
	v_mfma_f32_16x16x32_bf16 v[108:111], v[152:155], v[192:195], v[108:111]
	v_mfma_f32_16x16x32_bf16 v[104:107], v[160:163], v[192:195], v[104:107]
	v_mfma_f32_16x16x32_bf16 v[92:95], v[152:155], v[200:203], v[92:95]
	v_mfma_f32_16x16x32_bf16 v[88:91], v[160:163], v[200:203], v[88:91]
	v_mfma_f32_16x16x32_bf16 v[76:79], v[152:155], v[208:211], v[76:79]
	v_mfma_f32_16x16x32_bf16 v[72:75], v[160:163], v[208:211], v[72:75]
	v_mfma_f32_16x16x32_bf16 v[116:119], v[164:167], v[180:183], v[116:119]
	v_mfma_f32_16x16x32_bf16 v[112:115], v[172:175], v[180:183], v[112:115]
	v_mfma_f32_16x16x32_bf16 v[100:103], v[164:167], v[188:191], v[100:103]
	v_mfma_f32_16x16x32_bf16 v[96:99], v[172:175], v[188:191], v[96:99]
	v_mfma_f32_16x16x32_bf16 v[84:87], v[164:167], v[196:199], v[84:87]
	v_mfma_f32_16x16x32_bf16 v[80:83], v[172:175], v[196:199], v[80:83]
	v_mfma_f32_16x16x32_bf16 v[68:71], v[164:167], v[204:207], v[68:71]
	v_mfma_f32_16x16x32_bf16 v[64:67], v[172:175], v[204:207], v[64:67]
	v_mfma_f32_16x16x32_bf16 v[116:119], v[168:171], v[184:187], v[116:119]
	v_mfma_f32_16x16x32_bf16 v[112:115], v[176:179], v[184:187], v[112:115]
	v_mfma_f32_16x16x32_bf16 v[100:103], v[168:171], v[192:195], v[100:103]
	v_mfma_f32_16x16x32_bf16 v[96:99], v[176:179], v[192:195], v[96:99]
	v_mfma_f32_16x16x32_bf16 v[84:87], v[168:171], v[200:203], v[84:87]
	v_mfma_f32_16x16x32_bf16 v[80:83], v[176:179], v[200:203], v[80:83]
	v_mfma_f32_16x16x32_bf16 v[68:71], v[168:171], v[208:211], v[68:71]
	v_mfma_f32_16x16x32_bf16 v[64:67], v[176:179], v[208:211], v[64:67]
	s_setprio 0
	s_barrier
	s_setprio 2
	s_add_i32 s87, s57, s94
	v_lshl_add_u64 v[212:213], s[76:77], 0, v[128:129]
	s_mov_b32 m0, s87
	ds_read_b128 v[180:183], v151 offset:16384
	ds_read_b128 v[184:187], v151 offset:17408
	ds_read_b128 v[188:191], v151 offset:18432
	ds_read_b128 v[192:195], v151 offset:19456
	ds_read_b128 v[196:199], v151 offset:20480
	ds_read_b128 v[200:203], v151 offset:21504
	ds_read_b128 v[204:207], v151 offset:22528
	ds_read_b128 v[208:211], v151 offset:23552
	global_load_lds_dwordx4 v[212:213], off
	s_add_i32 m0, s87, 0x2000
	s_add_u32 s88, s76, 0x80000
	v_lshl_add_u64 v[214:215], s[76:77], 0, v[130:131]
	s_addc_u32 s89, s77, 0
	s_add_i32 s87, s81, s94
	global_load_lds_dwordx4 v[214:215], off
	v_lshl_add_u64 v[216:217], s[88:89], 0, v[128:129]
	s_mov_b32 m0, s87
	v_lshl_add_u64 v[218:219], s[78:79], 0, v[130:131]
	global_load_lds_dwordx4 v[216:217], off
	v_lshl_add_u64 v[216:217], s[88:89], 0, v[130:131]
	s_add_i32 m0, s87, 0x2000
	s_nop 0
	global_load_lds_dwordx4 v[216:217], off
	v_lshl_add_u64 v[216:217], s[78:79], 0, v[128:129]
	s_mov_b32 m0, s6
	s_nop 0
	global_load_lds_dwordx4 v[216:217], off
	s_mov_b32 m0, s7
	s_nop 0
	global_load_lds_dwordx4 v[218:219], off
	s_setprio 0
	s_waitcnt vmcnt(8)
	s_waitcnt lgkmcnt(0)
	s_barrier
	s_setprio 1
	s_waitcnt lgkmcnt(0)
	v_mfma_f32_16x16x32_bf16 v[60:63], v[140:143], v[180:183], v[60:63]
	v_mfma_f32_16x16x32_bf16 v[56:59], v[156:159], v[180:183], v[56:59]
	v_mfma_f32_16x16x32_bf16 v[44:47], v[140:143], v[188:191], v[44:47]
	v_mfma_f32_16x16x32_bf16 v[40:43], v[156:159], v[188:191], v[40:43]
	v_mfma_f32_16x16x32_bf16 v[28:31], v[140:143], v[196:199], v[28:31]
	v_mfma_f32_16x16x32_bf16 v[24:27], v[156:159], v[196:199], v[24:27]
	v_mfma_f32_16x16x32_bf16 v[12:15], v[140:143], v[204:207], v[12:15]
	v_mfma_f32_16x16x32_bf16 v[8:11], v[156:159], v[204:207], v[8:11]
	v_mfma_f32_16x16x32_bf16 v[60:63], v[152:155], v[184:187], v[60:63]
	v_mfma_f32_16x16x32_bf16 v[56:59], v[160:163], v[184:187], v[56:59]
	v_mfma_f32_16x16x32_bf16 v[44:47], v[152:155], v[192:195], v[44:47]
	v_mfma_f32_16x16x32_bf16 v[40:43], v[160:163], v[192:195], v[40:43]
	v_mfma_f32_16x16x32_bf16 v[28:31], v[152:155], v[200:203], v[28:31]
	v_mfma_f32_16x16x32_bf16 v[24:27], v[160:163], v[200:203], v[24:27]
	v_mfma_f32_16x16x32_bf16 v[12:15], v[152:155], v[208:211], v[12:15]
	v_mfma_f32_16x16x32_bf16 v[8:11], v[160:163], v[208:211], v[8:11]
	v_mfma_f32_16x16x32_bf16 v[52:55], v[164:167], v[180:183], v[52:55]
	v_mfma_f32_16x16x32_bf16 v[48:51], v[172:175], v[180:183], v[48:51]
	v_mfma_f32_16x16x32_bf16 v[36:39], v[164:167], v[188:191], v[36:39]
	v_mfma_f32_16x16x32_bf16 v[32:35], v[172:175], v[188:191], v[32:35]
	v_mfma_f32_16x16x32_bf16 v[20:23], v[164:167], v[196:199], v[20:23]
	v_mfma_f32_16x16x32_bf16 v[16:19], v[172:175], v[196:199], v[16:19]
	v_mfma_f32_16x16x32_bf16 v[4:7], v[164:167], v[204:207], v[4:7]
	v_mfma_f32_16x16x32_bf16 v[0:3], v[172:175], v[204:207], v[0:3]
	v_mfma_f32_16x16x32_bf16 v[52:55], v[168:171], v[184:187], v[52:55]
	v_mfma_f32_16x16x32_bf16 v[48:51], v[176:179], v[184:187], v[48:51]
	v_mfma_f32_16x16x32_bf16 v[36:39], v[168:171], v[192:195], v[36:39]
	v_mfma_f32_16x16x32_bf16 v[32:35], v[176:179], v[192:195], v[32:35]
	v_mfma_f32_16x16x32_bf16 v[20:23], v[168:171], v[200:203], v[20:23]
	v_mfma_f32_16x16x32_bf16 v[16:19], v[176:179], v[200:203], v[16:19]
	v_mfma_f32_16x16x32_bf16 v[4:7], v[168:171], v[208:211], v[4:7]
	v_mfma_f32_16x16x32_bf16 v[0:3], v[176:179], v[208:211], v[0:3]
	s_setprio 0
	s_barrier
	s_setprio 2
	s_add_i32 s87, 0, 0x18000
	s_add_i32 s88, 0, 0x1c000
	v_add_u32_e32 v160, s87, v145
	v_add_u32_e32 v176, s88, v145
	ds_read_b128 v[140:143], v160
	ds_read_b128 v[152:155], v160 offset:1024
	ds_read_b128 v[156:159], v160 offset:2048
	ds_read_b128 v[160:163], v160 offset:3072
	ds_read_b128 v[164:167], v176
	ds_read_b128 v[168:171], v176 offset:1024
	ds_read_b128 v[172:175], v176 offset:2048
	ds_read_b128 v[176:179], v176 offset:3072
	s_add_u32 s78, s78, 0x80000
	s_addc_u32 s79, s79, 0
	s_mov_b32 m0, s29
	v_lshl_add_u64 v[220:221], s[78:79], 0, v[128:129]
	ds_read_b128 v[180:183], v151 offset:32768
	ds_read_b128 v[184:187], v151 offset:33792
	ds_read_b128 v[188:191], v151 offset:34816
	ds_read_b128 v[192:195], v151 offset:35840
	ds_read_b128 v[196:199], v151 offset:36864
	ds_read_b128 v[200:203], v151 offset:37888
	ds_read_b128 v[204:207], v151 offset:38912
	ds_read_b128 v[208:211], v151 offset:39936
	global_load_lds_dwordx4 v[220:221], off
	v_lshl_add_u64 v[220:221], s[78:79], 0, v[130:131]
	s_mov_b32 m0, s30
	s_nop 0
	global_load_lds_dwordx4 v[220:221], off
	s_setprio 0
	s_waitcnt vmcnt(8)
	s_waitcnt lgkmcnt(0)
	s_barrier
	s_setprio 1
	s_waitcnt lgkmcnt(0)
	v_mfma_f32_16x16x32_bf16 v[124:127], v[140:143], v[180:183], v[124:127]
	v_mfma_f32_16x16x32_bf16 v[120:123], v[156:159], v[180:183], v[120:123]
	v_mfma_f32_16x16x32_bf16 v[108:111], v[140:143], v[188:191], v[108:111]
	v_mfma_f32_16x16x32_bf16 v[104:107], v[156:159], v[188:191], v[104:107]
	v_mfma_f32_16x16x32_bf16 v[92:95], v[140:143], v[196:199], v[92:95]
	v_mfma_f32_16x16x32_bf16 v[88:91], v[156:159], v[196:199], v[88:91]
	v_mfma_f32_16x16x32_bf16 v[76:79], v[140:143], v[204:207], v[76:79]
	v_mfma_f32_16x16x32_bf16 v[72:75], v[156:159], v[204:207], v[72:75]
	v_mfma_f32_16x16x32_bf16 v[124:127], v[152:155], v[184:187], v[124:127]
	v_mfma_f32_16x16x32_bf16 v[120:123], v[160:163], v[184:187], v[120:123]
	v_mfma_f32_16x16x32_bf16 v[108:111], v[152:155], v[192:195], v[108:111]
	v_mfma_f32_16x16x32_bf16 v[104:107], v[160:163], v[192:195], v[104:107]
	v_mfma_f32_16x16x32_bf16 v[92:95], v[152:155], v[200:203], v[92:95]
	v_mfma_f32_16x16x32_bf16 v[88:91], v[160:163], v[200:203], v[88:91]
	v_mfma_f32_16x16x32_bf16 v[76:79], v[152:155], v[208:211], v[76:79]
	v_mfma_f32_16x16x32_bf16 v[72:75], v[160:163], v[208:211], v[72:75]
	v_mfma_f32_16x16x32_bf16 v[116:119], v[164:167], v[180:183], v[116:119]
	v_mfma_f32_16x16x32_bf16 v[112:115], v[172:175], v[180:183], v[112:115]
	v_mfma_f32_16x16x32_bf16 v[100:103], v[164:167], v[188:191], v[100:103]
	v_mfma_f32_16x16x32_bf16 v[96:99], v[172:175], v[188:191], v[96:99]
	v_mfma_f32_16x16x32_bf16 v[84:87], v[164:167], v[196:199], v[84:87]
	v_mfma_f32_16x16x32_bf16 v[80:83], v[172:175], v[196:199], v[80:83]
	v_mfma_f32_16x16x32_bf16 v[68:71], v[164:167], v[204:207], v[68:71]
	v_mfma_f32_16x16x32_bf16 v[64:67], v[172:175], v[204:207], v[64:67]
	v_mfma_f32_16x16x32_bf16 v[116:119], v[168:171], v[184:187], v[116:119]
	v_mfma_f32_16x16x32_bf16 v[112:115], v[176:179], v[184:187], v[112:115]
	v_mfma_f32_16x16x32_bf16 v[100:103], v[168:171], v[192:195], v[100:103]
	v_mfma_f32_16x16x32_bf16 v[96:99], v[176:179], v[192:195], v[96:99]
	v_mfma_f32_16x16x32_bf16 v[84:87], v[168:171], v[200:203], v[84:87]
	v_mfma_f32_16x16x32_bf16 v[80:83], v[176:179], v[200:203], v[80:83]
	v_mfma_f32_16x16x32_bf16 v[68:71], v[168:171], v[208:211], v[68:71]
	v_mfma_f32_16x16x32_bf16 v[64:67], v[176:179], v[208:211], v[64:67]
	s_setprio 0
	s_barrier
	s_setprio 2
	s_add_i32 s78, s87, s94
	v_lshl_add_u64 v[212:213], v[212:213], 0, s[58:59]
	s_mov_b32 m0, s78
	ds_read_b128 v[180:183], v151 offset:49152
	ds_read_b128 v[184:187], v151 offset:50176
	ds_read_b128 v[188:191], v151 offset:51200
	ds_read_b128 v[192:195], v151 offset:52224
	ds_read_b128 v[196:199], v151 offset:53248
	ds_read_b128 v[200:203], v151 offset:54272
	ds_read_b128 v[204:207], v151 offset:55296
	ds_read_b128 v[208:211], v151 offset:56320
	global_load_lds_dwordx4 v[212:213], off
	s_add_i32 m0, s78, 0x2000
	s_add_u32 s76, s76, 0x80080
	v_lshl_add_u64 v[212:213], v[214:215], 0, s[58:59]
	s_addc_u32 s77, s77, 0
	s_add_i32 s78, s88, s94
	global_load_lds_dwordx4 v[212:213], off
	v_lshl_add_u64 v[212:213], s[76:77], 0, v[128:129]
	s_mov_b32 m0, s78
	s_nop 0
	global_load_lds_dwordx4 v[212:213], off
	v_lshl_add_u64 v[212:213], s[76:77], 0, v[130:131]
	s_add_i32 m0, s78, 0x2000
	s_nop 0
	global_load_lds_dwordx4 v[212:213], off
	v_lshl_add_u64 v[212:213], v[216:217], 0, s[58:59]
	s_mov_b32 m0, s34
	s_nop 0
	global_load_lds_dwordx4 v[212:213], off
	v_lshl_add_u64 v[212:213], v[218:219], 0, s[58:59]
	s_mov_b32 m0, s35
	s_nop 0
	global_load_lds_dwordx4 v[212:213], off
	s_setprio 0
	s_waitcnt vmcnt(8)
	s_waitcnt lgkmcnt(0)
	s_barrier
	s_setprio 1
	s_waitcnt lgkmcnt(0)
	v_mfma_f32_16x16x32_bf16 v[60:63], v[140:143], v[180:183], v[60:63]
	v_mfma_f32_16x16x32_bf16 v[56:59], v[156:159], v[180:183], v[56:59]
	v_mfma_f32_16x16x32_bf16 v[44:47], v[140:143], v[188:191], v[44:47]
	v_mfma_f32_16x16x32_bf16 v[40:43], v[156:159], v[188:191], v[40:43]
	v_mfma_f32_16x16x32_bf16 v[28:31], v[140:143], v[196:199], v[28:31]
	v_mfma_f32_16x16x32_bf16 v[24:27], v[156:159], v[196:199], v[24:27]
	v_mfma_f32_16x16x32_bf16 v[12:15], v[140:143], v[204:207], v[12:15]
	v_mfma_f32_16x16x32_bf16 v[8:11], v[156:159], v[204:207], v[8:11]
	v_mfma_f32_16x16x32_bf16 v[60:63], v[152:155], v[184:187], v[60:63]
	v_mfma_f32_16x16x32_bf16 v[56:59], v[160:163], v[184:187], v[56:59]
	v_mfma_f32_16x16x32_bf16 v[44:47], v[152:155], v[192:195], v[44:47]
	v_mfma_f32_16x16x32_bf16 v[40:43], v[160:163], v[192:195], v[40:43]
	v_mfma_f32_16x16x32_bf16 v[28:31], v[152:155], v[200:203], v[28:31]
	v_mfma_f32_16x16x32_bf16 v[24:27], v[160:163], v[200:203], v[24:27]
	v_mfma_f32_16x16x32_bf16 v[12:15], v[152:155], v[208:211], v[12:15]
	v_mfma_f32_16x16x32_bf16 v[8:11], v[160:163], v[208:211], v[8:11]
	v_mfma_f32_16x16x32_bf16 v[52:55], v[164:167], v[180:183], v[52:55]
	v_mfma_f32_16x16x32_bf16 v[48:51], v[172:175], v[180:183], v[48:51]
	v_mfma_f32_16x16x32_bf16 v[36:39], v[164:167], v[188:191], v[36:39]
	v_mfma_f32_16x16x32_bf16 v[32:35], v[172:175], v[188:191], v[32:35]
	v_mfma_f32_16x16x32_bf16 v[20:23], v[164:167], v[196:199], v[20:23]
	v_mfma_f32_16x16x32_bf16 v[16:19], v[172:175], v[196:199], v[16:19]
	v_mfma_f32_16x16x32_bf16 v[4:7], v[164:167], v[204:207], v[4:7]
	v_mfma_f32_16x16x32_bf16 v[0:3], v[172:175], v[204:207], v[0:3]
	v_mfma_f32_16x16x32_bf16 v[52:55], v[168:171], v[184:187], v[52:55]
	v_mfma_f32_16x16x32_bf16 v[48:51], v[176:179], v[184:187], v[48:51]
	v_mfma_f32_16x16x32_bf16 v[36:39], v[168:171], v[192:195], v[36:39]
	v_mfma_f32_16x16x32_bf16 v[32:35], v[176:179], v[192:195], v[32:35]
	v_mfma_f32_16x16x32_bf16 v[20:23], v[168:171], v[200:203], v[20:23]
	v_mfma_f32_16x16x32_bf16 v[16:19], v[176:179], v[200:203], v[16:19]
	v_mfma_f32_16x16x32_bf16 v[4:7], v[168:171], v[208:211], v[4:7]
	v_mfma_f32_16x16x32_bf16 v[0:3], v[176:179], v[208:211], v[0:3]
	s_setprio 0
	s_barrier
	s_setprio 2
	s_add_i32 s86, s86, 2
	s_add_u32 s74, s74, 0x100
	s_addc_u32 s75, s75, 0
	s_add_u32 s84, s84, 0x100
	s_addc_u32 s85, s85, 0
	s_cmp_gt_u32 s86, 29
	s_cbranch_scc0 .LBB0_1693
	s_setprio 0
	s_and_b64 vcc, exec, s[60:61]
	s_cbranch_vccz .LBB0_1696
	s_barrier

.LBB0_1785:
	ds_read_b128 v[146:149], v155
	ds_read_b128 v[160:163], v155 offset:1024
	ds_read_b128 v[164:167], v155 offset:2048
	ds_read_b128 v[168:171], v155 offset:3072
	ds_read_b128 v[172:175], v156
	ds_read_b128 v[176:179], v156 offset:1024
	ds_read_b128 v[180:183], v156 offset:2048
	ds_read_b128 v[184:187], v156 offset:3072
	s_add_u32 s60, s72, 0xfff80080
	s_addc_u32 s61, s73, -1
	s_cmp_eq_u32 s78, 28
	s_cselect_b32 s77, s56, s61
	s_cselect_b32 s76, s57, s60
	s_cselect_b32 s75, s23, s71
	s_cselect_b32 s74, s63, s69
	v_lshl_add_u64 v[220:221], s[72:73], 0, v[138:139]
	s_add_i32 m0, s6, 0xc000
	ds_read_b128 v[188:191], v157
	ds_read_b128 v[192:195], v157 offset:1024
	ds_read_b128 v[196:199], v157 offset:2048
	ds_read_b128 v[200:203], v157 offset:3072
	ds_read_b128 v[204:207], v157 offset:4096
	ds_read_b128 v[208:211], v157 offset:5120
	ds_read_b128 v[212:215], v157 offset:6144
	ds_read_b128 v[216:219], v157 offset:7168
	global_load_lds_dwordx4 v[220:221], off
	v_lshl_add_u64 v[220:221], s[72:73], 0, v[140:141]
	s_add_i32 m0, s6, 0xe000
	s_nop 0
	global_load_lds_dwordx4 v[220:221], off
	s_waitcnt vmcnt(8)
	s_waitcnt lgkmcnt(0)
	s_barrier
	s_setprio 1
	s_waitcnt lgkmcnt(0)
	v_mfma_f32_16x16x32_bf16 v[124:127], v[146:149], v[188:191], v[124:127]
	v_mfma_f32_16x16x32_bf16 v[120:123], v[164:167], v[188:191], v[120:123]
	v_mfma_f32_16x16x32_bf16 v[108:111], v[146:149], v[196:199], v[108:111]
	v_mfma_f32_16x16x32_bf16 v[104:107], v[164:167], v[196:199], v[104:107]
	v_mfma_f32_16x16x32_bf16 v[92:95], v[146:149], v[204:207], v[92:95]
	v_mfma_f32_16x16x32_bf16 v[88:91], v[164:167], v[204:207], v[88:91]
	v_mfma_f32_16x16x32_bf16 v[76:79], v[146:149], v[212:215], v[76:79]
	v_mfma_f32_16x16x32_bf16 v[72:75], v[164:167], v[212:215], v[72:75]
	v_mfma_f32_16x16x32_bf16 v[124:127], v[160:163], v[192:195], v[124:127]
	v_mfma_f32_16x16x32_bf16 v[120:123], v[168:171], v[192:195], v[120:123]
	v_mfma_f32_16x16x32_bf16 v[108:111], v[160:163], v[200:203], v[108:111]
	v_mfma_f32_16x16x32_bf16 v[104:107], v[168:171], v[200:203], v[104:107]
	v_mfma_f32_16x16x32_bf16 v[92:95], v[160:163], v[208:211], v[92:95]
	v_mfma_f32_16x16x32_bf16 v[88:91], v[168:171], v[208:211], v[88:91]
	v_mfma_f32_16x16x32_bf16 v[76:79], v[160:163], v[216:219], v[76:79]
	v_mfma_f32_16x16x32_bf16 v[72:75], v[168:171], v[216:219], v[72:75]
	v_mfma_f32_16x16x32_bf16 v[116:119], v[172:175], v[188:191], v[116:119]
	v_mfma_f32_16x16x32_bf16 v[112:115], v[180:183], v[188:191], v[112:115]
	v_mfma_f32_16x16x32_bf16 v[100:103], v[172:175], v[196:199], v[100:103]
	v_mfma_f32_16x16x32_bf16 v[96:99], v[180:183], v[196:199], v[96:99]
	v_mfma_f32_16x16x32_bf16 v[84:87], v[172:175], v[204:207], v[84:87]
	v_mfma_f32_16x16x32_bf16 v[80:83], v[180:183], v[204:207], v[80:83]
	v_mfma_f32_16x16x32_bf16 v[68:71], v[172:175], v[212:215], v[68:71]
	v_mfma_f32_16x16x32_bf16 v[64:67], v[180:183], v[212:215], v[64:67]
	v_mfma_f32_16x16x32_bf16 v[116:119], v[176:179], v[192:195], v[116:119]
	v_mfma_f32_16x16x32_bf16 v[112:115], v[184:187], v[192:195], v[112:115]
	v_mfma_f32_16x16x32_bf16 v[100:103], v[176:179], v[200:203], v[100:103]
	v_mfma_f32_16x16x32_bf16 v[96:99], v[184:187], v[200:203], v[96:99]
	v_mfma_f32_16x16x32_bf16 v[84:87], v[176:179], v[208:211], v[84:87]
	v_mfma_f32_16x16x32_bf16 v[80:83], v[184:187], v[208:211], v[80:83]
	v_mfma_f32_16x16x32_bf16 v[68:71], v[176:179], v[216:219], v[68:71]
	v_mfma_f32_16x16x32_bf16 v[64:67], v[184:187], v[216:219], v[64:67]
	s_setprio 0
	s_barrier
	s_setprio 2
	s_add_i32 s60, s35, s94
	v_lshl_add_u64 v[220:221], s[74:75], 0, v[130:131]
	s_mov_b32 m0, s60
	ds_read_b128 v[188:191], v157 offset:16384
	ds_read_b128 v[192:195], v157 offset:17408
	ds_read_b128 v[196:199], v157 offset:18432
	ds_read_b128 v[200:203], v157 offset:19456
	ds_read_b128 v[204:207], v157 offset:20480
	ds_read_b128 v[208:211], v157 offset:21504
	ds_read_b128 v[212:215], v157 offset:22528
	ds_read_b128 v[216:219], v157 offset:23552
	global_load_lds_dwordx4 v[220:221], off
	s_add_i32 m0, s60, 0x2000
	s_add_u32 s80, s74, 0x80000
	v_lshl_add_u64 v[222:223], s[74:75], 0, v[134:135]
	s_addc_u32 s81, s75, 0
	s_add_i32 s60, s46, s94
	global_load_lds_dwordx4 v[222:223], off
	v_lshl_add_u64 v[224:225], s[80:81], 0, v[130:131]
	s_mov_b32 m0, s60
	v_lshl_add_u64 v[226:227], s[76:77], 0, v[132:133]
	global_load_lds_dwordx4 v[224:225], off
	v_lshl_add_u64 v[224:225], s[80:81], 0, v[134:135]
	s_add_i32 m0, s60, 0x2000
	s_nop 0
	global_load_lds_dwordx4 v[224:225], off
	v_lshl_add_u64 v[224:225], s[76:77], 0, v[128:129]
	s_mov_b32 m0, s6
	s_nop 0
	global_load_lds_dwordx4 v[224:225], off
	s_mov_b32 m0, s7
	s_nop 0
	global_load_lds_dwordx4 v[226:227], off
	s_setprio 0
	s_waitcnt vmcnt(8)
	s_waitcnt lgkmcnt(0)
	s_barrier
	s_setprio 1
	s_waitcnt lgkmcnt(0)
	v_mfma_f32_16x16x32_bf16 v[60:63], v[146:149], v[188:191], v[60:63]
	v_mfma_f32_16x16x32_bf16 v[56:59], v[164:167], v[188:191], v[56:59]
	v_mfma_f32_16x16x32_bf16 v[44:47], v[146:149], v[196:199], v[44:47]
	v_mfma_f32_16x16x32_bf16 v[40:43], v[164:167], v[196:199], v[40:43]
	v_mfma_f32_16x16x32_bf16 v[28:31], v[146:149], v[204:207], v[28:31]
	v_mfma_f32_16x16x32_bf16 v[24:27], v[164:167], v[204:207], v[24:27]
	v_mfma_f32_16x16x32_bf16 v[12:15], v[146:149], v[212:215], v[12:15]
	v_mfma_f32_16x16x32_bf16 v[8:11], v[164:167], v[212:215], v[8:11]
	v_mfma_f32_16x16x32_bf16 v[60:63], v[160:163], v[192:195], v[60:63]
	v_mfma_f32_16x16x32_bf16 v[56:59], v[168:171], v[192:195], v[56:59]
	v_mfma_f32_16x16x32_bf16 v[44:47], v[160:163], v[200:203], v[44:47]
	v_mfma_f32_16x16x32_bf16 v[40:43], v[168:171], v[200:203], v[40:43]
	v_mfma_f32_16x16x32_bf16 v[28:31], v[160:163], v[208:211], v[28:31]
	v_mfma_f32_16x16x32_bf16 v[24:27], v[168:171], v[208:211], v[24:27]
	v_mfma_f32_16x16x32_bf16 v[12:15], v[160:163], v[216:219], v[12:15]
	v_mfma_f32_16x16x32_bf16 v[8:11], v[168:171], v[216:219], v[8:11]
	v_mfma_f32_16x16x32_bf16 v[52:55], v[172:175], v[188:191], v[52:55]
	v_mfma_f32_16x16x32_bf16 v[48:51], v[180:183], v[188:191], v[48:51]
	v_mfma_f32_16x16x32_bf16 v[36:39], v[172:175], v[196:199], v[36:39]
	v_mfma_f32_16x16x32_bf16 v[32:35], v[180:183], v[196:199], v[32:35]
	v_mfma_f32_16x16x32_bf16 v[20:23], v[172:175], v[204:207], v[20:23]
	v_mfma_f32_16x16x32_bf16 v[16:19], v[180:183], v[204:207], v[16:19]
	v_mfma_f32_16x16x32_bf16 v[4:7], v[172:175], v[212:215], v[4:7]
	v_mfma_f32_16x16x32_bf16 v[0:3], v[180:183], v[212:215], v[0:3]
	v_mfma_f32_16x16x32_bf16 v[52:55], v[176:179], v[192:195], v[52:55]
	v_mfma_f32_16x16x32_bf16 v[48:51], v[184:187], v[192:195], v[48:51]
	v_mfma_f32_16x16x32_bf16 v[36:39], v[176:179], v[200:203], v[36:39]
	v_mfma_f32_16x16x32_bf16 v[32:35], v[184:187], v[200:203], v[32:35]
	v_mfma_f32_16x16x32_bf16 v[20:23], v[176:179], v[208:211], v[20:23]
	v_mfma_f32_16x16x32_bf16 v[16:19], v[184:187], v[208:211], v[16:19]
	v_mfma_f32_16x16x32_bf16 v[4:7], v[176:179], v[216:219], v[4:7]
	v_mfma_f32_16x16x32_bf16 v[0:3], v[184:187], v[216:219], v[0:3]
	s_setprio 0
	s_barrier
	s_setprio 2
	s_add_i32 s60, 0, 0x18000
	v_add_u32_e32 v159, s60, v151
	s_add_i32 s61, 0, 0x1c000
	ds_read_b128 v[146:149], v159
	ds_read_b128 v[160:163], v159 offset:1024
	ds_read_b128 v[164:167], v159 offset:2048
	ds_read_b128 v[168:171], v159 offset:3072
	v_add_u32_e32 v159, s61, v151
	ds_read_b128 v[172:175], v159
	ds_read_b128 v[176:179], v159 offset:1024
	ds_read_b128 v[180:183], v159 offset:2048
	ds_read_b128 v[184:187], v159 offset:3072
	s_add_u32 s76, s76, 0x80000
	s_addc_u32 s77, s77, 0
	s_mov_b32 m0, s12
	v_lshl_add_u64 v[228:229], s[76:77], 0, v[128:129]
	ds_read_b128 v[188:191], v157 offset:32768
	ds_read_b128 v[192:195], v157 offset:33792
	ds_read_b128 v[196:199], v157 offset:34816
	ds_read_b128 v[200:203], v157 offset:35840
	ds_read_b128 v[204:207], v157 offset:36864
	ds_read_b128 v[208:211], v157 offset:37888
	ds_read_b128 v[212:215], v157 offset:38912
	ds_read_b128 v[216:219], v157 offset:39936
	global_load_lds_dwordx4 v[228:229], off
	v_lshl_add_u64 v[228:229], s[76:77], 0, v[132:133]
	s_mov_b32 m0, s13
	s_nop 0
	global_load_lds_dwordx4 v[228:229], off
	s_setprio 0
	s_waitcnt vmcnt(8)
	s_waitcnt lgkmcnt(0)
	s_barrier
	s_setprio 1
	s_waitcnt lgkmcnt(0)
	v_mfma_f32_16x16x32_bf16 v[124:127], v[146:149], v[188:191], v[124:127]
	v_mfma_f32_16x16x32_bf16 v[120:123], v[164:167], v[188:191], v[120:123]
	v_mfma_f32_16x16x32_bf16 v[108:111], v[146:149], v[196:199], v[108:111]
	v_mfma_f32_16x16x32_bf16 v[104:107], v[164:167], v[196:199], v[104:107]
	v_mfma_f32_16x16x32_bf16 v[92:95], v[146:149], v[204:207], v[92:95]
	v_mfma_f32_16x16x32_bf16 v[88:91], v[164:167], v[204:207], v[88:91]
	v_mfma_f32_16x16x32_bf16 v[76:79], v[146:149], v[212:215], v[76:79]
	v_mfma_f32_16x16x32_bf16 v[72:75], v[164:167], v[212:215], v[72:75]
	v_mfma_f32_16x16x32_bf16 v[124:127], v[160:163], v[192:195], v[124:127]
	v_mfma_f32_16x16x32_bf16 v[120:123], v[168:171], v[192:195], v[120:123]
	v_mfma_f32_16x16x32_bf16 v[108:111], v[160:163], v[200:203], v[108:111]
	v_mfma_f32_16x16x32_bf16 v[104:107], v[168:171], v[200:203], v[104:107]
	v_mfma_f32_16x16x32_bf16 v[92:95], v[160:163], v[208:211], v[92:95]
	v_mfma_f32_16x16x32_bf16 v[88:91], v[168:171], v[208:211], v[88:91]
	v_mfma_f32_16x16x32_bf16 v[76:79], v[160:163], v[216:219], v[76:79]
	v_mfma_f32_16x16x32_bf16 v[72:75], v[168:171], v[216:219], v[72:75]
	v_mfma_f32_16x16x32_bf16 v[116:119], v[172:175], v[188:191], v[116:119]
	v_mfma_f32_16x16x32_bf16 v[112:115], v[180:183], v[188:191], v[112:115]
	v_mfma_f32_16x16x32_bf16 v[100:103], v[172:175], v[196:199], v[100:103]
	v_mfma_f32_16x16x32_bf16 v[96:99], v[180:183], v[196:199], v[96:99]
	v_mfma_f32_16x16x32_bf16 v[84:87], v[172:175], v[204:207], v[84:87]
	v_mfma_f32_16x16x32_bf16 v[80:83], v[180:183], v[204:207], v[80:83]
	v_mfma_f32_16x16x32_bf16 v[68:71], v[172:175], v[212:215], v[68:71]
	v_mfma_f32_16x16x32_bf16 v[64:67], v[180:183], v[212:215], v[64:67]
	v_mfma_f32_16x16x32_bf16 v[116:119], v[176:179], v[192:195], v[116:119]
	v_mfma_f32_16x16x32_bf16 v[112:115], v[184:187], v[192:195], v[112:115]
	v_mfma_f32_16x16x32_bf16 v[100:103], v[176:179], v[200:203], v[100:103]
	v_mfma_f32_16x16x32_bf16 v[96:99], v[184:187], v[200:203], v[96:99]
	v_mfma_f32_16x16x32_bf16 v[84:87], v[176:179], v[208:211], v[84:87]
	v_mfma_f32_16x16x32_bf16 v[80:83], v[184:187], v[208:211], v[80:83]
	v_mfma_f32_16x16x32_bf16 v[68:71], v[176:179], v[216:219], v[68:71]
	v_mfma_f32_16x16x32_bf16 v[64:67], v[184:187], v[216:219], v[64:67]
	s_setprio 0
	s_barrier
	s_setprio 2
	s_add_i32 s60, s60, s94
	v_lshl_add_u64 v[220:221], v[220:221], 0, s[20:21]
	s_mov_b32 m0, s60
	ds_read_b128 v[188:191], v157 offset:49152
	ds_read_b128 v[192:195], v157 offset:50176
	ds_read_b128 v[196:199], v157 offset:51200
	ds_read_b128 v[200:203], v157 offset:52224
	ds_read_b128 v[204:207], v157 offset:53248
	ds_read_b128 v[208:211], v157 offset:54272
	ds_read_b128 v[212:215], v157 offset:55296
	ds_read_b128 v[216:219], v157 offset:56320
	global_load_lds_dwordx4 v[220:221], off
	s_add_i32 m0, s60, 0x2000
	s_add_u32 s74, s74, 0x80080
	v_lshl_add_u64 v[220:221], v[222:223], 0, s[20:21]
	s_addc_u32 s75, s75, 0
	s_add_i32 s60, s61, s94
	global_load_lds_dwordx4 v[220:221], off
	v_lshl_add_u64 v[220:221], s[74:75], 0, v[130:131]
	s_mov_b32 m0, s60
	s_nop 0
	global_load_lds_dwordx4 v[220:221], off
	v_lshl_add_u64 v[220:221], s[74:75], 0, v[134:135]
	s_add_i32 m0, s60, 0x2000
	s_nop 0
	global_load_lds_dwordx4 v[220:221], off
	v_lshl_add_u64 v[220:221], v[224:225], 0, s[20:21]
	s_mov_b32 m0, s30
	s_nop 0
	global_load_lds_dwordx4 v[220:221], off
	v_lshl_add_u64 v[220:221], v[226:227], 0, s[20:21]
	s_mov_b32 m0, s34
	s_nop 0
	global_load_lds_dwordx4 v[220:221], off
	s_setprio 0
	s_waitcnt vmcnt(8)
	s_waitcnt lgkmcnt(0)
	s_barrier
	s_setprio 1
	s_waitcnt lgkmcnt(0)
	v_mfma_f32_16x16x32_bf16 v[60:63], v[146:149], v[188:191], v[60:63]
	v_mfma_f32_16x16x32_bf16 v[56:59], v[164:167], v[188:191], v[56:59]
	v_mfma_f32_16x16x32_bf16 v[44:47], v[146:149], v[196:199], v[44:47]
	v_mfma_f32_16x16x32_bf16 v[40:43], v[164:167], v[196:199], v[40:43]
	v_mfma_f32_16x16x32_bf16 v[28:31], v[146:149], v[204:207], v[28:31]
	v_mfma_f32_16x16x32_bf16 v[24:27], v[164:167], v[204:207], v[24:27]
	v_mfma_f32_16x16x32_bf16 v[12:15], v[146:149], v[212:215], v[12:15]
	v_mfma_f32_16x16x32_bf16 v[8:11], v[164:167], v[212:215], v[8:11]
	v_mfma_f32_16x16x32_bf16 v[60:63], v[160:163], v[192:195], v[60:63]
	v_mfma_f32_16x16x32_bf16 v[56:59], v[168:171], v[192:195], v[56:59]
	v_mfma_f32_16x16x32_bf16 v[44:47], v[160:163], v[200:203], v[44:47]
	v_mfma_f32_16x16x32_bf16 v[40:43], v[168:171], v[200:203], v[40:43]
	v_mfma_f32_16x16x32_bf16 v[28:31], v[160:163], v[208:211], v[28:31]
	v_mfma_f32_16x16x32_bf16 v[24:27], v[168:171], v[208:211], v[24:27]
	v_mfma_f32_16x16x32_bf16 v[12:15], v[160:163], v[216:219], v[12:15]
	v_mfma_f32_16x16x32_bf16 v[8:11], v[168:171], v[216:219], v[8:11]
	v_mfma_f32_16x16x32_bf16 v[52:55], v[172:175], v[188:191], v[52:55]
	v_mfma_f32_16x16x32_bf16 v[48:51], v[180:183], v[188:191], v[48:51]
	v_mfma_f32_16x16x32_bf16 v[36:39], v[172:175], v[196:199], v[36:39]
	v_mfma_f32_16x16x32_bf16 v[32:35], v[180:183], v[196:199], v[32:35]
	v_mfma_f32_16x16x32_bf16 v[20:23], v[172:175], v[204:207], v[20:23]
	v_mfma_f32_16x16x32_bf16 v[16:19], v[180:183], v[204:207], v[16:19]
	v_mfma_f32_16x16x32_bf16 v[4:7], v[172:175], v[212:215], v[4:7]
	v_mfma_f32_16x16x32_bf16 v[0:3], v[180:183], v[212:215], v[0:3]
	v_mfma_f32_16x16x32_bf16 v[52:55], v[176:179], v[192:195], v[52:55]
	v_mfma_f32_16x16x32_bf16 v[48:51], v[184:187], v[192:195], v[48:51]
	v_mfma_f32_16x16x32_bf16 v[36:39], v[176:179], v[200:203], v[36:39]
	v_mfma_f32_16x16x32_bf16 v[32:35], v[184:187], v[200:203], v[32:35]
	v_mfma_f32_16x16x32_bf16 v[20:23], v[176:179], v[208:211], v[20:23]
	v_mfma_f32_16x16x32_bf16 v[16:19], v[184:187], v[208:211], v[16:19]
	v_mfma_f32_16x16x32_bf16 v[4:7], v[176:179], v[216:219], v[4:7]
	v_mfma_f32_16x16x32_bf16 v[0:3], v[184:187], v[216:219], v[0:3]
	s_setprio 0
	s_barrier
	s_setprio 2
	s_add_i32 s78, s78, 2
	s_add_u32 s72, s72, 0x100
	s_addc_u32 s73, s73, 0
	s_add_u32 s69, s69, 0x100
	s_addc_u32 s71, s71, 0
	s_cmp_gt_u32 s78, 29
	s_cbranch_scc0 .LBB0_1785
	s_setprio 0
	s_and_b64 vcc, exec, s[58:59]
	s_cbranch_vccz .LBB0_1788
	s_barrier

.LBB0_1897:
	ds_read_b128 v[140:143], v149
	ds_read_b128 v[152:155], v149 offset:1024
	ds_read_b128 v[156:159], v149 offset:2048
	ds_read_b128 v[160:163], v149 offset:3072
	ds_read_b128 v[164:167], v150
	ds_read_b128 v[168:171], v150 offset:1024
	ds_read_b128 v[172:175], v150 offset:2048
	ds_read_b128 v[176:179], v150 offset:3072
	s_add_u32 s60, s72, 0xffe00080
	s_addc_u32 s61, s73, -1
	s_cmpk_eq_i32 s79, 0x7c
	s_cselect_b32 s77, s56, s61
	s_cselect_b32 s76, s57, s60
	s_cselect_b32 s75, s63, s78
	s_cselect_b32 s74, s65, s71
	v_lshl_add_u64 v[212:213], s[72:73], 0, v[132:133]
	s_add_i32 m0, s6, 0xc000
	ds_read_b128 v[180:183], v151
	ds_read_b128 v[184:187], v151 offset:1024
	ds_read_b128 v[188:191], v151 offset:2048
	ds_read_b128 v[192:195], v151 offset:3072
	ds_read_b128 v[196:199], v151 offset:4096
	ds_read_b128 v[200:203], v151 offset:5120
	ds_read_b128 v[204:207], v151 offset:6144
	ds_read_b128 v[208:211], v151 offset:7168
	global_load_lds_dwordx4 v[212:213], off
	v_lshl_add_u64 v[212:213], s[72:73], 0, v[134:135]
	s_add_i32 m0, s6, 0xe000
	s_nop 0
	global_load_lds_dwordx4 v[212:213], off
	s_waitcnt vmcnt(8)
	s_waitcnt lgkmcnt(0)
	s_barrier
	s_setprio 1
	s_waitcnt lgkmcnt(0)
	v_mfma_f32_16x16x32_bf16 v[124:127], v[140:143], v[180:183], v[124:127]
	v_mfma_f32_16x16x32_bf16 v[120:123], v[156:159], v[180:183], v[120:123]
	v_mfma_f32_16x16x32_bf16 v[108:111], v[140:143], v[188:191], v[108:111]
	v_mfma_f32_16x16x32_bf16 v[104:107], v[156:159], v[188:191], v[104:107]
	v_mfma_f32_16x16x32_bf16 v[92:95], v[140:143], v[196:199], v[92:95]
	v_mfma_f32_16x16x32_bf16 v[88:91], v[156:159], v[196:199], v[88:91]
	v_mfma_f32_16x16x32_bf16 v[76:79], v[140:143], v[204:207], v[76:79]
	v_mfma_f32_16x16x32_bf16 v[72:75], v[156:159], v[204:207], v[72:75]
	v_mfma_f32_16x16x32_bf16 v[124:127], v[152:155], v[184:187], v[124:127]
	v_mfma_f32_16x16x32_bf16 v[120:123], v[160:163], v[184:187], v[120:123]
	v_mfma_f32_16x16x32_bf16 v[108:111], v[152:155], v[192:195], v[108:111]
	v_mfma_f32_16x16x32_bf16 v[104:107], v[160:163], v[192:195], v[104:107]
	v_mfma_f32_16x16x32_bf16 v[92:95], v[152:155], v[200:203], v[92:95]
	v_mfma_f32_16x16x32_bf16 v[88:91], v[160:163], v[200:203], v[88:91]
	v_mfma_f32_16x16x32_bf16 v[76:79], v[152:155], v[208:211], v[76:79]
	v_mfma_f32_16x16x32_bf16 v[72:75], v[160:163], v[208:211], v[72:75]
	v_mfma_f32_16x16x32_bf16 v[116:119], v[164:167], v[180:183], v[116:119]
	v_mfma_f32_16x16x32_bf16 v[112:115], v[172:175], v[180:183], v[112:115]
	v_mfma_f32_16x16x32_bf16 v[100:103], v[164:167], v[188:191], v[100:103]
	v_mfma_f32_16x16x32_bf16 v[96:99], v[172:175], v[188:191], v[96:99]
	v_mfma_f32_16x16x32_bf16 v[84:87], v[164:167], v[196:199], v[84:87]
	v_mfma_f32_16x16x32_bf16 v[80:83], v[172:175], v[196:199], v[80:83]
	v_mfma_f32_16x16x32_bf16 v[68:71], v[164:167], v[204:207], v[68:71]
	v_mfma_f32_16x16x32_bf16 v[64:67], v[172:175], v[204:207], v[64:67]
	v_mfma_f32_16x16x32_bf16 v[116:119], v[168:171], v[184:187], v[116:119]
	v_mfma_f32_16x16x32_bf16 v[112:115], v[176:179], v[184:187], v[112:115]
	v_mfma_f32_16x16x32_bf16 v[100:103], v[168:171], v[192:195], v[100:103]
	v_mfma_f32_16x16x32_bf16 v[96:99], v[176:179], v[192:195], v[96:99]
	v_mfma_f32_16x16x32_bf16 v[84:87], v[168:171], v[200:203], v[84:87]
	v_mfma_f32_16x16x32_bf16 v[80:83], v[176:179], v[200:203], v[80:83]
	v_mfma_f32_16x16x32_bf16 v[68:71], v[168:171], v[208:211], v[68:71]
	v_mfma_f32_16x16x32_bf16 v[64:67], v[176:179], v[208:211], v[64:67]
	s_setprio 0
	s_barrier
	s_setprio 2
	s_add_i32 s60, s34, s94
	v_lshl_add_u64 v[212:213], s[74:75], 0, v[128:129]
	s_mov_b32 m0, s60
	ds_read_b128 v[180:183], v151 offset:16384
	ds_read_b128 v[184:187], v151 offset:17408
	ds_read_b128 v[188:191], v151 offset:18432
	ds_read_b128 v[192:195], v151 offset:19456
	ds_read_b128 v[196:199], v151 offset:20480
	ds_read_b128 v[200:203], v151 offset:21504
	ds_read_b128 v[204:207], v151 offset:22528
	ds_read_b128 v[208:211], v151 offset:23552
	global_load_lds_dwordx4 v[212:213], off
	s_add_i32 m0, s60, 0x2000
	s_add_u32 s80, s74, 0x200000
	v_lshl_add_u64 v[214:215], s[74:75], 0, v[130:131]
	s_addc_u32 s81, s75, 0
	s_add_i32 s60, s35, s94
	global_load_lds_dwordx4 v[214:215], off
	v_lshl_add_u64 v[216:217], s[80:81], 0, v[128:129]
	s_mov_b32 m0, s60
	v_lshl_add_u64 v[218:219], s[76:77], 0, v[130:131]
	global_load_lds_dwordx4 v[216:217], off
	v_lshl_add_u64 v[216:217], s[80:81], 0, v[130:131]
	s_add_i32 m0, s60, 0x2000
	s_nop 0
	global_load_lds_dwordx4 v[216:217], off
	v_lshl_add_u64 v[216:217], s[76:77], 0, v[128:129]
	s_mov_b32 m0, s6
	s_nop 0
	global_load_lds_dwordx4 v[216:217], off
	s_mov_b32 m0, s7
	s_nop 0
	global_load_lds_dwordx4 v[218:219], off
	s_setprio 0
	s_waitcnt vmcnt(8)
	s_waitcnt lgkmcnt(0)
	s_barrier
	s_setprio 1
	s_waitcnt lgkmcnt(0)
	v_mfma_f32_16x16x32_bf16 v[60:63], v[140:143], v[180:183], v[60:63]
	v_mfma_f32_16x16x32_bf16 v[56:59], v[156:159], v[180:183], v[56:59]
	v_mfma_f32_16x16x32_bf16 v[44:47], v[140:143], v[188:191], v[44:47]
	v_mfma_f32_16x16x32_bf16 v[40:43], v[156:159], v[188:191], v[40:43]
	v_mfma_f32_16x16x32_bf16 v[28:31], v[140:143], v[196:199], v[28:31]
	v_mfma_f32_16x16x32_bf16 v[24:27], v[156:159], v[196:199], v[24:27]
	v_mfma_f32_16x16x32_bf16 v[12:15], v[140:143], v[204:207], v[12:15]
	v_mfma_f32_16x16x32_bf16 v[8:11], v[156:159], v[204:207], v[8:11]
	v_mfma_f32_16x16x32_bf16 v[60:63], v[152:155], v[184:187], v[60:63]
	v_mfma_f32_16x16x32_bf16 v[56:59], v[160:163], v[184:187], v[56:59]
	v_mfma_f32_16x16x32_bf16 v[44:47], v[152:155], v[192:195], v[44:47]
	v_mfma_f32_16x16x32_bf16 v[40:43], v[160:163], v[192:195], v[40:43]
	v_mfma_f32_16x16x32_bf16 v[28:31], v[152:155], v[200:203], v[28:31]
	v_mfma_f32_16x16x32_bf16 v[24:27], v[160:163], v[200:203], v[24:27]
	v_mfma_f32_16x16x32_bf16 v[12:15], v[152:155], v[208:211], v[12:15]
	v_mfma_f32_16x16x32_bf16 v[8:11], v[160:163], v[208:211], v[8:11]
	v_mfma_f32_16x16x32_bf16 v[52:55], v[164:167], v[180:183], v[52:55]
	v_mfma_f32_16x16x32_bf16 v[48:51], v[172:175], v[180:183], v[48:51]
	v_mfma_f32_16x16x32_bf16 v[36:39], v[164:167], v[188:191], v[36:39]
	v_mfma_f32_16x16x32_bf16 v[32:35], v[172:175], v[188:191], v[32:35]
	v_mfma_f32_16x16x32_bf16 v[20:23], v[164:167], v[196:199], v[20:23]
	v_mfma_f32_16x16x32_bf16 v[16:19], v[172:175], v[196:199], v[16:19]
	v_mfma_f32_16x16x32_bf16 v[4:7], v[164:167], v[204:207], v[4:7]
	v_mfma_f32_16x16x32_bf16 v[0:3], v[172:175], v[204:207], v[0:3]
	v_mfma_f32_16x16x32_bf16 v[52:55], v[168:171], v[184:187], v[52:55]
	v_mfma_f32_16x16x32_bf16 v[48:51], v[176:179], v[184:187], v[48:51]
	v_mfma_f32_16x16x32_bf16 v[36:39], v[168:171], v[192:195], v[36:39]
	v_mfma_f32_16x16x32_bf16 v[32:35], v[176:179], v[192:195], v[32:35]
	v_mfma_f32_16x16x32_bf16 v[20:23], v[168:171], v[200:203], v[20:23]
	v_mfma_f32_16x16x32_bf16 v[16:19], v[176:179], v[200:203], v[16:19]
	v_mfma_f32_16x16x32_bf16 v[4:7], v[168:171], v[208:211], v[4:7]
	v_mfma_f32_16x16x32_bf16 v[0:3], v[176:179], v[208:211], v[0:3]
	s_setprio 0
	s_barrier
	s_setprio 2
	s_add_i32 s60, 0, 0x18000
	s_add_i32 s61, 0, 0x1c000
	v_add_u32_e32 v160, s60, v145
	v_add_u32_e32 v176, s61, v145
	ds_read_b128 v[140:143], v160
	ds_read_b128 v[152:155], v160 offset:1024
	ds_read_b128 v[156:159], v160 offset:2048
	ds_read_b128 v[160:163], v160 offset:3072
	ds_read_b128 v[164:167], v176
	ds_read_b128 v[168:171], v176 offset:1024
	ds_read_b128 v[172:175], v176 offset:2048
	ds_read_b128 v[176:179], v176 offset:3072
	s_add_u32 s76, s76, 0x200000
	s_addc_u32 s77, s77, 0
	s_mov_b32 m0, s12
	v_lshl_add_u64 v[220:221], s[76:77], 0, v[128:129]
	ds_read_b128 v[180:183], v151 offset:32768
	ds_read_b128 v[184:187], v151 offset:33792
	ds_read_b128 v[188:191], v151 offset:34816
	ds_read_b128 v[192:195], v151 offset:35840
	ds_read_b128 v[196:199], v151 offset:36864
	ds_read_b128 v[200:203], v151 offset:37888
	ds_read_b128 v[204:207], v151 offset:38912
	ds_read_b128 v[208:211], v151 offset:39936
	global_load_lds_dwordx4 v[220:221], off
	v_lshl_add_u64 v[220:221], s[76:77], 0, v[130:131]
	s_mov_b32 m0, s13
	s_nop 0
	global_load_lds_dwordx4 v[220:221], off
	s_setprio 0
	s_waitcnt vmcnt(8)
	s_waitcnt lgkmcnt(0)
	s_barrier
	s_setprio 1
	s_waitcnt lgkmcnt(0)
	v_mfma_f32_16x16x32_bf16 v[124:127], v[140:143], v[180:183], v[124:127]
	v_mfma_f32_16x16x32_bf16 v[120:123], v[156:159], v[180:183], v[120:123]
	v_mfma_f32_16x16x32_bf16 v[108:111], v[140:143], v[188:191], v[108:111]
	v_mfma_f32_16x16x32_bf16 v[104:107], v[156:159], v[188:191], v[104:107]
	v_mfma_f32_16x16x32_bf16 v[92:95], v[140:143], v[196:199], v[92:95]
	v_mfma_f32_16x16x32_bf16 v[88:91], v[156:159], v[196:199], v[88:91]
	v_mfma_f32_16x16x32_bf16 v[76:79], v[140:143], v[204:207], v[76:79]
	v_mfma_f32_16x16x32_bf16 v[72:75], v[156:159], v[204:207], v[72:75]
	v_mfma_f32_16x16x32_bf16 v[124:127], v[152:155], v[184:187], v[124:127]
	v_mfma_f32_16x16x32_bf16 v[120:123], v[160:163], v[184:187], v[120:123]
	v_mfma_f32_16x16x32_bf16 v[108:111], v[152:155], v[192:195], v[108:111]
	v_mfma_f32_16x16x32_bf16 v[104:107], v[160:163], v[192:195], v[104:107]
	v_mfma_f32_16x16x32_bf16 v[92:95], v[152:155], v[200:203], v[92:95]
	v_mfma_f32_16x16x32_bf16 v[88:91], v[160:163], v[200:203], v[88:91]
	v_mfma_f32_16x16x32_bf16 v[76:79], v[152:155], v[208:211], v[76:79]
	v_mfma_f32_16x16x32_bf16 v[72:75], v[160:163], v[208:211], v[72:75]
	v_mfma_f32_16x16x32_bf16 v[116:119], v[164:167], v[180:183], v[116:119]
	v_mfma_f32_16x16x32_bf16 v[112:115], v[172:175], v[180:183], v[112:115]
	v_mfma_f32_16x16x32_bf16 v[100:103], v[164:167], v[188:191], v[100:103]
	v_mfma_f32_16x16x32_bf16 v[96:99], v[172:175], v[188:191], v[96:99]
	v_mfma_f32_16x16x32_bf16 v[84:87], v[164:167], v[196:199], v[84:87]
	v_mfma_f32_16x16x32_bf16 v[80:83], v[172:175], v[196:199], v[80:83]
	v_mfma_f32_16x16x32_bf16 v[68:71], v[164:167], v[204:207], v[68:71]
	v_mfma_f32_16x16x32_bf16 v[64:67], v[172:175], v[204:207], v[64:67]
	v_mfma_f32_16x16x32_bf16 v[116:119], v[168:171], v[184:187], v[116:119]
	v_mfma_f32_16x16x32_bf16 v[112:115], v[176:179], v[184:187], v[112:115]
	v_mfma_f32_16x16x32_bf16 v[100:103], v[168:171], v[192:195], v[100:103]
	v_mfma_f32_16x16x32_bf16 v[96:99], v[176:179], v[192:195], v[96:99]
	v_mfma_f32_16x16x32_bf16 v[84:87], v[168:171], v[200:203], v[84:87]
	v_mfma_f32_16x16x32_bf16 v[80:83], v[176:179], v[200:203], v[80:83]
	v_mfma_f32_16x16x32_bf16 v[68:71], v[168:171], v[208:211], v[68:71]
	v_mfma_f32_16x16x32_bf16 v[64:67], v[176:179], v[208:211], v[64:67]
	s_setprio 0
	s_barrier
	s_setprio 2
	s_add_i32 s60, s60, s94
	v_lshl_add_u64 v[212:213], v[212:213], 0, s[22:23]
	s_mov_b32 m0, s60
	ds_read_b128 v[180:183], v151 offset:49152
	ds_read_b128 v[184:187], v151 offset:50176
	ds_read_b128 v[188:191], v151 offset:51200
	ds_read_b128 v[192:195], v151 offset:52224
	ds_read_b128 v[196:199], v151 offset:53248
	ds_read_b128 v[200:203], v151 offset:54272
	ds_read_b128 v[204:207], v151 offset:55296
	ds_read_b128 v[208:211], v151 offset:56320
	global_load_lds_dwordx4 v[212:213], off
	s_add_i32 m0, s60, 0x2000
	s_add_u32 s74, s74, 0x200080
	v_lshl_add_u64 v[212:213], v[214:215], 0, s[22:23]
	s_addc_u32 s75, s75, 0
	s_add_i32 s60, s61, s94
	global_load_lds_dwordx4 v[212:213], off
	v_lshl_add_u64 v[212:213], s[74:75], 0, v[128:129]
	s_mov_b32 m0, s60
	s_nop 0
	global_load_lds_dwordx4 v[212:213], off
	v_lshl_add_u64 v[212:213], s[74:75], 0, v[130:131]
	s_add_i32 m0, s60, 0x2000
	s_nop 0
	global_load_lds_dwordx4 v[212:213], off
	v_lshl_add_u64 v[212:213], v[216:217], 0, s[22:23]
	s_mov_b32 m0, s29
	s_nop 0
	global_load_lds_dwordx4 v[212:213], off
	v_lshl_add_u64 v[212:213], v[218:219], 0, s[22:23]
	s_mov_b32 m0, s30
	s_nop 0
	global_load_lds_dwordx4 v[212:213], off
	s_setprio 0
	s_waitcnt vmcnt(8)
	s_waitcnt lgkmcnt(0)
	s_barrier
	s_setprio 1
	s_waitcnt lgkmcnt(0)
	v_mfma_f32_16x16x32_bf16 v[60:63], v[140:143], v[180:183], v[60:63]
	v_mfma_f32_16x16x32_bf16 v[56:59], v[156:159], v[180:183], v[56:59]
	v_mfma_f32_16x16x32_bf16 v[44:47], v[140:143], v[188:191], v[44:47]
	v_mfma_f32_16x16x32_bf16 v[40:43], v[156:159], v[188:191], v[40:43]
	v_mfma_f32_16x16x32_bf16 v[28:31], v[140:143], v[196:199], v[28:31]
	v_mfma_f32_16x16x32_bf16 v[24:27], v[156:159], v[196:199], v[24:27]
	v_mfma_f32_16x16x32_bf16 v[12:15], v[140:143], v[204:207], v[12:15]
	v_mfma_f32_16x16x32_bf16 v[8:11], v[156:159], v[204:207], v[8:11]
	v_mfma_f32_16x16x32_bf16 v[60:63], v[152:155], v[184:187], v[60:63]
	v_mfma_f32_16x16x32_bf16 v[56:59], v[160:163], v[184:187], v[56:59]
	v_mfma_f32_16x16x32_bf16 v[44:47], v[152:155], v[192:195], v[44:47]
	v_mfma_f32_16x16x32_bf16 v[40:43], v[160:163], v[192:195], v[40:43]
	v_mfma_f32_16x16x32_bf16 v[28:31], v[152:155], v[200:203], v[28:31]
	v_mfma_f32_16x16x32_bf16 v[24:27], v[160:163], v[200:203], v[24:27]
	v_mfma_f32_16x16x32_bf16 v[12:15], v[152:155], v[208:211], v[12:15]
	v_mfma_f32_16x16x32_bf16 v[8:11], v[160:163], v[208:211], v[8:11]
	v_mfma_f32_16x16x32_bf16 v[52:55], v[164:167], v[180:183], v[52:55]
	v_mfma_f32_16x16x32_bf16 v[48:51], v[172:175], v[180:183], v[48:51]
	v_mfma_f32_16x16x32_bf16 v[36:39], v[164:167], v[188:191], v[36:39]
	v_mfma_f32_16x16x32_bf16 v[32:35], v[172:175], v[188:191], v[32:35]
	v_mfma_f32_16x16x32_bf16 v[20:23], v[164:167], v[196:199], v[20:23]
	v_mfma_f32_16x16x32_bf16 v[16:19], v[172:175], v[196:199], v[16:19]
	v_mfma_f32_16x16x32_bf16 v[4:7], v[164:167], v[204:207], v[4:7]
	v_mfma_f32_16x16x32_bf16 v[0:3], v[172:175], v[204:207], v[0:3]
	v_mfma_f32_16x16x32_bf16 v[52:55], v[168:171], v[184:187], v[52:55]
	v_mfma_f32_16x16x32_bf16 v[48:51], v[176:179], v[184:187], v[48:51]
	v_mfma_f32_16x16x32_bf16 v[36:39], v[168:171], v[192:195], v[36:39]
	v_mfma_f32_16x16x32_bf16 v[32:35], v[176:179], v[192:195], v[32:35]
	v_mfma_f32_16x16x32_bf16 v[20:23], v[168:171], v[200:203], v[20:23]
	v_mfma_f32_16x16x32_bf16 v[16:19], v[176:179], v[200:203], v[16:19]
	v_mfma_f32_16x16x32_bf16 v[4:7], v[168:171], v[208:211], v[4:7]
	v_mfma_f32_16x16x32_bf16 v[0:3], v[176:179], v[208:211], v[0:3]
	s_setprio 0
	s_barrier
	s_setprio 2
	s_add_i32 s79, s79, 2
	s_add_u32 s72, s72, 0x100
	s_addc_u32 s73, s73, 0
	s_add_u32 s71, s71, 0x100
	s_addc_u32 s78, s78, 0
	s_cmpk_gt_u32 s79, 0x7d
	s_cbranch_scc0 .LBB0_1897
	s_setprio 0
	s_and_b64 vcc, exec, s[58:59]
	s_cbranch_vccz .LBB0_1900
	s_barrier

.LBB0_2128:
	ds_read_b128 v[148:151], v179
	ds_read_b128 v[152:155], v179 offset:1024
	ds_read_b128 v[156:159], v179 offset:2048
	ds_read_b128 v[160:163], v179 offset:3072
	ds_read_b128 v[164:167], v180
	ds_read_b128 v[168:171], v180 offset:1024
	ds_read_b128 v[184:187], v180 offset:2048
	ds_read_b128 v[188:191], v180 offset:3072
	s_add_u32 s60, s84, 0xfff80080
	s_addc_u32 s61, s85, -1
	s_cmp_eq_u32 s95, 28
	s_cselect_b32 s89, s23, s61
	s_cselect_b32 s88, s79, s60
	s_cselect_b32 s87, s77, s97
	s_cselect_b32 s86, vcc_lo, vcc_hi
	v_lshl_add_u64 v[172:173], s[84:85], 0, v[140:141]
	s_add_i32 m0, s6, 0xc000
	ds_read_b128 v[192:195], v181
	ds_read_b128 v[196:199], v181 offset:1024
	ds_read_b128 v[200:203], v181 offset:2048
	ds_read_b128 v[204:207], v181 offset:3072
	ds_read_b128 v[208:211], v181 offset:4096
	ds_read_b128 v[212:215], v181 offset:5120
	ds_read_b128 v[216:219], v181 offset:6144
	ds_read_b128 v[220:223], v181 offset:7168
	global_load_lds_dwordx4 v[172:173], off
	v_lshl_add_u64 v[172:173], s[84:85], 0, v[142:143]
	s_add_i32 m0, s6, 0xe000
	s_nop 0
	global_load_lds_dwordx4 v[172:173], off
	s_waitcnt vmcnt(8)
	s_waitcnt lgkmcnt(0)
	s_barrier
	s_setprio 1
	s_waitcnt lgkmcnt(0)
	v_mfma_f32_16x16x32_bf16 v[124:127], v[148:151], v[192:195], v[124:127]
	v_mfma_f32_16x16x32_bf16 v[120:123], v[156:159], v[192:195], v[120:123]
	v_mfma_f32_16x16x32_bf16 v[108:111], v[148:151], v[200:203], v[108:111]
	v_mfma_f32_16x16x32_bf16 v[104:107], v[156:159], v[200:203], v[104:107]
	v_mfma_f32_16x16x32_bf16 v[92:95], v[148:151], v[208:211], v[92:95]
	v_mfma_f32_16x16x32_bf16 v[88:91], v[156:159], v[208:211], v[88:91]
	v_mfma_f32_16x16x32_bf16 v[76:79], v[148:151], v[216:219], v[76:79]
	v_mfma_f32_16x16x32_bf16 v[72:75], v[156:159], v[216:219], v[72:75]
	v_mfma_f32_16x16x32_bf16 v[124:127], v[152:155], v[196:199], v[124:127]
	v_mfma_f32_16x16x32_bf16 v[120:123], v[160:163], v[196:199], v[120:123]
	v_mfma_f32_16x16x32_bf16 v[108:111], v[152:155], v[204:207], v[108:111]
	v_mfma_f32_16x16x32_bf16 v[104:107], v[160:163], v[204:207], v[104:107]
	v_mfma_f32_16x16x32_bf16 v[92:95], v[152:155], v[212:215], v[92:95]
	v_mfma_f32_16x16x32_bf16 v[88:91], v[160:163], v[212:215], v[88:91]
	v_mfma_f32_16x16x32_bf16 v[76:79], v[152:155], v[220:223], v[76:79]
	v_mfma_f32_16x16x32_bf16 v[72:75], v[160:163], v[220:223], v[72:75]
	v_mfma_f32_16x16x32_bf16 v[116:119], v[164:167], v[192:195], v[116:119]
	v_mfma_f32_16x16x32_bf16 v[112:115], v[184:187], v[192:195], v[112:115]
	v_mfma_f32_16x16x32_bf16 v[100:103], v[164:167], v[200:203], v[100:103]
	v_mfma_f32_16x16x32_bf16 v[96:99], v[184:187], v[200:203], v[96:99]
	v_mfma_f32_16x16x32_bf16 v[84:87], v[164:167], v[208:211], v[84:87]
	v_mfma_f32_16x16x32_bf16 v[80:83], v[184:187], v[208:211], v[80:83]
	v_mfma_f32_16x16x32_bf16 v[68:71], v[164:167], v[216:219], v[68:71]
	v_mfma_f32_16x16x32_bf16 v[64:67], v[184:187], v[216:219], v[64:67]
	v_mfma_f32_16x16x32_bf16 v[116:119], v[168:171], v[196:199], v[116:119]
	v_mfma_f32_16x16x32_bf16 v[112:115], v[188:191], v[196:199], v[112:115]
	v_mfma_f32_16x16x32_bf16 v[100:103], v[168:171], v[204:207], v[100:103]
	v_mfma_f32_16x16x32_bf16 v[96:99], v[188:191], v[204:207], v[96:99]
	v_mfma_f32_16x16x32_bf16 v[84:87], v[168:171], v[212:215], v[84:87]
	v_mfma_f32_16x16x32_bf16 v[80:83], v[188:191], v[212:215], v[80:83]
	v_mfma_f32_16x16x32_bf16 v[68:71], v[168:171], v[220:223], v[68:71]
	v_mfma_f32_16x16x32_bf16 v[64:67], v[188:191], v[220:223], v[64:67]
	s_setprio 0
	s_barrier
	s_setprio 2
	s_add_i32 s60, s12, s94
	v_lshl_add_u64 v[172:173], s[86:87], 0, v[130:131]
	s_mov_b32 m0, s60
	ds_read_b128 v[192:195], v181 offset:16384
	ds_read_b128 v[196:199], v181 offset:17408
	ds_read_b128 v[200:203], v181 offset:18432
	ds_read_b128 v[204:207], v181 offset:19456
	ds_read_b128 v[208:211], v181 offset:20480
	ds_read_b128 v[212:215], v181 offset:21504
	ds_read_b128 v[216:219], v181 offset:22528
	ds_read_b128 v[220:223], v181 offset:23552
	global_load_lds_dwordx4 v[172:173], off
	s_add_i32 m0, s60, 0x2000
	s_add_u32 s60, s86, 0x80000
	v_lshl_add_u64 v[224:225], s[86:87], 0, v[134:135]
	s_addc_u32 s61, s87, 0
	s_add_i32 s96, s13, s94
	global_load_lds_dwordx4 v[224:225], off
	v_lshl_add_u64 v[226:227], s[60:61], 0, v[130:131]
	s_mov_b32 m0, s96
	v_lshl_add_u64 v[228:229], s[88:89], 0, v[132:133]
	global_load_lds_dwordx4 v[226:227], off
	v_lshl_add_u64 v[226:227], s[60:61], 0, v[134:135]
	s_add_i32 m0, s96, 0x2000
	s_nop 0
	global_load_lds_dwordx4 v[226:227], off
	v_lshl_add_u64 v[226:227], s[88:89], 0, v[128:129]
	s_mov_b32 m0, s6
	s_nop 0
	global_load_lds_dwordx4 v[226:227], off
	s_mov_b32 m0, s7
	s_nop 0
	global_load_lds_dwordx4 v[228:229], off
	s_setprio 0
	s_waitcnt vmcnt(8)
	s_waitcnt lgkmcnt(0)
	s_barrier
	s_setprio 1
	s_waitcnt lgkmcnt(0)
	v_mfma_f32_16x16x32_bf16 v[60:63], v[148:151], v[192:195], v[60:63]
	v_mfma_f32_16x16x32_bf16 v[56:59], v[156:159], v[192:195], v[56:59]
	v_mfma_f32_16x16x32_bf16 v[44:47], v[148:151], v[200:203], v[44:47]
	v_mfma_f32_16x16x32_bf16 v[40:43], v[156:159], v[200:203], v[40:43]
	v_mfma_f32_16x16x32_bf16 v[28:31], v[148:151], v[208:211], v[28:31]
	v_mfma_f32_16x16x32_bf16 v[24:27], v[156:159], v[208:211], v[24:27]
	v_mfma_f32_16x16x32_bf16 v[12:15], v[148:151], v[216:219], v[12:15]
	v_mfma_f32_16x16x32_bf16 v[8:11], v[156:159], v[216:219], v[8:11]
	v_mfma_f32_16x16x32_bf16 v[60:63], v[152:155], v[196:199], v[60:63]
	v_mfma_f32_16x16x32_bf16 v[56:59], v[160:163], v[196:199], v[56:59]
	v_mfma_f32_16x16x32_bf16 v[44:47], v[152:155], v[204:207], v[44:47]
	v_mfma_f32_16x16x32_bf16 v[40:43], v[160:163], v[204:207], v[40:43]
	v_mfma_f32_16x16x32_bf16 v[28:31], v[152:155], v[212:215], v[28:31]
	v_mfma_f32_16x16x32_bf16 v[24:27], v[160:163], v[212:215], v[24:27]
	v_mfma_f32_16x16x32_bf16 v[12:15], v[152:155], v[220:223], v[12:15]
	v_mfma_f32_16x16x32_bf16 v[8:11], v[160:163], v[220:223], v[8:11]
	v_mfma_f32_16x16x32_bf16 v[52:55], v[164:167], v[192:195], v[52:55]
	v_mfma_f32_16x16x32_bf16 v[48:51], v[184:187], v[192:195], v[48:51]
	v_mfma_f32_16x16x32_bf16 v[36:39], v[164:167], v[200:203], v[36:39]
	v_mfma_f32_16x16x32_bf16 v[32:35], v[184:187], v[200:203], v[32:35]
	v_mfma_f32_16x16x32_bf16 v[20:23], v[164:167], v[208:211], v[20:23]
	v_mfma_f32_16x16x32_bf16 v[16:19], v[184:187], v[208:211], v[16:19]
	v_mfma_f32_16x16x32_bf16 v[4:7], v[164:167], v[216:219], v[4:7]
	v_mfma_f32_16x16x32_bf16 v[0:3], v[184:187], v[216:219], v[0:3]
	v_mfma_f32_16x16x32_bf16 v[52:55], v[168:171], v[196:199], v[52:55]
	v_mfma_f32_16x16x32_bf16 v[48:51], v[188:191], v[196:199], v[48:51]
	v_mfma_f32_16x16x32_bf16 v[36:39], v[168:171], v[204:207], v[36:39]
	v_mfma_f32_16x16x32_bf16 v[32:35], v[188:191], v[204:207], v[32:35]
	v_mfma_f32_16x16x32_bf16 v[20:23], v[168:171], v[212:215], v[20:23]
	v_mfma_f32_16x16x32_bf16 v[16:19], v[188:191], v[212:215], v[16:19]
	v_mfma_f32_16x16x32_bf16 v[4:7], v[168:171], v[220:223], v[4:7]
	v_mfma_f32_16x16x32_bf16 v[0:3], v[188:191], v[220:223], v[0:3]
	s_setprio 0
	s_barrier
	s_setprio 2
	s_add_i32 s96, 0, 0x18000
	v_add_u32_e32 v136, s96, v175
	s_add_i32 s8, 0, 0x1c000
	ds_read_b128 v[148:151], v136
	ds_read_b128 v[152:155], v136 offset:1024
	ds_read_b128 v[156:159], v136 offset:2048
	ds_read_b128 v[160:163], v136 offset:3072
	v_add_u32_e32 v136, s8, v175
	ds_read_b128 v[164:167], v136
	ds_read_b128 v[168:171], v136 offset:1024
	ds_read_b128 v[184:187], v136 offset:2048
	ds_read_b128 v[188:191], v136 offset:3072
	s_add_u32 s60, s88, 0x80000
	s_addc_u32 s61, s89, 0
	s_mov_b32 m0, s34
	v_lshl_add_u64 v[230:231], s[60:61], 0, v[128:129]
	ds_read_b128 v[192:195], v181 offset:32768
	ds_read_b128 v[196:199], v181 offset:33792
	ds_read_b128 v[200:203], v181 offset:34816
	ds_read_b128 v[204:207], v181 offset:35840
	ds_read_b128 v[208:211], v181 offset:36864
	ds_read_b128 v[212:215], v181 offset:37888
	ds_read_b128 v[216:219], v181 offset:38912
	ds_read_b128 v[220:223], v181 offset:39936
	global_load_lds_dwordx4 v[230:231], off
	v_lshl_add_u64 v[230:231], s[60:61], 0, v[132:133]
	s_mov_b32 m0, s46
	s_nop 0
	global_load_lds_dwordx4 v[230:231], off
	s_setprio 0
	s_waitcnt vmcnt(8)
	s_waitcnt lgkmcnt(0)
	s_barrier
	s_setprio 1
	s_waitcnt lgkmcnt(0)
	v_mfma_f32_16x16x32_bf16 v[124:127], v[148:151], v[192:195], v[124:127]
	v_mfma_f32_16x16x32_bf16 v[120:123], v[156:159], v[192:195], v[120:123]
	v_mfma_f32_16x16x32_bf16 v[108:111], v[148:151], v[200:203], v[108:111]
	v_mfma_f32_16x16x32_bf16 v[104:107], v[156:159], v[200:203], v[104:107]
	v_mfma_f32_16x16x32_bf16 v[92:95], v[148:151], v[208:211], v[92:95]
	v_mfma_f32_16x16x32_bf16 v[88:91], v[156:159], v[208:211], v[88:91]
	v_mfma_f32_16x16x32_bf16 v[76:79], v[148:151], v[216:219], v[76:79]
	v_mfma_f32_16x16x32_bf16 v[72:75], v[156:159], v[216:219], v[72:75]
	v_mfma_f32_16x16x32_bf16 v[124:127], v[152:155], v[196:199], v[124:127]
	v_mfma_f32_16x16x32_bf16 v[120:123], v[160:163], v[196:199], v[120:123]
	v_mfma_f32_16x16x32_bf16 v[108:111], v[152:155], v[204:207], v[108:111]
	v_mfma_f32_16x16x32_bf16 v[104:107], v[160:163], v[204:207], v[104:107]
	v_mfma_f32_16x16x32_bf16 v[92:95], v[152:155], v[212:215], v[92:95]
	v_mfma_f32_16x16x32_bf16 v[88:91], v[160:163], v[212:215], v[88:91]
	v_mfma_f32_16x16x32_bf16 v[76:79], v[152:155], v[220:223], v[76:79]
	v_mfma_f32_16x16x32_bf16 v[72:75], v[160:163], v[220:223], v[72:75]
	v_mfma_f32_16x16x32_bf16 v[116:119], v[164:167], v[192:195], v[116:119]
	v_mfma_f32_16x16x32_bf16 v[112:115], v[184:187], v[192:195], v[112:115]
	v_mfma_f32_16x16x32_bf16 v[100:103], v[164:167], v[200:203], v[100:103]
	v_mfma_f32_16x16x32_bf16 v[96:99], v[184:187], v[200:203], v[96:99]
	v_mfma_f32_16x16x32_bf16 v[84:87], v[164:167], v[208:211], v[84:87]
	v_mfma_f32_16x16x32_bf16 v[80:83], v[184:187], v[208:211], v[80:83]
	v_mfma_f32_16x16x32_bf16 v[68:71], v[164:167], v[216:219], v[68:71]
	v_mfma_f32_16x16x32_bf16 v[64:67], v[184:187], v[216:219], v[64:67]
	v_mfma_f32_16x16x32_bf16 v[116:119], v[168:171], v[196:199], v[116:119]
	v_mfma_f32_16x16x32_bf16 v[112:115], v[188:191], v[196:199], v[112:115]
	v_mfma_f32_16x16x32_bf16 v[100:103], v[168:171], v[204:207], v[100:103]
	v_mfma_f32_16x16x32_bf16 v[96:99], v[188:191], v[204:207], v[96:99]
	v_mfma_f32_16x16x32_bf16 v[84:87], v[168:171], v[212:215], v[84:87]
	v_mfma_f32_16x16x32_bf16 v[80:83], v[188:191], v[212:215], v[80:83]
	v_mfma_f32_16x16x32_bf16 v[68:71], v[168:171], v[220:223], v[68:71]
	v_mfma_f32_16x16x32_bf16 v[64:67], v[188:191], v[220:223], v[64:67]
	s_setprio 0
	s_barrier
	s_setprio 2
	s_add_i32 s9, s96, s94
	v_lshl_add_u64 v[172:173], v[172:173], 0, s[74:75]
	s_mov_b32 m0, s9
	ds_read_b128 v[192:195], v181 offset:49152
	ds_read_b128 v[196:199], v181 offset:50176
	ds_read_b128 v[200:203], v181 offset:51200
	ds_read_b128 v[204:207], v181 offset:52224
	ds_read_b128 v[208:211], v181 offset:53248
	ds_read_b128 v[212:215], v181 offset:54272
	ds_read_b128 v[216:219], v181 offset:55296
	ds_read_b128 v[220:223], v181 offset:56320
	global_load_lds_dwordx4 v[172:173], off
	s_add_i32 m0, s9, 0x2000
	s_add_u32 s60, s86, 0x80080
	v_lshl_add_u64 v[172:173], v[224:225], 0, s[74:75]
	s_addc_u32 s61, s87, 0
	s_add_i32 s8, s8, s94
	global_load_lds_dwordx4 v[172:173], off
	v_lshl_add_u64 v[172:173], s[60:61], 0, v[130:131]
	s_mov_b32 m0, s8
	s_nop 0
	global_load_lds_dwordx4 v[172:173], off
	v_lshl_add_u64 v[172:173], s[60:61], 0, v[134:135]
	s_add_i32 m0, s8, 0x2000
	s_nop 0
	global_load_lds_dwordx4 v[172:173], off
	v_lshl_add_u64 v[172:173], v[226:227], 0, s[74:75]
	s_mov_b32 m0, s56
	s_nop 0
	global_load_lds_dwordx4 v[172:173], off
	v_lshl_add_u64 v[172:173], v[228:229], 0, s[74:75]
	s_mov_b32 m0, s57
	s_nop 0
	global_load_lds_dwordx4 v[172:173], off
	s_setprio 0
	s_waitcnt vmcnt(8)
	s_waitcnt lgkmcnt(0)
	s_barrier
	s_setprio 1
	s_waitcnt lgkmcnt(0)
	v_mfma_f32_16x16x32_bf16 v[60:63], v[148:151], v[192:195], v[60:63]
	v_mfma_f32_16x16x32_bf16 v[56:59], v[156:159], v[192:195], v[56:59]
	v_mfma_f32_16x16x32_bf16 v[44:47], v[148:151], v[200:203], v[44:47]
	v_mfma_f32_16x16x32_bf16 v[40:43], v[156:159], v[200:203], v[40:43]
	v_mfma_f32_16x16x32_bf16 v[28:31], v[148:151], v[208:211], v[28:31]
	v_mfma_f32_16x16x32_bf16 v[24:27], v[156:159], v[208:211], v[24:27]
	v_mfma_f32_16x16x32_bf16 v[12:15], v[148:151], v[216:219], v[12:15]
	v_mfma_f32_16x16x32_bf16 v[8:11], v[156:159], v[216:219], v[8:11]
	v_mfma_f32_16x16x32_bf16 v[60:63], v[152:155], v[196:199], v[60:63]
	v_mfma_f32_16x16x32_bf16 v[56:59], v[160:163], v[196:199], v[56:59]
	v_mfma_f32_16x16x32_bf16 v[44:47], v[152:155], v[204:207], v[44:47]
	v_mfma_f32_16x16x32_bf16 v[40:43], v[160:163], v[204:207], v[40:43]
	v_mfma_f32_16x16x32_bf16 v[28:31], v[152:155], v[212:215], v[28:31]
	v_mfma_f32_16x16x32_bf16 v[24:27], v[160:163], v[212:215], v[24:27]
	v_mfma_f32_16x16x32_bf16 v[12:15], v[152:155], v[220:223], v[12:15]
	v_mfma_f32_16x16x32_bf16 v[8:11], v[160:163], v[220:223], v[8:11]
	v_mfma_f32_16x16x32_bf16 v[52:55], v[164:167], v[192:195], v[52:55]
	v_mfma_f32_16x16x32_bf16 v[48:51], v[184:187], v[192:195], v[48:51]
	v_mfma_f32_16x16x32_bf16 v[36:39], v[164:167], v[200:203], v[36:39]
	v_mfma_f32_16x16x32_bf16 v[32:35], v[184:187], v[200:203], v[32:35]
	v_mfma_f32_16x16x32_bf16 v[20:23], v[164:167], v[208:211], v[20:23]
	v_mfma_f32_16x16x32_bf16 v[16:19], v[184:187], v[208:211], v[16:19]
	v_mfma_f32_16x16x32_bf16 v[4:7], v[164:167], v[216:219], v[4:7]
	v_mfma_f32_16x16x32_bf16 v[0:3], v[184:187], v[216:219], v[0:3]
	v_mfma_f32_16x16x32_bf16 v[52:55], v[168:171], v[196:199], v[52:55]
	v_mfma_f32_16x16x32_bf16 v[48:51], v[188:191], v[196:199], v[48:51]
	v_mfma_f32_16x16x32_bf16 v[36:39], v[168:171], v[204:207], v[36:39]
	v_mfma_f32_16x16x32_bf16 v[32:35], v[188:191], v[204:207], v[32:35]
	v_mfma_f32_16x16x32_bf16 v[20:23], v[168:171], v[212:215], v[20:23]
	v_mfma_f32_16x16x32_bf16 v[16:19], v[188:191], v[212:215], v[16:19]
	v_mfma_f32_16x16x32_bf16 v[4:7], v[168:171], v[220:223], v[4:7]
	v_mfma_f32_16x16x32_bf16 v[0:3], v[188:191], v[220:223], v[0:3]
	s_setprio 0
	s_barrier
	s_setprio 2
	s_add_i32 s95, s95, 2
	s_add_u32 s84, s84, 0x100
	s_addc_u32 s85, s85, 0
	s_add_u32 vcc_hi, vcc_hi, 0x100
	s_addc_u32 s97, s97, 0
	s_cmp_gt_u32 s95, 29
	s_cbranch_scc0 .LBB0_2128
	s_setprio 0
	s_and_b64 vcc, exec, s[58:59]
	s_cbranch_vccz .LBB0_2131
	s_barrier

.LBB0_2459:
	ds_read_b128 v[148:151], v163
	ds_read_b128 v[152:155], v163 offset:1024
	ds_read_b128 v[168:171], v163 offset:2048
	ds_read_b128 v[172:175], v163 offset:3072
	ds_read_b128 v[176:179], v164
	ds_read_b128 v[180:183], v164 offset:1024
	ds_read_b128 v[184:187], v164 offset:2048
	ds_read_b128 v[188:191], v164 offset:3072
	s_add_u32 s16, s70, 0x100
	s_addc_u32 s17, s71, 0
	s_cmp_eq_u32 s86, 8
	s_cselect_b32 s75, s23, s17
	s_cselect_b32 s74, s22, s16
	s_cselect_b32 s73, s49, s85
	s_cselect_b32 s72, s48, s84
	v_lshl_add_u64 v[156:157], s[70:71], 0, v[140:141]
	s_add_i32 m0, s12, 0xc000
	ds_read_b128 v[192:195], v165
	ds_read_b128 v[196:199], v165 offset:1024
	ds_read_b128 v[200:203], v165 offset:2048
	ds_read_b128 v[204:207], v165 offset:3072
	ds_read_b128 v[208:211], v165 offset:4096
	ds_read_b128 v[212:215], v165 offset:5120
	ds_read_b128 v[216:219], v165 offset:6144
	ds_read_b128 v[220:223], v165 offset:7168
	global_load_lds_dwordx4 v[156:157], off
	v_lshl_add_u64 v[156:157], s[70:71], 0, v[142:143]
	s_add_i32 m0, s12, 0xe000
	s_nop 0
	global_load_lds_dwordx4 v[156:157], off
	s_waitcnt vmcnt(8)
	s_waitcnt lgkmcnt(0)
	s_barrier
	s_setprio 1
	s_waitcnt lgkmcnt(0)
	v_mfma_f32_16x16x32_bf16 v[124:127], v[148:151], v[192:195], v[124:127]
	v_mfma_f32_16x16x32_bf16 v[120:123], v[168:171], v[192:195], v[120:123]
	v_mfma_f32_16x16x32_bf16 v[108:111], v[148:151], v[200:203], v[108:111]
	v_mfma_f32_16x16x32_bf16 v[104:107], v[168:171], v[200:203], v[104:107]
	v_mfma_f32_16x16x32_bf16 v[92:95], v[148:151], v[208:211], v[92:95]
	v_mfma_f32_16x16x32_bf16 v[88:91], v[168:171], v[208:211], v[88:91]
	v_mfma_f32_16x16x32_bf16 v[76:79], v[148:151], v[216:219], v[76:79]
	v_mfma_f32_16x16x32_bf16 v[72:75], v[168:171], v[216:219], v[72:75]
	v_mfma_f32_16x16x32_bf16 v[124:127], v[152:155], v[196:199], v[124:127]
	v_mfma_f32_16x16x32_bf16 v[120:123], v[172:175], v[196:199], v[120:123]
	v_mfma_f32_16x16x32_bf16 v[108:111], v[152:155], v[204:207], v[108:111]
	v_mfma_f32_16x16x32_bf16 v[104:107], v[172:175], v[204:207], v[104:107]
	v_mfma_f32_16x16x32_bf16 v[92:95], v[152:155], v[212:215], v[92:95]
	v_mfma_f32_16x16x32_bf16 v[88:91], v[172:175], v[212:215], v[88:91]
	v_mfma_f32_16x16x32_bf16 v[76:79], v[152:155], v[220:223], v[76:79]
	v_mfma_f32_16x16x32_bf16 v[72:75], v[172:175], v[220:223], v[72:75]
	v_mfma_f32_16x16x32_bf16 v[116:119], v[176:179], v[192:195], v[116:119]
	v_mfma_f32_16x16x32_bf16 v[112:115], v[184:187], v[192:195], v[112:115]
	v_mfma_f32_16x16x32_bf16 v[100:103], v[176:179], v[200:203], v[100:103]
	v_mfma_f32_16x16x32_bf16 v[96:99], v[184:187], v[200:203], v[96:99]
	v_mfma_f32_16x16x32_bf16 v[84:87], v[176:179], v[208:211], v[84:87]
	v_mfma_f32_16x16x32_bf16 v[80:83], v[184:187], v[208:211], v[80:83]
	v_mfma_f32_16x16x32_bf16 v[68:71], v[176:179], v[216:219], v[68:71]
	v_mfma_f32_16x16x32_bf16 v[64:67], v[184:187], v[216:219], v[64:67]
	v_mfma_f32_16x16x32_bf16 v[116:119], v[180:183], v[196:199], v[116:119]
	v_mfma_f32_16x16x32_bf16 v[112:115], v[188:191], v[196:199], v[112:115]
	v_mfma_f32_16x16x32_bf16 v[100:103], v[180:183], v[204:207], v[100:103]
	v_mfma_f32_16x16x32_bf16 v[96:99], v[188:191], v[204:207], v[96:99]
	v_mfma_f32_16x16x32_bf16 v[84:87], v[180:183], v[212:215], v[84:87]
	v_mfma_f32_16x16x32_bf16 v[80:83], v[188:191], v[212:215], v[80:83]
	v_mfma_f32_16x16x32_bf16 v[68:71], v[180:183], v[220:223], v[68:71]
	v_mfma_f32_16x16x32_bf16 v[64:67], v[188:191], v[220:223], v[64:67]
	s_setprio 0
	s_barrier
	s_setprio 2
	s_add_i32 s8, s76, s94
	v_lshl_add_u64 v[156:157], s[72:73], 0, v[130:131]
	s_mov_b32 m0, s8
	ds_read_b128 v[192:195], v165 offset:16384
	ds_read_b128 v[196:199], v165 offset:17408
	ds_read_b128 v[200:203], v165 offset:18432
	ds_read_b128 v[204:207], v165 offset:19456
	ds_read_b128 v[208:211], v165 offset:20480
	ds_read_b128 v[212:215], v165 offset:21504
	ds_read_b128 v[216:219], v165 offset:22528
	ds_read_b128 v[220:223], v165 offset:23552
	global_load_lds_dwordx4 v[156:157], off
	s_add_i32 m0, s8, 0x2000
	s_add_u32 s60, s72, 0x30000
	v_lshl_add_u64 v[224:225], s[72:73], 0, v[134:135]
	s_addc_u32 s61, s73, 0
	s_add_i32 s8, s77, s94
	global_load_lds_dwordx4 v[224:225], off
	v_lshl_add_u64 v[226:227], s[60:61], 0, v[130:131]
	s_mov_b32 m0, s8
	v_lshl_add_u64 v[228:229], s[74:75], 0, v[132:133]
	global_load_lds_dwordx4 v[226:227], off
	v_lshl_add_u64 v[226:227], s[60:61], 0, v[134:135]
	s_add_i32 m0, s8, 0x2000
	s_nop 0
	global_load_lds_dwordx4 v[226:227], off
	v_lshl_add_u64 v[226:227], s[74:75], 0, v[128:129]
	s_mov_b32 m0, s12
	s_nop 0
	global_load_lds_dwordx4 v[226:227], off
	s_mov_b32 m0, s13
	s_nop 0
	global_load_lds_dwordx4 v[228:229], off
	s_setprio 0
	s_waitcnt vmcnt(8)
	s_waitcnt lgkmcnt(0)
	s_barrier
	s_setprio 1
	s_waitcnt lgkmcnt(0)
	v_mfma_f32_16x16x32_bf16 v[60:63], v[148:151], v[192:195], v[60:63]
	v_mfma_f32_16x16x32_bf16 v[56:59], v[168:171], v[192:195], v[56:59]
	v_mfma_f32_16x16x32_bf16 v[44:47], v[148:151], v[200:203], v[44:47]
	v_mfma_f32_16x16x32_bf16 v[40:43], v[168:171], v[200:203], v[40:43]
	v_mfma_f32_16x16x32_bf16 v[28:31], v[148:151], v[208:211], v[28:31]
	v_mfma_f32_16x16x32_bf16 v[24:27], v[168:171], v[208:211], v[24:27]
	v_mfma_f32_16x16x32_bf16 v[12:15], v[148:151], v[216:219], v[12:15]
	v_mfma_f32_16x16x32_bf16 v[8:11], v[168:171], v[216:219], v[8:11]
	v_mfma_f32_16x16x32_bf16 v[60:63], v[152:155], v[196:199], v[60:63]
	v_mfma_f32_16x16x32_bf16 v[56:59], v[172:175], v[196:199], v[56:59]
	v_mfma_f32_16x16x32_bf16 v[44:47], v[152:155], v[204:207], v[44:47]
	v_mfma_f32_16x16x32_bf16 v[40:43], v[172:175], v[204:207], v[40:43]
	v_mfma_f32_16x16x32_bf16 v[28:31], v[152:155], v[212:215], v[28:31]
	v_mfma_f32_16x16x32_bf16 v[24:27], v[172:175], v[212:215], v[24:27]
	v_mfma_f32_16x16x32_bf16 v[12:15], v[152:155], v[220:223], v[12:15]
	v_mfma_f32_16x16x32_bf16 v[8:11], v[172:175], v[220:223], v[8:11]
	v_mfma_f32_16x16x32_bf16 v[52:55], v[176:179], v[192:195], v[52:55]
	v_mfma_f32_16x16x32_bf16 v[48:51], v[184:187], v[192:195], v[48:51]
	v_mfma_f32_16x16x32_bf16 v[36:39], v[176:179], v[200:203], v[36:39]
	v_mfma_f32_16x16x32_bf16 v[32:35], v[184:187], v[200:203], v[32:35]
	v_mfma_f32_16x16x32_bf16 v[20:23], v[176:179], v[208:211], v[20:23]
	v_mfma_f32_16x16x32_bf16 v[16:19], v[184:187], v[208:211], v[16:19]
	v_mfma_f32_16x16x32_bf16 v[4:7], v[176:179], v[216:219], v[4:7]
	v_mfma_f32_16x16x32_bf16 v[0:3], v[184:187], v[216:219], v[0:3]
	v_mfma_f32_16x16x32_bf16 v[52:55], v[180:183], v[196:199], v[52:55]
	v_mfma_f32_16x16x32_bf16 v[48:51], v[188:191], v[196:199], v[48:51]
	v_mfma_f32_16x16x32_bf16 v[36:39], v[180:183], v[204:207], v[36:39]
	v_mfma_f32_16x16x32_bf16 v[32:35], v[188:191], v[204:207], v[32:35]
	v_mfma_f32_16x16x32_bf16 v[20:23], v[180:183], v[212:215], v[20:23]
	v_mfma_f32_16x16x32_bf16 v[16:19], v[188:191], v[212:215], v[16:19]
	v_mfma_f32_16x16x32_bf16 v[4:7], v[180:183], v[220:223], v[4:7]
	v_mfma_f32_16x16x32_bf16 v[0:3], v[188:191], v[220:223], v[0:3]
	s_setprio 0
	s_barrier
	s_setprio 2
	s_add_i32 s8, 0, 0x18000
	v_add_u32_e32 v136, s8, v159
	s_add_i32 s9, 0, 0x1c000
	ds_read_b128 v[148:151], v136
	ds_read_b128 v[152:155], v136 offset:1024
	ds_read_b128 v[168:171], v136 offset:2048
	ds_read_b128 v[172:175], v136 offset:3072
	v_add_u32_e32 v136, s9, v159
	ds_read_b128 v[176:179], v136
	ds_read_b128 v[180:183], v136 offset:1024
	ds_read_b128 v[184:187], v136 offset:2048
	ds_read_b128 v[188:191], v136 offset:3072
	s_add_u32 s60, s74, 0x60000
	s_addc_u32 s61, s75, 0
	s_mov_b32 m0, s29
	v_lshl_add_u64 v[230:231], s[60:61], 0, v[128:129]
	ds_read_b128 v[192:195], v165 offset:32768
	ds_read_b128 v[196:199], v165 offset:33792
	ds_read_b128 v[200:203], v165 offset:34816
	ds_read_b128 v[204:207], v165 offset:35840
	ds_read_b128 v[208:211], v165 offset:36864
	ds_read_b128 v[212:215], v165 offset:37888
	ds_read_b128 v[216:219], v165 offset:38912
	ds_read_b128 v[220:223], v165 offset:39936
	global_load_lds_dwordx4 v[230:231], off
	v_lshl_add_u64 v[230:231], s[60:61], 0, v[132:133]
	s_mov_b32 m0, s30
	s_nop 0
	global_load_lds_dwordx4 v[230:231], off
	s_setprio 0
	s_waitcnt vmcnt(8)
	s_waitcnt lgkmcnt(0)
	s_barrier
	s_setprio 1
	s_waitcnt lgkmcnt(0)
	v_mfma_f32_16x16x32_bf16 v[124:127], v[148:151], v[192:195], v[124:127]
	v_mfma_f32_16x16x32_bf16 v[120:123], v[168:171], v[192:195], v[120:123]
	v_mfma_f32_16x16x32_bf16 v[108:111], v[148:151], v[200:203], v[108:111]
	v_mfma_f32_16x16x32_bf16 v[104:107], v[168:171], v[200:203], v[104:107]
	v_mfma_f32_16x16x32_bf16 v[92:95], v[148:151], v[208:211], v[92:95]
	v_mfma_f32_16x16x32_bf16 v[88:91], v[168:171], v[208:211], v[88:91]
	v_mfma_f32_16x16x32_bf16 v[76:79], v[148:151], v[216:219], v[76:79]
	v_mfma_f32_16x16x32_bf16 v[72:75], v[168:171], v[216:219], v[72:75]
	v_mfma_f32_16x16x32_bf16 v[124:127], v[152:155], v[196:199], v[124:127]
	v_mfma_f32_16x16x32_bf16 v[120:123], v[172:175], v[196:199], v[120:123]
	v_mfma_f32_16x16x32_bf16 v[108:111], v[152:155], v[204:207], v[108:111]
	v_mfma_f32_16x16x32_bf16 v[104:107], v[172:175], v[204:207], v[104:107]
	v_mfma_f32_16x16x32_bf16 v[92:95], v[152:155], v[212:215], v[92:95]
	v_mfma_f32_16x16x32_bf16 v[88:91], v[172:175], v[212:215], v[88:91]
	v_mfma_f32_16x16x32_bf16 v[76:79], v[152:155], v[220:223], v[76:79]
	v_mfma_f32_16x16x32_bf16 v[72:75], v[172:175], v[220:223], v[72:75]
	v_mfma_f32_16x16x32_bf16 v[116:119], v[176:179], v[192:195], v[116:119]
	v_mfma_f32_16x16x32_bf16 v[112:115], v[184:187], v[192:195], v[112:115]
	v_mfma_f32_16x16x32_bf16 v[100:103], v[176:179], v[200:203], v[100:103]
	v_mfma_f32_16x16x32_bf16 v[96:99], v[184:187], v[200:203], v[96:99]
	v_mfma_f32_16x16x32_bf16 v[84:87], v[176:179], v[208:211], v[84:87]
	v_mfma_f32_16x16x32_bf16 v[80:83], v[184:187], v[208:211], v[80:83]
	v_mfma_f32_16x16x32_bf16 v[68:71], v[176:179], v[216:219], v[68:71]
	v_mfma_f32_16x16x32_bf16 v[64:67], v[184:187], v[216:219], v[64:67]
	v_mfma_f32_16x16x32_bf16 v[116:119], v[180:183], v[196:199], v[116:119]
	v_mfma_f32_16x16x32_bf16 v[112:115], v[188:191], v[196:199], v[112:115]
	v_mfma_f32_16x16x32_bf16 v[100:103], v[180:183], v[204:207], v[100:103]
	v_mfma_f32_16x16x32_bf16 v[96:99], v[188:191], v[204:207], v[96:99]
	v_mfma_f32_16x16x32_bf16 v[84:87], v[180:183], v[212:215], v[84:87]
	v_mfma_f32_16x16x32_bf16 v[80:83], v[188:191], v[212:215], v[80:83]
	v_mfma_f32_16x16x32_bf16 v[68:71], v[180:183], v[220:223], v[68:71]
	v_mfma_f32_16x16x32_bf16 v[64:67], v[188:191], v[220:223], v[64:67]
	s_setprio 0
	s_barrier
	s_setprio 2
	s_add_i32 s8, s8, s94
	v_lshl_add_u64 v[156:157], v[156:157], 0, s[20:21]
	s_mov_b32 m0, s8
	ds_read_b128 v[192:195], v165 offset:49152
	ds_read_b128 v[196:199], v165 offset:50176
	ds_read_b128 v[200:203], v165 offset:51200
	ds_read_b128 v[204:207], v165 offset:52224
	ds_read_b128 v[208:211], v165 offset:53248
	ds_read_b128 v[212:215], v165 offset:54272
	ds_read_b128 v[216:219], v165 offset:55296
	ds_read_b128 v[220:223], v165 offset:56320
	global_load_lds_dwordx4 v[156:157], off
	s_add_i32 m0, s8, 0x2000
	s_add_u32 s60, s72, 0x30080
	v_lshl_add_u64 v[156:157], v[224:225], 0, s[20:21]
	s_addc_u32 s61, s73, 0
	s_add_i32 s8, s9, s94
	global_load_lds_dwordx4 v[156:157], off
	v_lshl_add_u64 v[156:157], s[60:61], 0, v[130:131]
	s_mov_b32 m0, s8
	s_nop 0
	global_load_lds_dwordx4 v[156:157], off
	v_lshl_add_u64 v[156:157], s[60:61], 0, v[134:135]
	s_add_i32 m0, s8, 0x2000
	s_nop 0
	global_load_lds_dwordx4 v[156:157], off
	v_lshl_add_u64 v[156:157], v[226:227], 0, s[20:21]
	s_mov_b32 m0, s46
	s_nop 0
	global_load_lds_dwordx4 v[156:157], off
	v_lshl_add_u64 v[156:157], v[228:229], 0, s[20:21]
	s_mov_b32 m0, s56
	s_nop 0
	global_load_lds_dwordx4 v[156:157], off
	s_setprio 0
	s_waitcnt vmcnt(8)
	s_waitcnt lgkmcnt(0)
	s_barrier
	s_setprio 1
	s_waitcnt lgkmcnt(0)
	v_mfma_f32_16x16x32_bf16 v[60:63], v[148:151], v[192:195], v[60:63]
	v_mfma_f32_16x16x32_bf16 v[56:59], v[168:171], v[192:195], v[56:59]
	v_mfma_f32_16x16x32_bf16 v[44:47], v[148:151], v[200:203], v[44:47]
	v_mfma_f32_16x16x32_bf16 v[40:43], v[168:171], v[200:203], v[40:43]
	v_mfma_f32_16x16x32_bf16 v[28:31], v[148:151], v[208:211], v[28:31]
	v_mfma_f32_16x16x32_bf16 v[24:27], v[168:171], v[208:211], v[24:27]
	v_mfma_f32_16x16x32_bf16 v[12:15], v[148:151], v[216:219], v[12:15]
	v_mfma_f32_16x16x32_bf16 v[8:11], v[168:171], v[216:219], v[8:11]
	v_mfma_f32_16x16x32_bf16 v[60:63], v[152:155], v[196:199], v[60:63]
	v_mfma_f32_16x16x32_bf16 v[56:59], v[172:175], v[196:199], v[56:59]
	v_mfma_f32_16x16x32_bf16 v[44:47], v[152:155], v[204:207], v[44:47]
	v_mfma_f32_16x16x32_bf16 v[40:43], v[172:175], v[204:207], v[40:43]
	v_mfma_f32_16x16x32_bf16 v[28:31], v[152:155], v[212:215], v[28:31]
	v_mfma_f32_16x16x32_bf16 v[24:27], v[172:175], v[212:215], v[24:27]
	v_mfma_f32_16x16x32_bf16 v[12:15], v[152:155], v[220:223], v[12:15]
	v_mfma_f32_16x16x32_bf16 v[8:11], v[172:175], v[220:223], v[8:11]
	v_mfma_f32_16x16x32_bf16 v[52:55], v[176:179], v[192:195], v[52:55]
	v_mfma_f32_16x16x32_bf16 v[48:51], v[184:187], v[192:195], v[48:51]
	v_mfma_f32_16x16x32_bf16 v[36:39], v[176:179], v[200:203], v[36:39]
	v_mfma_f32_16x16x32_bf16 v[32:35], v[184:187], v[200:203], v[32:35]
	v_mfma_f32_16x16x32_bf16 v[20:23], v[176:179], v[208:211], v[20:23]
	v_mfma_f32_16x16x32_bf16 v[16:19], v[184:187], v[208:211], v[16:19]
	v_mfma_f32_16x16x32_bf16 v[4:7], v[176:179], v[216:219], v[4:7]
	v_mfma_f32_16x16x32_bf16 v[0:3], v[184:187], v[216:219], v[0:3]
	v_mfma_f32_16x16x32_bf16 v[52:55], v[180:183], v[196:199], v[52:55]
	v_mfma_f32_16x16x32_bf16 v[48:51], v[188:191], v[196:199], v[48:51]
	v_mfma_f32_16x16x32_bf16 v[36:39], v[180:183], v[204:207], v[36:39]
	v_mfma_f32_16x16x32_bf16 v[32:35], v[188:191], v[204:207], v[32:35]
	v_mfma_f32_16x16x32_bf16 v[20:23], v[180:183], v[212:215], v[20:23]
	v_mfma_f32_16x16x32_bf16 v[16:19], v[188:191], v[212:215], v[16:19]
	v_mfma_f32_16x16x32_bf16 v[4:7], v[180:183], v[220:223], v[4:7]
	v_mfma_f32_16x16x32_bf16 v[0:3], v[188:191], v[220:223], v[0:3]
	s_setprio 0
	s_barrier
	s_setprio 2
	s_add_i32 s86, s86, 2
	s_add_u32 s84, s84, 0x100
	s_addc_u32 s85, s85, 0
	s_cmp_gt_u32 s86, 9
	s_mov_b64 s[70:71], s[16:17]
	s_cbranch_scc0 .LBB0_2459
	s_setprio 0
	s_and_b64 vcc, exec, s[58:59]
	s_cbranch_vccz .LBB0_2462
	s_barrier

.LBB0_2535:
	ds_read_b128 v[146:149], v155
	ds_read_b128 v[160:163], v155 offset:1024
	ds_read_b128 v[164:167], v155 offset:2048
	ds_read_b128 v[168:171], v155 offset:3072
	ds_read_b128 v[172:175], v156
	ds_read_b128 v[176:179], v156 offset:1024
	ds_read_b128 v[180:183], v156 offset:2048
	ds_read_b128 v[184:187], v156 offset:3072
	s_add_u32 s16, s68, 0x100
	s_addc_u32 s17, s69, 0
	s_cmp_eq_u32 s80, 4
	s_cselect_b32 s73, s49, s17
	s_cselect_b32 s72, s48, s16
	s_cselect_b32 s71, s43, s79
	s_cselect_b32 s70, s77, s78
	v_lshl_add_u64 v[220:221], s[68:69], 0, v[138:139]
	s_add_i32 m0, s29, 0xc000
	ds_read_b128 v[188:191], v157
	ds_read_b128 v[192:195], v157 offset:1024
	ds_read_b128 v[196:199], v157 offset:2048
	ds_read_b128 v[200:203], v157 offset:3072
	ds_read_b128 v[204:207], v157 offset:4096
	ds_read_b128 v[208:211], v157 offset:5120
	ds_read_b128 v[212:215], v157 offset:6144
	ds_read_b128 v[216:219], v157 offset:7168
	global_load_lds_dwordx4 v[220:221], off
	v_lshl_add_u64 v[220:221], s[68:69], 0, v[140:141]
	s_add_i32 m0, s29, 0xe000
	s_nop 0
	global_load_lds_dwordx4 v[220:221], off
	s_waitcnt vmcnt(8)
	s_waitcnt lgkmcnt(0)
	s_barrier
	s_setprio 1
	s_waitcnt lgkmcnt(0)
	v_mfma_f32_16x16x32_bf16 v[124:127], v[146:149], v[188:191], v[124:127]
	v_mfma_f32_16x16x32_bf16 v[120:123], v[164:167], v[188:191], v[120:123]
	v_mfma_f32_16x16x32_bf16 v[108:111], v[146:149], v[196:199], v[108:111]
	v_mfma_f32_16x16x32_bf16 v[104:107], v[164:167], v[196:199], v[104:107]
	v_mfma_f32_16x16x32_bf16 v[92:95], v[146:149], v[204:207], v[92:95]
	v_mfma_f32_16x16x32_bf16 v[88:91], v[164:167], v[204:207], v[88:91]
	v_mfma_f32_16x16x32_bf16 v[76:79], v[146:149], v[212:215], v[76:79]
	v_mfma_f32_16x16x32_bf16 v[72:75], v[164:167], v[212:215], v[72:75]
	v_mfma_f32_16x16x32_bf16 v[124:127], v[160:163], v[192:195], v[124:127]
	v_mfma_f32_16x16x32_bf16 v[120:123], v[168:171], v[192:195], v[120:123]
	v_mfma_f32_16x16x32_bf16 v[108:111], v[160:163], v[200:203], v[108:111]
	v_mfma_f32_16x16x32_bf16 v[104:107], v[168:171], v[200:203], v[104:107]
	v_mfma_f32_16x16x32_bf16 v[92:95], v[160:163], v[208:211], v[92:95]
	v_mfma_f32_16x16x32_bf16 v[88:91], v[168:171], v[208:211], v[88:91]
	v_mfma_f32_16x16x32_bf16 v[76:79], v[160:163], v[216:219], v[76:79]
	v_mfma_f32_16x16x32_bf16 v[72:75], v[168:171], v[216:219], v[72:75]
	v_mfma_f32_16x16x32_bf16 v[116:119], v[172:175], v[188:191], v[116:119]
	v_mfma_f32_16x16x32_bf16 v[112:115], v[180:183], v[188:191], v[112:115]
	v_mfma_f32_16x16x32_bf16 v[100:103], v[172:175], v[196:199], v[100:103]
	v_mfma_f32_16x16x32_bf16 v[96:99], v[180:183], v[196:199], v[96:99]
	v_mfma_f32_16x16x32_bf16 v[84:87], v[172:175], v[204:207], v[84:87]
	v_mfma_f32_16x16x32_bf16 v[80:83], v[180:183], v[204:207], v[80:83]
	v_mfma_f32_16x16x32_bf16 v[68:71], v[172:175], v[212:215], v[68:71]
	v_mfma_f32_16x16x32_bf16 v[64:67], v[180:183], v[212:215], v[64:67]
	v_mfma_f32_16x16x32_bf16 v[116:119], v[176:179], v[192:195], v[116:119]
	v_mfma_f32_16x16x32_bf16 v[112:115], v[184:187], v[192:195], v[112:115]
	v_mfma_f32_16x16x32_bf16 v[100:103], v[176:179], v[200:203], v[100:103]
	v_mfma_f32_16x16x32_bf16 v[96:99], v[184:187], v[200:203], v[96:99]
	v_mfma_f32_16x16x32_bf16 v[84:87], v[176:179], v[208:211], v[84:87]
	v_mfma_f32_16x16x32_bf16 v[80:83], v[184:187], v[208:211], v[80:83]
	v_mfma_f32_16x16x32_bf16 v[68:71], v[176:179], v[216:219], v[68:71]
	v_mfma_f32_16x16x32_bf16 v[64:67], v[184:187], v[216:219], v[64:67]
	s_setprio 0
	s_barrier
	s_setprio 2
	s_add_i32 s8, s67, s94
	v_lshl_add_u64 v[220:221], s[70:71], 0, v[130:131]
	s_mov_b32 m0, s8
	ds_read_b128 v[188:191], v157 offset:16384
	ds_read_b128 v[192:195], v157 offset:17408
	ds_read_b128 v[196:199], v157 offset:18432
	ds_read_b128 v[200:203], v157 offset:19456
	ds_read_b128 v[204:207], v157 offset:20480
	ds_read_b128 v[208:211], v157 offset:21504
	ds_read_b128 v[212:215], v157 offset:22528
	ds_read_b128 v[216:219], v157 offset:23552
	global_load_lds_dwordx4 v[220:221], off
	s_add_i32 m0, s8, 0x2000
	s_add_u32 s60, s70, 0x20000
	v_lshl_add_u64 v[222:223], s[70:71], 0, v[134:135]
	s_addc_u32 s61, s71, 0
	s_add_i32 s8, s74, s94
	global_load_lds_dwordx4 v[222:223], off
	v_lshl_add_u64 v[224:225], s[60:61], 0, v[130:131]
	s_mov_b32 m0, s8
	v_lshl_add_u64 v[226:227], s[72:73], 0, v[132:133]
	global_load_lds_dwordx4 v[224:225], off
	v_lshl_add_u64 v[224:225], s[60:61], 0, v[134:135]
	s_add_i32 m0, s8, 0x2000
	s_nop 0
	global_load_lds_dwordx4 v[224:225], off
	v_lshl_add_u64 v[224:225], s[72:73], 0, v[128:129]
	s_mov_b32 m0, s29
	s_nop 0
	global_load_lds_dwordx4 v[224:225], off
	s_mov_b32 m0, s30
	s_nop 0
	global_load_lds_dwordx4 v[226:227], off
	s_setprio 0
	s_waitcnt vmcnt(8)
	s_waitcnt lgkmcnt(0)
	s_barrier
	s_setprio 1
	s_waitcnt lgkmcnt(0)
	v_mfma_f32_16x16x32_bf16 v[60:63], v[146:149], v[188:191], v[60:63]
	v_mfma_f32_16x16x32_bf16 v[56:59], v[164:167], v[188:191], v[56:59]
	v_mfma_f32_16x16x32_bf16 v[44:47], v[146:149], v[196:199], v[44:47]
	v_mfma_f32_16x16x32_bf16 v[40:43], v[164:167], v[196:199], v[40:43]
	v_mfma_f32_16x16x32_bf16 v[28:31], v[146:149], v[204:207], v[28:31]
	v_mfma_f32_16x16x32_bf16 v[24:27], v[164:167], v[204:207], v[24:27]
	v_mfma_f32_16x16x32_bf16 v[12:15], v[146:149], v[212:215], v[12:15]
	v_mfma_f32_16x16x32_bf16 v[8:11], v[164:167], v[212:215], v[8:11]
	v_mfma_f32_16x16x32_bf16 v[60:63], v[160:163], v[192:195], v[60:63]
	v_mfma_f32_16x16x32_bf16 v[56:59], v[168:171], v[192:195], v[56:59]
	v_mfma_f32_16x16x32_bf16 v[44:47], v[160:163], v[200:203], v[44:47]
	v_mfma_f32_16x16x32_bf16 v[40:43], v[168:171], v[200:203], v[40:43]
	v_mfma_f32_16x16x32_bf16 v[28:31], v[160:163], v[208:211], v[28:31]
	v_mfma_f32_16x16x32_bf16 v[24:27], v[168:171], v[208:211], v[24:27]
	v_mfma_f32_16x16x32_bf16 v[12:15], v[160:163], v[216:219], v[12:15]
	v_mfma_f32_16x16x32_bf16 v[8:11], v[168:171], v[216:219], v[8:11]
	v_mfma_f32_16x16x32_bf16 v[52:55], v[172:175], v[188:191], v[52:55]
	v_mfma_f32_16x16x32_bf16 v[48:51], v[180:183], v[188:191], v[48:51]
	v_mfma_f32_16x16x32_bf16 v[36:39], v[172:175], v[196:199], v[36:39]
	v_mfma_f32_16x16x32_bf16 v[32:35], v[180:183], v[196:199], v[32:35]
	v_mfma_f32_16x16x32_bf16 v[20:23], v[172:175], v[204:207], v[20:23]
	v_mfma_f32_16x16x32_bf16 v[16:19], v[180:183], v[204:207], v[16:19]
	v_mfma_f32_16x16x32_bf16 v[4:7], v[172:175], v[212:215], v[4:7]
	v_mfma_f32_16x16x32_bf16 v[0:3], v[180:183], v[212:215], v[0:3]
	v_mfma_f32_16x16x32_bf16 v[52:55], v[176:179], v[192:195], v[52:55]
	v_mfma_f32_16x16x32_bf16 v[48:51], v[184:187], v[192:195], v[48:51]
	v_mfma_f32_16x16x32_bf16 v[36:39], v[176:179], v[200:203], v[36:39]
	v_mfma_f32_16x16x32_bf16 v[32:35], v[184:187], v[200:203], v[32:35]
	v_mfma_f32_16x16x32_bf16 v[20:23], v[176:179], v[208:211], v[20:23]
	v_mfma_f32_16x16x32_bf16 v[16:19], v[184:187], v[208:211], v[16:19]
	v_mfma_f32_16x16x32_bf16 v[4:7], v[176:179], v[216:219], v[4:7]
	v_mfma_f32_16x16x32_bf16 v[0:3], v[184:187], v[216:219], v[0:3]
	s_setprio 0
	s_barrier
	s_setprio 2
	s_add_i32 s8, 0, 0x18000
	v_add_u32_e32 v159, s8, v151
	s_add_i32 s9, 0, 0x1c000
	ds_read_b128 v[146:149], v159
	ds_read_b128 v[160:163], v159 offset:1024
	ds_read_b128 v[164:167], v159 offset:2048
	ds_read_b128 v[168:171], v159 offset:3072
	v_add_u32_e32 v159, s9, v151
	ds_read_b128 v[172:175], v159
	ds_read_b128 v[176:179], v159 offset:1024
	ds_read_b128 v[180:183], v159 offset:2048
	ds_read_b128 v[184:187], v159 offset:3072
	s_add_u32 s60, s72, 0x60000
	s_addc_u32 s61, s73, 0
	s_mov_b32 m0, s34
	v_lshl_add_u64 v[228:229], s[60:61], 0, v[128:129]
	ds_read_b128 v[188:191], v157 offset:32768
	ds_read_b128 v[192:195], v157 offset:33792
	ds_read_b128 v[196:199], v157 offset:34816
	ds_read_b128 v[200:203], v157 offset:35840
	ds_read_b128 v[204:207], v157 offset:36864
	ds_read_b128 v[208:211], v157 offset:37888
	ds_read_b128 v[212:215], v157 offset:38912
	ds_read_b128 v[216:219], v157 offset:39936
	global_load_lds_dwordx4 v[228:229], off
	v_lshl_add_u64 v[228:229], s[60:61], 0, v[132:133]
	s_mov_b32 m0, s35
	s_nop 0
	global_load_lds_dwordx4 v[228:229], off
	s_setprio 0
	s_waitcnt vmcnt(8)
	s_waitcnt lgkmcnt(0)
	s_barrier
	s_setprio 1
	s_waitcnt lgkmcnt(0)
	v_mfma_f32_16x16x32_bf16 v[124:127], v[146:149], v[188:191], v[124:127]
	v_mfma_f32_16x16x32_bf16 v[120:123], v[164:167], v[188:191], v[120:123]
	v_mfma_f32_16x16x32_bf16 v[108:111], v[146:149], v[196:199], v[108:111]
	v_mfma_f32_16x16x32_bf16 v[104:107], v[164:167], v[196:199], v[104:107]
	v_mfma_f32_16x16x32_bf16 v[92:95], v[146:149], v[204:207], v[92:95]
	v_mfma_f32_16x16x32_bf16 v[88:91], v[164:167], v[204:207], v[88:91]
	v_mfma_f32_16x16x32_bf16 v[76:79], v[146:149], v[212:215], v[76:79]
	v_mfma_f32_16x16x32_bf16 v[72:75], v[164:167], v[212:215], v[72:75]
	v_mfma_f32_16x16x32_bf16 v[124:127], v[160:163], v[192:195], v[124:127]
	v_mfma_f32_16x16x32_bf16 v[120:123], v[168:171], v[192:195], v[120:123]
	v_mfma_f32_16x16x32_bf16 v[108:111], v[160:163], v[200:203], v[108:111]
	v_mfma_f32_16x16x32_bf16 v[104:107], v[168:171], v[200:203], v[104:107]
	v_mfma_f32_16x16x32_bf16 v[92:95], v[160:163], v[208:211], v[92:95]
	v_mfma_f32_16x16x32_bf16 v[88:91], v[168:171], v[208:211], v[88:91]
	v_mfma_f32_16x16x32_bf16 v[76:79], v[160:163], v[216:219], v[76:79]
	v_mfma_f32_16x16x32_bf16 v[72:75], v[168:171], v[216:219], v[72:75]
	v_mfma_f32_16x16x32_bf16 v[116:119], v[172:175], v[188:191], v[116:119]
	v_mfma_f32_16x16x32_bf16 v[112:115], v[180:183], v[188:191], v[112:115]
	v_mfma_f32_16x16x32_bf16 v[100:103], v[172:175], v[196:199], v[100:103]
	v_mfma_f32_16x16x32_bf16 v[96:99], v[180:183], v[196:199], v[96:99]
	v_mfma_f32_16x16x32_bf16 v[84:87], v[172:175], v[204:207], v[84:87]
	v_mfma_f32_16x16x32_bf16 v[80:83], v[180:183], v[204:207], v[80:83]
	v_mfma_f32_16x16x32_bf16 v[68:71], v[172:175], v[212:215], v[68:71]
	v_mfma_f32_16x16x32_bf16 v[64:67], v[180:183], v[212:215], v[64:67]
	v_mfma_f32_16x16x32_bf16 v[116:119], v[176:179], v[192:195], v[116:119]
	v_mfma_f32_16x16x32_bf16 v[112:115], v[184:187], v[192:195], v[112:115]
	v_mfma_f32_16x16x32_bf16 v[100:103], v[176:179], v[200:203], v[100:103]
	v_mfma_f32_16x16x32_bf16 v[96:99], v[184:187], v[200:203], v[96:99]
	v_mfma_f32_16x16x32_bf16 v[84:87], v[176:179], v[208:211], v[84:87]
	v_mfma_f32_16x16x32_bf16 v[80:83], v[184:187], v[208:211], v[80:83]
	v_mfma_f32_16x16x32_bf16 v[68:71], v[176:179], v[216:219], v[68:71]
	v_mfma_f32_16x16x32_bf16 v[64:67], v[184:187], v[216:219], v[64:67]
	s_setprio 0
	s_barrier
	s_setprio 2
	s_add_i32 s8, s8, s94
	v_lshl_add_u64 v[220:221], v[220:221], 0, s[22:23]
	s_mov_b32 m0, s8
	ds_read_b128 v[188:191], v157 offset:49152
	ds_read_b128 v[192:195], v157 offset:50176
	ds_read_b128 v[196:199], v157 offset:51200
	ds_read_b128 v[200:203], v157 offset:52224
	ds_read_b128 v[204:207], v157 offset:53248
	ds_read_b128 v[208:211], v157 offset:54272
	ds_read_b128 v[212:215], v157 offset:55296
	ds_read_b128 v[216:219], v157 offset:56320
	global_load_lds_dwordx4 v[220:221], off
	s_add_i32 m0, s8, 0x2000
	s_add_u32 s60, s70, 0x20080
	v_lshl_add_u64 v[220:221], v[222:223], 0, s[22:23]
	s_addc_u32 s61, s71, 0
	s_add_i32 s8, s9, s94
	global_load_lds_dwordx4 v[220:221], off
	v_lshl_add_u64 v[220:221], s[60:61], 0, v[130:131]
	s_mov_b32 m0, s8
	s_nop 0
	global_load_lds_dwordx4 v[220:221], off
	v_lshl_add_u64 v[220:221], s[60:61], 0, v[134:135]
	s_add_i32 m0, s8, 0x2000
	s_nop 0
	global_load_lds_dwordx4 v[220:221], off
	v_lshl_add_u64 v[220:221], v[224:225], 0, s[22:23]
	s_mov_b32 m0, s56
	s_nop 0
	global_load_lds_dwordx4 v[220:221], off
	v_lshl_add_u64 v[220:221], v[226:227], 0, s[22:23]
	s_mov_b32 m0, s57
	s_nop 0
	global_load_lds_dwordx4 v[220:221], off
	s_setprio 0
	s_waitcnt vmcnt(8)
	s_waitcnt lgkmcnt(0)
	s_barrier
	s_setprio 1
	s_waitcnt lgkmcnt(0)
	v_mfma_f32_16x16x32_bf16 v[60:63], v[146:149], v[188:191], v[60:63]
	v_mfma_f32_16x16x32_bf16 v[56:59], v[164:167], v[188:191], v[56:59]
	v_mfma_f32_16x16x32_bf16 v[44:47], v[146:149], v[196:199], v[44:47]
	v_mfma_f32_16x16x32_bf16 v[40:43], v[164:167], v[196:199], v[40:43]
	v_mfma_f32_16x16x32_bf16 v[28:31], v[146:149], v[204:207], v[28:31]
	v_mfma_f32_16x16x32_bf16 v[24:27], v[164:167], v[204:207], v[24:27]
	v_mfma_f32_16x16x32_bf16 v[12:15], v[146:149], v[212:215], v[12:15]
	v_mfma_f32_16x16x32_bf16 v[8:11], v[164:167], v[212:215], v[8:11]
	v_mfma_f32_16x16x32_bf16 v[60:63], v[160:163], v[192:195], v[60:63]
	v_mfma_f32_16x16x32_bf16 v[56:59], v[168:171], v[192:195], v[56:59]
	v_mfma_f32_16x16x32_bf16 v[44:47], v[160:163], v[200:203], v[44:47]
	v_mfma_f32_16x16x32_bf16 v[40:43], v[168:171], v[200:203], v[40:43]
	v_mfma_f32_16x16x32_bf16 v[28:31], v[160:163], v[208:211], v[28:31]
	v_mfma_f32_16x16x32_bf16 v[24:27], v[168:171], v[208:211], v[24:27]
	v_mfma_f32_16x16x32_bf16 v[12:15], v[160:163], v[216:219], v[12:15]
	v_mfma_f32_16x16x32_bf16 v[8:11], v[168:171], v[216:219], v[8:11]
	v_mfma_f32_16x16x32_bf16 v[52:55], v[172:175], v[188:191], v[52:55]
	v_mfma_f32_16x16x32_bf16 v[48:51], v[180:183], v[188:191], v[48:51]
	v_mfma_f32_16x16x32_bf16 v[36:39], v[172:175], v[196:199], v[36:39]
	v_mfma_f32_16x16x32_bf16 v[32:35], v[180:183], v[196:199], v[32:35]
	v_mfma_f32_16x16x32_bf16 v[20:23], v[172:175], v[204:207], v[20:23]
	v_mfma_f32_16x16x32_bf16 v[16:19], v[180:183], v[204:207], v[16:19]
	v_mfma_f32_16x16x32_bf16 v[4:7], v[172:175], v[212:215], v[4:7]
	v_mfma_f32_16x16x32_bf16 v[0:3], v[180:183], v[212:215], v[0:3]
	v_mfma_f32_16x16x32_bf16 v[52:55], v[176:179], v[192:195], v[52:55]
	v_mfma_f32_16x16x32_bf16 v[48:51], v[184:187], v[192:195], v[48:51]
	v_mfma_f32_16x16x32_bf16 v[36:39], v[176:179], v[200:203], v[36:39]
	v_mfma_f32_16x16x32_bf16 v[32:35], v[184:187], v[200:203], v[32:35]
	v_mfma_f32_16x16x32_bf16 v[20:23], v[176:179], v[208:211], v[20:23]
	v_mfma_f32_16x16x32_bf16 v[16:19], v[184:187], v[208:211], v[16:19]
	v_mfma_f32_16x16x32_bf16 v[4:7], v[176:179], v[216:219], v[4:7]
	v_mfma_f32_16x16x32_bf16 v[0:3], v[184:187], v[216:219], v[0:3]
	s_setprio 0
	s_barrier
	s_setprio 2
	s_add_i32 s80, s80, 2
	s_add_u32 s78, s78, 0x100
	s_addc_u32 s79, s79, 0
	s_cmp_gt_u32 s80, 5
	s_mov_b64 s[68:69], s[16:17]
	s_cbranch_scc0 .LBB0_2535
	s_setprio 0
	s_and_b64 vcc, exec, s[58:59]
	s_cbranch_vccz .LBB0_2538
	s_barrier

.LBB0_2713:
	ds_read_b128 v[140:143], v149
	ds_read_b128 v[152:155], v149 offset:1024
	ds_read_b128 v[156:159], v149 offset:2048
	ds_read_b128 v[160:163], v149 offset:3072
	ds_read_b128 v[164:167], v150
	ds_read_b128 v[168:171], v150 offset:1024
	ds_read_b128 v[172:175], v150 offset:2048
	ds_read_b128 v[176:179], v150 offset:3072
	s_add_u32 s8, s62, 0xfff80080
	s_addc_u32 s9, s63, -1
	s_cmp_eq_u32 s72, 28
	s_cselect_b32 s67, s43, s9
	s_cselect_b32 s66, s57, s8
	s_cselect_b32 s65, s23, s71
	s_cselect_b32 s64, s69, s70
	v_lshl_add_u64 v[212:213], s[62:63], 0, v[132:133]
	s_add_i32 m0, s12, 0xc000
	ds_read_b128 v[180:183], v151
	ds_read_b128 v[184:187], v151 offset:1024
	ds_read_b128 v[188:191], v151 offset:2048
	ds_read_b128 v[192:195], v151 offset:3072
	ds_read_b128 v[196:199], v151 offset:4096
	ds_read_b128 v[200:203], v151 offset:5120
	ds_read_b128 v[204:207], v151 offset:6144
	ds_read_b128 v[208:211], v151 offset:7168
	global_load_lds_dwordx4 v[212:213], off
	v_lshl_add_u64 v[212:213], s[62:63], 0, v[134:135]
	s_add_i32 m0, s12, 0xe000
	s_nop 0
	global_load_lds_dwordx4 v[212:213], off
	s_waitcnt vmcnt(8)
	s_waitcnt lgkmcnt(0)
	s_barrier
	s_setprio 1
	s_waitcnt lgkmcnt(0)
	v_mfma_f32_16x16x32_bf16 v[124:127], v[140:143], v[180:183], v[124:127]
	v_mfma_f32_16x16x32_bf16 v[120:123], v[156:159], v[180:183], v[120:123]
	v_mfma_f32_16x16x32_bf16 v[108:111], v[140:143], v[188:191], v[108:111]
	v_mfma_f32_16x16x32_bf16 v[104:107], v[156:159], v[188:191], v[104:107]
	v_mfma_f32_16x16x32_bf16 v[92:95], v[140:143], v[196:199], v[92:95]
	v_mfma_f32_16x16x32_bf16 v[88:91], v[156:159], v[196:199], v[88:91]
	v_mfma_f32_16x16x32_bf16 v[76:79], v[140:143], v[204:207], v[76:79]
	v_mfma_f32_16x16x32_bf16 v[72:75], v[156:159], v[204:207], v[72:75]
	v_mfma_f32_16x16x32_bf16 v[124:127], v[152:155], v[184:187], v[124:127]
	v_mfma_f32_16x16x32_bf16 v[120:123], v[160:163], v[184:187], v[120:123]
	v_mfma_f32_16x16x32_bf16 v[108:111], v[152:155], v[192:195], v[108:111]
	v_mfma_f32_16x16x32_bf16 v[104:107], v[160:163], v[192:195], v[104:107]
	v_mfma_f32_16x16x32_bf16 v[92:95], v[152:155], v[200:203], v[92:95]
	v_mfma_f32_16x16x32_bf16 v[88:91], v[160:163], v[200:203], v[88:91]
	v_mfma_f32_16x16x32_bf16 v[76:79], v[152:155], v[208:211], v[76:79]
	v_mfma_f32_16x16x32_bf16 v[72:75], v[160:163], v[208:211], v[72:75]
	v_mfma_f32_16x16x32_bf16 v[116:119], v[164:167], v[180:183], v[116:119]
	v_mfma_f32_16x16x32_bf16 v[112:115], v[172:175], v[180:183], v[112:115]
	v_mfma_f32_16x16x32_bf16 v[100:103], v[164:167], v[188:191], v[100:103]
	v_mfma_f32_16x16x32_bf16 v[96:99], v[172:175], v[188:191], v[96:99]
	v_mfma_f32_16x16x32_bf16 v[84:87], v[164:167], v[196:199], v[84:87]
	v_mfma_f32_16x16x32_bf16 v[80:83], v[172:175], v[196:199], v[80:83]
	v_mfma_f32_16x16x32_bf16 v[68:71], v[164:167], v[204:207], v[68:71]
	v_mfma_f32_16x16x32_bf16 v[64:67], v[172:175], v[204:207], v[64:67]
	v_mfma_f32_16x16x32_bf16 v[116:119], v[168:171], v[184:187], v[116:119]
	v_mfma_f32_16x16x32_bf16 v[112:115], v[176:179], v[184:187], v[112:115]
	v_mfma_f32_16x16x32_bf16 v[100:103], v[168:171], v[192:195], v[100:103]
	v_mfma_f32_16x16x32_bf16 v[96:99], v[176:179], v[192:195], v[96:99]
	v_mfma_f32_16x16x32_bf16 v[84:87], v[168:171], v[200:203], v[84:87]
	v_mfma_f32_16x16x32_bf16 v[80:83], v[176:179], v[200:203], v[80:83]
	v_mfma_f32_16x16x32_bf16 v[68:71], v[168:171], v[208:211], v[68:71]
	v_mfma_f32_16x16x32_bf16 v[64:67], v[176:179], v[208:211], v[64:67]
	s_setprio 0
	s_barrier
	s_setprio 2
	s_add_i32 s8, s46, s94
	v_lshl_add_u64 v[212:213], s[64:65], 0, v[128:129]
	s_mov_b32 m0, s8
	ds_read_b128 v[180:183], v151 offset:16384
	ds_read_b128 v[184:187], v151 offset:17408
	ds_read_b128 v[188:191], v151 offset:18432
	ds_read_b128 v[192:195], v151 offset:19456
	ds_read_b128 v[196:199], v151 offset:20480
	ds_read_b128 v[200:203], v151 offset:21504
	ds_read_b128 v[204:207], v151 offset:22528
	ds_read_b128 v[208:211], v151 offset:23552
	global_load_lds_dwordx4 v[212:213], off
	s_add_i32 m0, s8, 0x2000
	s_add_u32 s60, s64, 0x80000
	v_lshl_add_u64 v[214:215], s[64:65], 0, v[130:131]
	s_addc_u32 s61, s65, 0
	s_add_i32 s8, s47, s94
	global_load_lds_dwordx4 v[214:215], off
	v_lshl_add_u64 v[216:217], s[60:61], 0, v[128:129]
	s_mov_b32 m0, s8
	v_lshl_add_u64 v[218:219], s[66:67], 0, v[130:131]
	global_load_lds_dwordx4 v[216:217], off
	v_lshl_add_u64 v[216:217], s[60:61], 0, v[130:131]
	s_add_i32 m0, s8, 0x2000
	s_nop 0
	global_load_lds_dwordx4 v[216:217], off
	v_lshl_add_u64 v[216:217], s[66:67], 0, v[128:129]
	s_mov_b32 m0, s12
	s_nop 0
	global_load_lds_dwordx4 v[216:217], off
	s_mov_b32 m0, s13
	s_nop 0
	global_load_lds_dwordx4 v[218:219], off
	s_setprio 0
	s_waitcnt vmcnt(8)
	s_waitcnt lgkmcnt(0)
	s_barrier
	s_setprio 1
	s_waitcnt lgkmcnt(0)
	v_mfma_f32_16x16x32_bf16 v[60:63], v[140:143], v[180:183], v[60:63]
	v_mfma_f32_16x16x32_bf16 v[56:59], v[156:159], v[180:183], v[56:59]
	v_mfma_f32_16x16x32_bf16 v[44:47], v[140:143], v[188:191], v[44:47]
	v_mfma_f32_16x16x32_bf16 v[40:43], v[156:159], v[188:191], v[40:43]
	v_mfma_f32_16x16x32_bf16 v[28:31], v[140:143], v[196:199], v[28:31]
	v_mfma_f32_16x16x32_bf16 v[24:27], v[156:159], v[196:199], v[24:27]
	v_mfma_f32_16x16x32_bf16 v[12:15], v[140:143], v[204:207], v[12:15]
	v_mfma_f32_16x16x32_bf16 v[8:11], v[156:159], v[204:207], v[8:11]
	v_mfma_f32_16x16x32_bf16 v[60:63], v[152:155], v[184:187], v[60:63]
	v_mfma_f32_16x16x32_bf16 v[56:59], v[160:163], v[184:187], v[56:59]
	v_mfma_f32_16x16x32_bf16 v[44:47], v[152:155], v[192:195], v[44:47]
	v_mfma_f32_16x16x32_bf16 v[40:43], v[160:163], v[192:195], v[40:43]
	v_mfma_f32_16x16x32_bf16 v[28:31], v[152:155], v[200:203], v[28:31]
	v_mfma_f32_16x16x32_bf16 v[24:27], v[160:163], v[200:203], v[24:27]
	v_mfma_f32_16x16x32_bf16 v[12:15], v[152:155], v[208:211], v[12:15]
	v_mfma_f32_16x16x32_bf16 v[8:11], v[160:163], v[208:211], v[8:11]
	v_mfma_f32_16x16x32_bf16 v[52:55], v[164:167], v[180:183], v[52:55]
	v_mfma_f32_16x16x32_bf16 v[48:51], v[172:175], v[180:183], v[48:51]
	v_mfma_f32_16x16x32_bf16 v[36:39], v[164:167], v[188:191], v[36:39]
	v_mfma_f32_16x16x32_bf16 v[32:35], v[172:175], v[188:191], v[32:35]
	v_mfma_f32_16x16x32_bf16 v[20:23], v[164:167], v[196:199], v[20:23]
	v_mfma_f32_16x16x32_bf16 v[16:19], v[172:175], v[196:199], v[16:19]
	v_mfma_f32_16x16x32_bf16 v[4:7], v[164:167], v[204:207], v[4:7]
	v_mfma_f32_16x16x32_bf16 v[0:3], v[172:175], v[204:207], v[0:3]
	v_mfma_f32_16x16x32_bf16 v[52:55], v[168:171], v[184:187], v[52:55]
	v_mfma_f32_16x16x32_bf16 v[48:51], v[176:179], v[184:187], v[48:51]
	v_mfma_f32_16x16x32_bf16 v[36:39], v[168:171], v[192:195], v[36:39]
	v_mfma_f32_16x16x32_bf16 v[32:35], v[176:179], v[192:195], v[32:35]
	v_mfma_f32_16x16x32_bf16 v[20:23], v[168:171], v[200:203], v[20:23]
	v_mfma_f32_16x16x32_bf16 v[16:19], v[176:179], v[200:203], v[16:19]
	v_mfma_f32_16x16x32_bf16 v[4:7], v[168:171], v[208:211], v[4:7]
	v_mfma_f32_16x16x32_bf16 v[0:3], v[176:179], v[208:211], v[0:3]
	s_setprio 0
	s_barrier
	s_setprio 2
	s_add_i32 s8, 0, 0x18000
	s_add_i32 s9, 0, 0x1c000
	v_add_u32_e32 v160, s8, v145
	v_add_u32_e32 v176, s9, v145
	ds_read_b128 v[140:143], v160
	ds_read_b128 v[152:155], v160 offset:1024
	ds_read_b128 v[156:159], v160 offset:2048
	ds_read_b128 v[160:163], v160 offset:3072
	ds_read_b128 v[164:167], v176
	ds_read_b128 v[168:171], v176 offset:1024
	ds_read_b128 v[172:175], v176 offset:2048
	ds_read_b128 v[176:179], v176 offset:3072
	s_add_u32 s60, s66, 0x80000
	s_addc_u32 s61, s67, 0
	s_mov_b32 m0, s29
	v_lshl_add_u64 v[220:221], s[60:61], 0, v[128:129]
	ds_read_b128 v[180:183], v151 offset:32768
	ds_read_b128 v[184:187], v151 offset:33792
	ds_read_b128 v[188:191], v151 offset:34816
	ds_read_b128 v[192:195], v151 offset:35840
	ds_read_b128 v[196:199], v151 offset:36864
	ds_read_b128 v[200:203], v151 offset:37888
	ds_read_b128 v[204:207], v151 offset:38912
	ds_read_b128 v[208:211], v151 offset:39936
	global_load_lds_dwordx4 v[220:221], off
	v_lshl_add_u64 v[220:221], s[60:61], 0, v[130:131]
	s_mov_b32 m0, s30
	s_nop 0
	global_load_lds_dwordx4 v[220:221], off
	s_setprio 0
	s_waitcnt vmcnt(8)
	s_waitcnt lgkmcnt(0)
	s_barrier
	s_setprio 1
	s_waitcnt lgkmcnt(0)
	v_mfma_f32_16x16x32_bf16 v[124:127], v[140:143], v[180:183], v[124:127]
	v_mfma_f32_16x16x32_bf16 v[120:123], v[156:159], v[180:183], v[120:123]
	v_mfma_f32_16x16x32_bf16 v[108:111], v[140:143], v[188:191], v[108:111]
	v_mfma_f32_16x16x32_bf16 v[104:107], v[156:159], v[188:191], v[104:107]
	v_mfma_f32_16x16x32_bf16 v[92:95], v[140:143], v[196:199], v[92:95]
	v_mfma_f32_16x16x32_bf16 v[88:91], v[156:159], v[196:199], v[88:91]
	v_mfma_f32_16x16x32_bf16 v[76:79], v[140:143], v[204:207], v[76:79]
	v_mfma_f32_16x16x32_bf16 v[72:75], v[156:159], v[204:207], v[72:75]
	v_mfma_f32_16x16x32_bf16 v[124:127], v[152:155], v[184:187], v[124:127]
	v_mfma_f32_16x16x32_bf16 v[120:123], v[160:163], v[184:187], v[120:123]
	v_mfma_f32_16x16x32_bf16 v[108:111], v[152:155], v[192:195], v[108:111]
	v_mfma_f32_16x16x32_bf16 v[104:107], v[160:163], v[192:195], v[104:107]
	v_mfma_f32_16x16x32_bf16 v[92:95], v[152:155], v[200:203], v[92:95]
	v_mfma_f32_16x16x32_bf16 v[88:91], v[160:163], v[200:203], v[88:91]
	v_mfma_f32_16x16x32_bf16 v[76:79], v[152:155], v[208:211], v[76:79]
	v_mfma_f32_16x16x32_bf16 v[72:75], v[160:163], v[208:211], v[72:75]
	v_mfma_f32_16x16x32_bf16 v[116:119], v[164:167], v[180:183], v[116:119]
	v_mfma_f32_16x16x32_bf16 v[112:115], v[172:175], v[180:183], v[112:115]
	v_mfma_f32_16x16x32_bf16 v[100:103], v[164:167], v[188:191], v[100:103]
	v_mfma_f32_16x16x32_bf16 v[96:99], v[172:175], v[188:191], v[96:99]
	v_mfma_f32_16x16x32_bf16 v[84:87], v[164:167], v[196:199], v[84:87]
	v_mfma_f32_16x16x32_bf16 v[80:83], v[172:175], v[196:199], v[80:83]
	v_mfma_f32_16x16x32_bf16 v[68:71], v[164:167], v[204:207], v[68:71]
	v_mfma_f32_16x16x32_bf16 v[64:67], v[172:175], v[204:207], v[64:67]
	v_mfma_f32_16x16x32_bf16 v[116:119], v[168:171], v[184:187], v[116:119]
	v_mfma_f32_16x16x32_bf16 v[112:115], v[176:179], v[184:187], v[112:115]
	v_mfma_f32_16x16x32_bf16 v[100:103], v[168:171], v[192:195], v[100:103]
	v_mfma_f32_16x16x32_bf16 v[96:99], v[176:179], v[192:195], v[96:99]
	v_mfma_f32_16x16x32_bf16 v[84:87], v[168:171], v[200:203], v[84:87]
	v_mfma_f32_16x16x32_bf16 v[80:83], v[176:179], v[200:203], v[80:83]
	v_mfma_f32_16x16x32_bf16 v[68:71], v[168:171], v[208:211], v[68:71]
	v_mfma_f32_16x16x32_bf16 v[64:67], v[176:179], v[208:211], v[64:67]
	s_setprio 0
	s_barrier
	s_setprio 2
	s_add_i32 s8, s8, s94
	v_lshl_add_u64 v[212:213], v[212:213], 0, s[20:21]
	s_mov_b32 m0, s8
	ds_read_b128 v[180:183], v151 offset:49152
	ds_read_b128 v[184:187], v151 offset:50176
	ds_read_b128 v[188:191], v151 offset:51200
	ds_read_b128 v[192:195], v151 offset:52224
	ds_read_b128 v[196:199], v151 offset:53248
	ds_read_b128 v[200:203], v151 offset:54272
	ds_read_b128 v[204:207], v151 offset:55296
	ds_read_b128 v[208:211], v151 offset:56320
	global_load_lds_dwordx4 v[212:213], off
	s_add_i32 m0, s8, 0x2000
	s_add_u32 s60, s64, 0x80080
	v_lshl_add_u64 v[212:213], v[214:215], 0, s[20:21]
	s_addc_u32 s61, s65, 0
	s_add_i32 s8, s9, s94
	global_load_lds_dwordx4 v[212:213], off
	v_lshl_add_u64 v[212:213], s[60:61], 0, v[128:129]
	s_mov_b32 m0, s8
	s_nop 0
	global_load_lds_dwordx4 v[212:213], off
	v_lshl_add_u64 v[212:213], s[60:61], 0, v[130:131]
	s_add_i32 m0, s8, 0x2000
	s_nop 0
	global_load_lds_dwordx4 v[212:213], off
	v_lshl_add_u64 v[212:213], v[216:217], 0, s[20:21]
	s_mov_b32 m0, s34
	s_nop 0
	global_load_lds_dwordx4 v[212:213], off
	v_lshl_add_u64 v[212:213], v[218:219], 0, s[20:21]
	s_mov_b32 m0, s35
	s_nop 0
	global_load_lds_dwordx4 v[212:213], off
	s_setprio 0
	s_waitcnt vmcnt(8)
	s_waitcnt lgkmcnt(0)
	s_barrier
	s_setprio 1
	s_waitcnt lgkmcnt(0)
	v_mfma_f32_16x16x32_bf16 v[60:63], v[140:143], v[180:183], v[60:63]
	v_mfma_f32_16x16x32_bf16 v[56:59], v[156:159], v[180:183], v[56:59]
	v_mfma_f32_16x16x32_bf16 v[44:47], v[140:143], v[188:191], v[44:47]
	v_mfma_f32_16x16x32_bf16 v[40:43], v[156:159], v[188:191], v[40:43]
	v_mfma_f32_16x16x32_bf16 v[28:31], v[140:143], v[196:199], v[28:31]
	v_mfma_f32_16x16x32_bf16 v[24:27], v[156:159], v[196:199], v[24:27]
	v_mfma_f32_16x16x32_bf16 v[12:15], v[140:143], v[204:207], v[12:15]
	v_mfma_f32_16x16x32_bf16 v[8:11], v[156:159], v[204:207], v[8:11]
	v_mfma_f32_16x16x32_bf16 v[60:63], v[152:155], v[184:187], v[60:63]
	v_mfma_f32_16x16x32_bf16 v[56:59], v[160:163], v[184:187], v[56:59]
	v_mfma_f32_16x16x32_bf16 v[44:47], v[152:155], v[192:195], v[44:47]
	v_mfma_f32_16x16x32_bf16 v[40:43], v[160:163], v[192:195], v[40:43]
	v_mfma_f32_16x16x32_bf16 v[28:31], v[152:155], v[200:203], v[28:31]
	v_mfma_f32_16x16x32_bf16 v[24:27], v[160:163], v[200:203], v[24:27]
	v_mfma_f32_16x16x32_bf16 v[12:15], v[152:155], v[208:211], v[12:15]
	v_mfma_f32_16x16x32_bf16 v[8:11], v[160:163], v[208:211], v[8:11]
	v_mfma_f32_16x16x32_bf16 v[52:55], v[164:167], v[180:183], v[52:55]
	v_mfma_f32_16x16x32_bf16 v[48:51], v[172:175], v[180:183], v[48:51]
	v_mfma_f32_16x16x32_bf16 v[36:39], v[164:167], v[188:191], v[36:39]
	v_mfma_f32_16x16x32_bf16 v[32:35], v[172:175], v[188:191], v[32:35]
	v_mfma_f32_16x16x32_bf16 v[20:23], v[164:167], v[196:199], v[20:23]
	v_mfma_f32_16x16x32_bf16 v[16:19], v[172:175], v[196:199], v[16:19]
	v_mfma_f32_16x16x32_bf16 v[4:7], v[164:167], v[204:207], v[4:7]
	v_mfma_f32_16x16x32_bf16 v[0:3], v[172:175], v[204:207], v[0:3]
	v_mfma_f32_16x16x32_bf16 v[52:55], v[168:171], v[184:187], v[52:55]
	v_mfma_f32_16x16x32_bf16 v[48:51], v[176:179], v[184:187], v[48:51]
	v_mfma_f32_16x16x32_bf16 v[36:39], v[168:171], v[192:195], v[36:39]
	v_mfma_f32_16x16x32_bf16 v[32:35], v[176:179], v[192:195], v[32:35]
	v_mfma_f32_16x16x32_bf16 v[20:23], v[168:171], v[200:203], v[20:23]
	v_mfma_f32_16x16x32_bf16 v[16:19], v[176:179], v[200:203], v[16:19]
	v_mfma_f32_16x16x32_bf16 v[4:7], v[168:171], v[208:211], v[4:7]
	v_mfma_f32_16x16x32_bf16 v[0:3], v[176:179], v[208:211], v[0:3]
	s_setprio 0
	s_barrier
	s_setprio 2
	s_add_i32 s72, s72, 2
	s_add_u32 s62, s62, 0x100
	s_addc_u32 s63, s63, 0
	s_add_u32 s70, s70, 0x100
	s_addc_u32 s71, s71, 0
	s_cmp_gt_u32 s72, 29
	s_cbranch_scc0 .LBB0_2713
	s_setprio 0
	s_and_b64 vcc, exec, s[58:59]
	s_cbranch_vccz .LBB0_2716
	s_barrier

.LBB0_2805:
	ds_read_b128 v[146:149], v155
	ds_read_b128 v[160:163], v155 offset:1024
	ds_read_b128 v[164:167], v155 offset:2048
	ds_read_b128 v[168:171], v155 offset:3072
	ds_read_b128 v[172:175], v156
	ds_read_b128 v[176:179], v156 offset:1024
	ds_read_b128 v[180:183], v156 offset:2048
	ds_read_b128 v[184:187], v156 offset:3072
	s_add_u32 s8, s48, 0xfff80080
	s_addc_u32 s9, s49, -1
	s_cmp_eq_u32 s67, 28
	s_cselect_b32 s61, s21, s9
	s_cselect_b32 s60, s43, s8
	s_cselect_b32 s57, s19, s66
	s_cselect_b32 s56, s45, s65
	v_lshl_add_u64 v[220:221], s[48:49], 0, v[138:139]
	s_add_i32 m0, s29, 0xc000
	ds_read_b128 v[188:191], v157
	ds_read_b128 v[192:195], v157 offset:1024
	ds_read_b128 v[196:199], v157 offset:2048
	ds_read_b128 v[200:203], v157 offset:3072
	ds_read_b128 v[204:207], v157 offset:4096
	ds_read_b128 v[208:211], v157 offset:5120
	ds_read_b128 v[212:215], v157 offset:6144
	ds_read_b128 v[216:219], v157 offset:7168
	global_load_lds_dwordx4 v[220:221], off
	v_lshl_add_u64 v[220:221], s[48:49], 0, v[140:141]
	s_add_i32 m0, s29, 0xe000
	s_nop 0
	global_load_lds_dwordx4 v[220:221], off
	s_waitcnt vmcnt(8)
	s_waitcnt lgkmcnt(0)
	s_barrier
	s_setprio 1
	s_waitcnt lgkmcnt(0)
	v_mfma_f32_16x16x32_bf16 v[124:127], v[146:149], v[188:191], v[124:127]
	v_mfma_f32_16x16x32_bf16 v[120:123], v[164:167], v[188:191], v[120:123]
	v_mfma_f32_16x16x32_bf16 v[108:111], v[146:149], v[196:199], v[108:111]
	v_mfma_f32_16x16x32_bf16 v[104:107], v[164:167], v[196:199], v[104:107]
	v_mfma_f32_16x16x32_bf16 v[92:95], v[146:149], v[204:207], v[92:95]
	v_mfma_f32_16x16x32_bf16 v[88:91], v[164:167], v[204:207], v[88:91]
	v_mfma_f32_16x16x32_bf16 v[76:79], v[146:149], v[212:215], v[76:79]
	v_mfma_f32_16x16x32_bf16 v[72:75], v[164:167], v[212:215], v[72:75]
	v_mfma_f32_16x16x32_bf16 v[124:127], v[160:163], v[192:195], v[124:127]
	v_mfma_f32_16x16x32_bf16 v[120:123], v[168:171], v[192:195], v[120:123]
	v_mfma_f32_16x16x32_bf16 v[108:111], v[160:163], v[200:203], v[108:111]
	v_mfma_f32_16x16x32_bf16 v[104:107], v[168:171], v[200:203], v[104:107]
	v_mfma_f32_16x16x32_bf16 v[92:95], v[160:163], v[208:211], v[92:95]
	v_mfma_f32_16x16x32_bf16 v[88:91], v[168:171], v[208:211], v[88:91]
	v_mfma_f32_16x16x32_bf16 v[76:79], v[160:163], v[216:219], v[76:79]
	v_mfma_f32_16x16x32_bf16 v[72:75], v[168:171], v[216:219], v[72:75]
	v_mfma_f32_16x16x32_bf16 v[116:119], v[172:175], v[188:191], v[116:119]
	v_mfma_f32_16x16x32_bf16 v[112:115], v[180:183], v[188:191], v[112:115]
	v_mfma_f32_16x16x32_bf16 v[100:103], v[172:175], v[196:199], v[100:103]
	v_mfma_f32_16x16x32_bf16 v[96:99], v[180:183], v[196:199], v[96:99]
	v_mfma_f32_16x16x32_bf16 v[84:87], v[172:175], v[204:207], v[84:87]
	v_mfma_f32_16x16x32_bf16 v[80:83], v[180:183], v[204:207], v[80:83]
	v_mfma_f32_16x16x32_bf16 v[68:71], v[172:175], v[212:215], v[68:71]
	v_mfma_f32_16x16x32_bf16 v[64:67], v[180:183], v[212:215], v[64:67]
	v_mfma_f32_16x16x32_bf16 v[116:119], v[176:179], v[192:195], v[116:119]
	v_mfma_f32_16x16x32_bf16 v[112:115], v[184:187], v[192:195], v[112:115]
	v_mfma_f32_16x16x32_bf16 v[100:103], v[176:179], v[200:203], v[100:103]
	v_mfma_f32_16x16x32_bf16 v[96:99], v[184:187], v[200:203], v[96:99]
	v_mfma_f32_16x16x32_bf16 v[84:87], v[176:179], v[208:211], v[84:87]
	v_mfma_f32_16x16x32_bf16 v[80:83], v[184:187], v[208:211], v[80:83]
	v_mfma_f32_16x16x32_bf16 v[68:71], v[176:179], v[216:219], v[68:71]
	v_mfma_f32_16x16x32_bf16 v[64:67], v[184:187], v[216:219], v[64:67]
	s_setprio 0
	s_barrier
	s_setprio 2
	s_add_i32 s8, s63, s94
	v_lshl_add_u64 v[220:221], s[56:57], 0, v[130:131]
	s_mov_b32 m0, s8
	ds_read_b128 v[188:191], v157 offset:16384
	ds_read_b128 v[192:195], v157 offset:17408
	ds_read_b128 v[196:199], v157 offset:18432
	ds_read_b128 v[200:203], v157 offset:19456
	ds_read_b128 v[204:207], v157 offset:20480
	ds_read_b128 v[208:211], v157 offset:21504
	ds_read_b128 v[212:215], v157 offset:22528
	ds_read_b128 v[216:219], v157 offset:23552
	global_load_lds_dwordx4 v[220:221], off
	s_add_i32 m0, s8, 0x2000
	s_add_u32 s68, s56, 0x80000
	v_lshl_add_u64 v[222:223], s[56:57], 0, v[134:135]
	s_addc_u32 s69, s57, 0
	s_add_i32 s8, s64, s94
	global_load_lds_dwordx4 v[222:223], off
	v_lshl_add_u64 v[224:225], s[68:69], 0, v[130:131]
	s_mov_b32 m0, s8
	v_lshl_add_u64 v[226:227], s[60:61], 0, v[132:133]
	global_load_lds_dwordx4 v[224:225], off
	v_lshl_add_u64 v[224:225], s[68:69], 0, v[134:135]
	s_add_i32 m0, s8, 0x2000
	s_nop 0
	global_load_lds_dwordx4 v[224:225], off
	v_lshl_add_u64 v[224:225], s[60:61], 0, v[128:129]
	s_mov_b32 m0, s29
	s_nop 0
	global_load_lds_dwordx4 v[224:225], off
	s_mov_b32 m0, s30
	s_nop 0
	global_load_lds_dwordx4 v[226:227], off
	s_setprio 0
	s_waitcnt vmcnt(8)
	s_waitcnt lgkmcnt(0)
	s_barrier
	s_setprio 1
	s_waitcnt lgkmcnt(0)
	v_mfma_f32_16x16x32_bf16 v[60:63], v[146:149], v[188:191], v[60:63]
	v_mfma_f32_16x16x32_bf16 v[56:59], v[164:167], v[188:191], v[56:59]
	v_mfma_f32_16x16x32_bf16 v[44:47], v[146:149], v[196:199], v[44:47]
	v_mfma_f32_16x16x32_bf16 v[40:43], v[164:167], v[196:199], v[40:43]
	v_mfma_f32_16x16x32_bf16 v[28:31], v[146:149], v[204:207], v[28:31]
	v_mfma_f32_16x16x32_bf16 v[24:27], v[164:167], v[204:207], v[24:27]
	v_mfma_f32_16x16x32_bf16 v[12:15], v[146:149], v[212:215], v[12:15]
	v_mfma_f32_16x16x32_bf16 v[8:11], v[164:167], v[212:215], v[8:11]
	v_mfma_f32_16x16x32_bf16 v[60:63], v[160:163], v[192:195], v[60:63]
	v_mfma_f32_16x16x32_bf16 v[56:59], v[168:171], v[192:195], v[56:59]
	v_mfma_f32_16x16x32_bf16 v[44:47], v[160:163], v[200:203], v[44:47]
	v_mfma_f32_16x16x32_bf16 v[40:43], v[168:171], v[200:203], v[40:43]
	v_mfma_f32_16x16x32_bf16 v[28:31], v[160:163], v[208:211], v[28:31]
	v_mfma_f32_16x16x32_bf16 v[24:27], v[168:171], v[208:211], v[24:27]
	v_mfma_f32_16x16x32_bf16 v[12:15], v[160:163], v[216:219], v[12:15]
	v_mfma_f32_16x16x32_bf16 v[8:11], v[168:171], v[216:219], v[8:11]
	v_mfma_f32_16x16x32_bf16 v[52:55], v[172:175], v[188:191], v[52:55]
	v_mfma_f32_16x16x32_bf16 v[48:51], v[180:183], v[188:191], v[48:51]
	v_mfma_f32_16x16x32_bf16 v[36:39], v[172:175], v[196:199], v[36:39]
	v_mfma_f32_16x16x32_bf16 v[32:35], v[180:183], v[196:199], v[32:35]
	v_mfma_f32_16x16x32_bf16 v[20:23], v[172:175], v[204:207], v[20:23]
	v_mfma_f32_16x16x32_bf16 v[16:19], v[180:183], v[204:207], v[16:19]
	v_mfma_f32_16x16x32_bf16 v[4:7], v[172:175], v[212:215], v[4:7]
	v_mfma_f32_16x16x32_bf16 v[0:3], v[180:183], v[212:215], v[0:3]
	v_mfma_f32_16x16x32_bf16 v[52:55], v[176:179], v[192:195], v[52:55]
	v_mfma_f32_16x16x32_bf16 v[48:51], v[184:187], v[192:195], v[48:51]
	v_mfma_f32_16x16x32_bf16 v[36:39], v[176:179], v[200:203], v[36:39]
	v_mfma_f32_16x16x32_bf16 v[32:35], v[184:187], v[200:203], v[32:35]
	v_mfma_f32_16x16x32_bf16 v[20:23], v[176:179], v[208:211], v[20:23]
	v_mfma_f32_16x16x32_bf16 v[16:19], v[184:187], v[208:211], v[16:19]
	v_mfma_f32_16x16x32_bf16 v[4:7], v[176:179], v[216:219], v[4:7]
	v_mfma_f32_16x16x32_bf16 v[0:3], v[184:187], v[216:219], v[0:3]
	s_setprio 0
	s_barrier
	s_setprio 2
	s_add_i32 s8, 0, 0x18000
	v_add_u32_e32 v159, s8, v151
	s_add_i32 s9, 0, 0x1c000
	ds_read_b128 v[146:149], v159
	ds_read_b128 v[160:163], v159 offset:1024
	ds_read_b128 v[164:167], v159 offset:2048
	ds_read_b128 v[168:171], v159 offset:3072
	v_add_u32_e32 v159, s9, v151
	ds_read_b128 v[172:175], v159
	ds_read_b128 v[176:179], v159 offset:1024
	ds_read_b128 v[180:183], v159 offset:2048
	ds_read_b128 v[184:187], v159 offset:3072
	s_add_u32 s60, s60, 0x80000
	s_addc_u32 s61, s61, 0
	s_mov_b32 m0, s34
	v_lshl_add_u64 v[228:229], s[60:61], 0, v[128:129]
	ds_read_b128 v[188:191], v157 offset:32768
	ds_read_b128 v[192:195], v157 offset:33792
	ds_read_b128 v[196:199], v157 offset:34816
	ds_read_b128 v[200:203], v157 offset:35840
	ds_read_b128 v[204:207], v157 offset:36864
	ds_read_b128 v[208:211], v157 offset:37888
	ds_read_b128 v[212:215], v157 offset:38912
	ds_read_b128 v[216:219], v157 offset:39936
	global_load_lds_dwordx4 v[228:229], off
	v_lshl_add_u64 v[228:229], s[60:61], 0, v[132:133]
	s_mov_b32 m0, s35
	s_nop 0
	global_load_lds_dwordx4 v[228:229], off
	s_setprio 0
	s_waitcnt vmcnt(8)
	s_waitcnt lgkmcnt(0)
	s_barrier
	s_setprio 1
	s_waitcnt lgkmcnt(0)
	v_mfma_f32_16x16x32_bf16 v[124:127], v[146:149], v[188:191], v[124:127]
	v_mfma_f32_16x16x32_bf16 v[120:123], v[164:167], v[188:191], v[120:123]
	v_mfma_f32_16x16x32_bf16 v[108:111], v[146:149], v[196:199], v[108:111]
	v_mfma_f32_16x16x32_bf16 v[104:107], v[164:167], v[196:199], v[104:107]
	v_mfma_f32_16x16x32_bf16 v[92:95], v[146:149], v[204:207], v[92:95]
	v_mfma_f32_16x16x32_bf16 v[88:91], v[164:167], v[204:207], v[88:91]
	v_mfma_f32_16x16x32_bf16 v[76:79], v[146:149], v[212:215], v[76:79]
	v_mfma_f32_16x16x32_bf16 v[72:75], v[164:167], v[212:215], v[72:75]
	v_mfma_f32_16x16x32_bf16 v[124:127], v[160:163], v[192:195], v[124:127]
	v_mfma_f32_16x16x32_bf16 v[120:123], v[168:171], v[192:195], v[120:123]
	v_mfma_f32_16x16x32_bf16 v[108:111], v[160:163], v[200:203], v[108:111]
	v_mfma_f32_16x16x32_bf16 v[104:107], v[168:171], v[200:203], v[104:107]
	v_mfma_f32_16x16x32_bf16 v[92:95], v[160:163], v[208:211], v[92:95]
	v_mfma_f32_16x16x32_bf16 v[88:91], v[168:171], v[208:211], v[88:91]
	v_mfma_f32_16x16x32_bf16 v[76:79], v[160:163], v[216:219], v[76:79]
	v_mfma_f32_16x16x32_bf16 v[72:75], v[168:171], v[216:219], v[72:75]
	v_mfma_f32_16x16x32_bf16 v[116:119], v[172:175], v[188:191], v[116:119]
	v_mfma_f32_16x16x32_bf16 v[112:115], v[180:183], v[188:191], v[112:115]
	v_mfma_f32_16x16x32_bf16 v[100:103], v[172:175], v[196:199], v[100:103]
	v_mfma_f32_16x16x32_bf16 v[96:99], v[180:183], v[196:199], v[96:99]
	v_mfma_f32_16x16x32_bf16 v[84:87], v[172:175], v[204:207], v[84:87]
	v_mfma_f32_16x16x32_bf16 v[80:83], v[180:183], v[204:207], v[80:83]
	v_mfma_f32_16x16x32_bf16 v[68:71], v[172:175], v[212:215], v[68:71]
	v_mfma_f32_16x16x32_bf16 v[64:67], v[180:183], v[212:215], v[64:67]
	v_mfma_f32_16x16x32_bf16 v[116:119], v[176:179], v[192:195], v[116:119]
	v_mfma_f32_16x16x32_bf16 v[112:115], v[184:187], v[192:195], v[112:115]
	v_mfma_f32_16x16x32_bf16 v[100:103], v[176:179], v[200:203], v[100:103]
	v_mfma_f32_16x16x32_bf16 v[96:99], v[184:187], v[200:203], v[96:99]
	v_mfma_f32_16x16x32_bf16 v[84:87], v[176:179], v[208:211], v[84:87]
	v_mfma_f32_16x16x32_bf16 v[80:83], v[184:187], v[208:211], v[80:83]
	v_mfma_f32_16x16x32_bf16 v[68:71], v[176:179], v[216:219], v[68:71]
	v_mfma_f32_16x16x32_bf16 v[64:67], v[184:187], v[216:219], v[64:67]
	s_setprio 0
	s_barrier
	s_setprio 2
	s_add_i32 s8, s8, s94
	v_lshl_add_u64 v[220:221], v[220:221], 0, s[16:17]
	s_mov_b32 m0, s8
	ds_read_b128 v[188:191], v157 offset:49152
	ds_read_b128 v[192:195], v157 offset:50176
	ds_read_b128 v[196:199], v157 offset:51200
	ds_read_b128 v[200:203], v157 offset:52224
	ds_read_b128 v[204:207], v157 offset:53248
	ds_read_b128 v[208:211], v157 offset:54272
	ds_read_b128 v[212:215], v157 offset:55296
	ds_read_b128 v[216:219], v157 offset:56320
	global_load_lds_dwordx4 v[220:221], off
	s_add_i32 m0, s8, 0x2000
	s_add_u32 s56, s56, 0x80080
	v_lshl_add_u64 v[220:221], v[222:223], 0, s[16:17]
	s_addc_u32 s57, s57, 0
	s_add_i32 s8, s9, s94
	global_load_lds_dwordx4 v[220:221], off
	v_lshl_add_u64 v[220:221], s[56:57], 0, v[130:131]
	s_mov_b32 m0, s8
	s_nop 0
	global_load_lds_dwordx4 v[220:221], off
	v_lshl_add_u64 v[220:221], s[56:57], 0, v[134:135]
	s_add_i32 m0, s8, 0x2000
	s_nop 0
	global_load_lds_dwordx4 v[220:221], off
	v_lshl_add_u64 v[220:221], v[224:225], 0, s[16:17]
	s_mov_b32 m0, s47
	s_nop 0
	global_load_lds_dwordx4 v[220:221], off
	v_lshl_add_u64 v[220:221], v[226:227], 0, s[16:17]
	s_mov_b32 m0, s62
	s_nop 0
	global_load_lds_dwordx4 v[220:221], off
	s_setprio 0
	s_waitcnt vmcnt(8)
	s_waitcnt lgkmcnt(0)
	s_barrier
	s_setprio 1
	s_waitcnt lgkmcnt(0)
	v_mfma_f32_16x16x32_bf16 v[60:63], v[146:149], v[188:191], v[60:63]
	v_mfma_f32_16x16x32_bf16 v[56:59], v[164:167], v[188:191], v[56:59]
	v_mfma_f32_16x16x32_bf16 v[44:47], v[146:149], v[196:199], v[44:47]
	v_mfma_f32_16x16x32_bf16 v[40:43], v[164:167], v[196:199], v[40:43]
	v_mfma_f32_16x16x32_bf16 v[28:31], v[146:149], v[204:207], v[28:31]
	v_mfma_f32_16x16x32_bf16 v[24:27], v[164:167], v[204:207], v[24:27]
	v_mfma_f32_16x16x32_bf16 v[12:15], v[146:149], v[212:215], v[12:15]
	v_mfma_f32_16x16x32_bf16 v[8:11], v[164:167], v[212:215], v[8:11]
	v_mfma_f32_16x16x32_bf16 v[60:63], v[160:163], v[192:195], v[60:63]
	v_mfma_f32_16x16x32_bf16 v[56:59], v[168:171], v[192:195], v[56:59]
	v_mfma_f32_16x16x32_bf16 v[44:47], v[160:163], v[200:203], v[44:47]
	v_mfma_f32_16x16x32_bf16 v[40:43], v[168:171], v[200:203], v[40:43]
	v_mfma_f32_16x16x32_bf16 v[28:31], v[160:163], v[208:211], v[28:31]
	v_mfma_f32_16x16x32_bf16 v[24:27], v[168:171], v[208:211], v[24:27]
	v_mfma_f32_16x16x32_bf16 v[12:15], v[160:163], v[216:219], v[12:15]
	v_mfma_f32_16x16x32_bf16 v[8:11], v[168:171], v[216:219], v[8:11]
	v_mfma_f32_16x16x32_bf16 v[52:55], v[172:175], v[188:191], v[52:55]
	v_mfma_f32_16x16x32_bf16 v[48:51], v[180:183], v[188:191], v[48:51]
	v_mfma_f32_16x16x32_bf16 v[36:39], v[172:175], v[196:199], v[36:39]
	v_mfma_f32_16x16x32_bf16 v[32:35], v[180:183], v[196:199], v[32:35]
	v_mfma_f32_16x16x32_bf16 v[20:23], v[172:175], v[204:207], v[20:23]
	v_mfma_f32_16x16x32_bf16 v[16:19], v[180:183], v[204:207], v[16:19]
	v_mfma_f32_16x16x32_bf16 v[4:7], v[172:175], v[212:215], v[4:7]
	v_mfma_f32_16x16x32_bf16 v[0:3], v[180:183], v[212:215], v[0:3]
	v_mfma_f32_16x16x32_bf16 v[52:55], v[176:179], v[192:195], v[52:55]
	v_mfma_f32_16x16x32_bf16 v[48:51], v[184:187], v[192:195], v[48:51]
	v_mfma_f32_16x16x32_bf16 v[36:39], v[176:179], v[200:203], v[36:39]
	v_mfma_f32_16x16x32_bf16 v[32:35], v[184:187], v[200:203], v[32:35]
	v_mfma_f32_16x16x32_bf16 v[20:23], v[176:179], v[208:211], v[20:23]
	v_mfma_f32_16x16x32_bf16 v[16:19], v[184:187], v[208:211], v[16:19]
	v_mfma_f32_16x16x32_bf16 v[4:7], v[176:179], v[216:219], v[4:7]
	v_mfma_f32_16x16x32_bf16 v[0:3], v[184:187], v[216:219], v[0:3]
	s_setprio 0
	s_barrier
	s_setprio 2
	s_add_i32 s67, s67, 2
	s_add_u32 s48, s48, 0x100
	s_addc_u32 s49, s49, 0
	s_add_u32 s65, s65, 0x100
	s_addc_u32 s66, s66, 0
	s_cmp_gt_u32 s67, 29
	s_cbranch_scc0 .LBB0_2805
	s_setprio 0
	s_and_b64 vcc, exec, s[58:59]
	s_cbranch_vccz .LBB0_2808
	s_barrier

.LBB0_2917:
	ds_read_b128 v[140:143], v149
	ds_read_b128 v[152:155], v149 offset:1024
	ds_read_b128 v[156:159], v149 offset:2048
	ds_read_b128 v[160:163], v149 offset:3072
	ds_read_b128 v[164:167], v150
	ds_read_b128 v[168:171], v150 offset:1024
	ds_read_b128 v[172:175], v150 offset:2048
	ds_read_b128 v[176:179], v150 offset:3072
	s_add_u32 s42, s40, 0xffe00080
	s_addc_u32 s43, s41, -1
	s_cmpk_eq_i32 s64, 0x7c
	s_cselect_b32 s45, s21, s43
	s_cselect_b32 s44, s39, s42
	s_cselect_b32 s43, s19, s63
	s_cselect_b32 s42, s61, s62
	v_lshl_add_u64 v[212:213], s[40:41], 0, v[132:133]
	s_add_i32 m0, s29, 0xc000
	ds_read_b128 v[180:183], v151
	ds_read_b128 v[184:187], v151 offset:1024
	ds_read_b128 v[188:191], v151 offset:2048
	ds_read_b128 v[192:195], v151 offset:3072
	ds_read_b128 v[196:199], v151 offset:4096
	ds_read_b128 v[200:203], v151 offset:5120
	ds_read_b128 v[204:207], v151 offset:6144
	ds_read_b128 v[208:211], v151 offset:7168
	global_load_lds_dwordx4 v[212:213], off
	v_lshl_add_u64 v[212:213], s[40:41], 0, v[134:135]
	s_add_i32 m0, s29, 0xe000
	s_nop 0
	global_load_lds_dwordx4 v[212:213], off
	s_waitcnt vmcnt(8)
	s_waitcnt lgkmcnt(0)
	s_barrier
	s_setprio 1
	s_waitcnt lgkmcnt(0)
	v_mfma_f32_16x16x32_bf16 v[124:127], v[140:143], v[180:183], v[124:127]
	v_mfma_f32_16x16x32_bf16 v[120:123], v[156:159], v[180:183], v[120:123]
	v_mfma_f32_16x16x32_bf16 v[108:111], v[140:143], v[188:191], v[108:111]
	v_mfma_f32_16x16x32_bf16 v[104:107], v[156:159], v[188:191], v[104:107]
	v_mfma_f32_16x16x32_bf16 v[92:95], v[140:143], v[196:199], v[92:95]
	v_mfma_f32_16x16x32_bf16 v[88:91], v[156:159], v[196:199], v[88:91]
	v_mfma_f32_16x16x32_bf16 v[76:79], v[140:143], v[204:207], v[76:79]
	v_mfma_f32_16x16x32_bf16 v[72:75], v[156:159], v[204:207], v[72:75]
	v_mfma_f32_16x16x32_bf16 v[124:127], v[152:155], v[184:187], v[124:127]
	v_mfma_f32_16x16x32_bf16 v[120:123], v[160:163], v[184:187], v[120:123]
	v_mfma_f32_16x16x32_bf16 v[108:111], v[152:155], v[192:195], v[108:111]
	v_mfma_f32_16x16x32_bf16 v[104:107], v[160:163], v[192:195], v[104:107]
	v_mfma_f32_16x16x32_bf16 v[92:95], v[152:155], v[200:203], v[92:95]
	v_mfma_f32_16x16x32_bf16 v[88:91], v[160:163], v[200:203], v[88:91]
	v_mfma_f32_16x16x32_bf16 v[76:79], v[152:155], v[208:211], v[76:79]
	v_mfma_f32_16x16x32_bf16 v[72:75], v[160:163], v[208:211], v[72:75]
	v_mfma_f32_16x16x32_bf16 v[116:119], v[164:167], v[180:183], v[116:119]
	v_mfma_f32_16x16x32_bf16 v[112:115], v[172:175], v[180:183], v[112:115]
	v_mfma_f32_16x16x32_bf16 v[100:103], v[164:167], v[188:191], v[100:103]
	v_mfma_f32_16x16x32_bf16 v[96:99], v[172:175], v[188:191], v[96:99]
	v_mfma_f32_16x16x32_bf16 v[84:87], v[164:167], v[196:199], v[84:87]
	v_mfma_f32_16x16x32_bf16 v[80:83], v[172:175], v[196:199], v[80:83]
	v_mfma_f32_16x16x32_bf16 v[68:71], v[164:167], v[204:207], v[68:71]
	v_mfma_f32_16x16x32_bf16 v[64:67], v[172:175], v[204:207], v[64:67]
	v_mfma_f32_16x16x32_bf16 v[116:119], v[168:171], v[184:187], v[116:119]
	v_mfma_f32_16x16x32_bf16 v[112:115], v[176:179], v[184:187], v[112:115]
	v_mfma_f32_16x16x32_bf16 v[100:103], v[168:171], v[192:195], v[100:103]
	v_mfma_f32_16x16x32_bf16 v[96:99], v[176:179], v[192:195], v[96:99]
	v_mfma_f32_16x16x32_bf16 v[84:87], v[168:171], v[200:203], v[84:87]
	v_mfma_f32_16x16x32_bf16 v[80:83], v[176:179], v[200:203], v[80:83]
	v_mfma_f32_16x16x32_bf16 v[68:71], v[168:171], v[208:211], v[68:71]
	v_mfma_f32_16x16x32_bf16 v[64:67], v[176:179], v[208:211], v[64:67]
	s_setprio 0
	s_barrier
	s_setprio 2
	s_add_i32 s65, s56, s94
	v_lshl_add_u64 v[212:213], s[42:43], 0, v[128:129]
	s_mov_b32 m0, s65
	ds_read_b128 v[180:183], v151 offset:16384
	ds_read_b128 v[184:187], v151 offset:17408
	ds_read_b128 v[188:191], v151 offset:18432
	ds_read_b128 v[192:195], v151 offset:19456
	ds_read_b128 v[196:199], v151 offset:20480
	ds_read_b128 v[200:203], v151 offset:21504
	ds_read_b128 v[204:207], v151 offset:22528
	ds_read_b128 v[208:211], v151 offset:23552
	global_load_lds_dwordx4 v[212:213], off
	s_add_i32 m0, s65, 0x2000
	s_add_u32 s66, s42, 0x200000
	v_lshl_add_u64 v[214:215], s[42:43], 0, v[130:131]
	s_addc_u32 s67, s43, 0
	s_add_i32 s65, s57, s94
	global_load_lds_dwordx4 v[214:215], off
	v_lshl_add_u64 v[216:217], s[66:67], 0, v[128:129]
	s_mov_b32 m0, s65
	v_lshl_add_u64 v[218:219], s[44:45], 0, v[130:131]
	global_load_lds_dwordx4 v[216:217], off
	v_lshl_add_u64 v[216:217], s[66:67], 0, v[130:131]
	s_add_i32 m0, s65, 0x2000
	s_nop 0
	global_load_lds_dwordx4 v[216:217], off
	v_lshl_add_u64 v[216:217], s[44:45], 0, v[128:129]
	s_mov_b32 m0, s29
	s_nop 0
	global_load_lds_dwordx4 v[216:217], off
	s_mov_b32 m0, s30
	s_nop 0
	global_load_lds_dwordx4 v[218:219], off
	s_setprio 0
	s_waitcnt vmcnt(8)
	s_waitcnt lgkmcnt(0)
	s_barrier
	s_setprio 1
	s_waitcnt lgkmcnt(0)
	v_mfma_f32_16x16x32_bf16 v[60:63], v[140:143], v[180:183], v[60:63]
	v_mfma_f32_16x16x32_bf16 v[56:59], v[156:159], v[180:183], v[56:59]
	v_mfma_f32_16x16x32_bf16 v[44:47], v[140:143], v[188:191], v[44:47]
	v_mfma_f32_16x16x32_bf16 v[40:43], v[156:159], v[188:191], v[40:43]
	v_mfma_f32_16x16x32_bf16 v[28:31], v[140:143], v[196:199], v[28:31]
	v_mfma_f32_16x16x32_bf16 v[24:27], v[156:159], v[196:199], v[24:27]
	v_mfma_f32_16x16x32_bf16 v[12:15], v[140:143], v[204:207], v[12:15]
	v_mfma_f32_16x16x32_bf16 v[8:11], v[156:159], v[204:207], v[8:11]
	v_mfma_f32_16x16x32_bf16 v[60:63], v[152:155], v[184:187], v[60:63]
	v_mfma_f32_16x16x32_bf16 v[56:59], v[160:163], v[184:187], v[56:59]
	v_mfma_f32_16x16x32_bf16 v[44:47], v[152:155], v[192:195], v[44:47]
	v_mfma_f32_16x16x32_bf16 v[40:43], v[160:163], v[192:195], v[40:43]
	v_mfma_f32_16x16x32_bf16 v[28:31], v[152:155], v[200:203], v[28:31]
	v_mfma_f32_16x16x32_bf16 v[24:27], v[160:163], v[200:203], v[24:27]
	v_mfma_f32_16x16x32_bf16 v[12:15], v[152:155], v[208:211], v[12:15]
	v_mfma_f32_16x16x32_bf16 v[8:11], v[160:163], v[208:211], v[8:11]
	v_mfma_f32_16x16x32_bf16 v[52:55], v[164:167], v[180:183], v[52:55]
	v_mfma_f32_16x16x32_bf16 v[48:51], v[172:175], v[180:183], v[48:51]
	v_mfma_f32_16x16x32_bf16 v[36:39], v[164:167], v[188:191], v[36:39]
	v_mfma_f32_16x16x32_bf16 v[32:35], v[172:175], v[188:191], v[32:35]
	v_mfma_f32_16x16x32_bf16 v[20:23], v[164:167], v[196:199], v[20:23]
	v_mfma_f32_16x16x32_bf16 v[16:19], v[172:175], v[196:199], v[16:19]
	v_mfma_f32_16x16x32_bf16 v[4:7], v[164:167], v[204:207], v[4:7]
	v_mfma_f32_16x16x32_bf16 v[0:3], v[172:175], v[204:207], v[0:3]
	v_mfma_f32_16x16x32_bf16 v[52:55], v[168:171], v[184:187], v[52:55]
	v_mfma_f32_16x16x32_bf16 v[48:51], v[176:179], v[184:187], v[48:51]
	v_mfma_f32_16x16x32_bf16 v[36:39], v[168:171], v[192:195], v[36:39]
	v_mfma_f32_16x16x32_bf16 v[32:35], v[176:179], v[192:195], v[32:35]
	v_mfma_f32_16x16x32_bf16 v[20:23], v[168:171], v[200:203], v[20:23]
	v_mfma_f32_16x16x32_bf16 v[16:19], v[176:179], v[200:203], v[16:19]
	v_mfma_f32_16x16x32_bf16 v[4:7], v[168:171], v[208:211], v[4:7]
	v_mfma_f32_16x16x32_bf16 v[0:3], v[176:179], v[208:211], v[0:3]
	s_setprio 0
	s_barrier
	s_setprio 2
	s_add_i32 s65, 0, 0x18000
	s_add_i32 s66, 0, 0x1c000
	v_add_u32_e32 v160, s65, v145
	v_add_u32_e32 v176, s66, v145
	ds_read_b128 v[140:143], v160
	ds_read_b128 v[152:155], v160 offset:1024
	ds_read_b128 v[156:159], v160 offset:2048
	ds_read_b128 v[160:163], v160 offset:3072
	ds_read_b128 v[164:167], v176
	ds_read_b128 v[168:171], v176 offset:1024
	ds_read_b128 v[172:175], v176 offset:2048
	ds_read_b128 v[176:179], v176 offset:3072
	s_add_u32 s44, s44, 0x200000
	s_addc_u32 s45, s45, 0
	s_mov_b32 m0, s46
	v_lshl_add_u64 v[220:221], s[44:45], 0, v[128:129]
	ds_read_b128 v[180:183], v151 offset:32768
	ds_read_b128 v[184:187], v151 offset:33792
	ds_read_b128 v[188:191], v151 offset:34816
	ds_read_b128 v[192:195], v151 offset:35840
	ds_read_b128 v[196:199], v151 offset:36864
	ds_read_b128 v[200:203], v151 offset:37888
	ds_read_b128 v[204:207], v151 offset:38912
	ds_read_b128 v[208:211], v151 offset:39936
	global_load_lds_dwordx4 v[220:221], off
	v_lshl_add_u64 v[220:221], s[44:45], 0, v[130:131]
	s_mov_b32 m0, s47
	s_nop 0
	global_load_lds_dwordx4 v[220:221], off
	s_setprio 0
	s_waitcnt vmcnt(8)
	s_waitcnt lgkmcnt(0)
	s_barrier
	s_setprio 1
	s_waitcnt lgkmcnt(0)
	v_mfma_f32_16x16x32_bf16 v[124:127], v[140:143], v[180:183], v[124:127]
	v_mfma_f32_16x16x32_bf16 v[120:123], v[156:159], v[180:183], v[120:123]
	v_mfma_f32_16x16x32_bf16 v[108:111], v[140:143], v[188:191], v[108:111]
	v_mfma_f32_16x16x32_bf16 v[104:107], v[156:159], v[188:191], v[104:107]
	v_mfma_f32_16x16x32_bf16 v[92:95], v[140:143], v[196:199], v[92:95]
	v_mfma_f32_16x16x32_bf16 v[88:91], v[156:159], v[196:199], v[88:91]
	v_mfma_f32_16x16x32_bf16 v[76:79], v[140:143], v[204:207], v[76:79]
	v_mfma_f32_16x16x32_bf16 v[72:75], v[156:159], v[204:207], v[72:75]
	v_mfma_f32_16x16x32_bf16 v[124:127], v[152:155], v[184:187], v[124:127]
	v_mfma_f32_16x16x32_bf16 v[120:123], v[160:163], v[184:187], v[120:123]
	v_mfma_f32_16x16x32_bf16 v[108:111], v[152:155], v[192:195], v[108:111]
	v_mfma_f32_16x16x32_bf16 v[104:107], v[160:163], v[192:195], v[104:107]
	v_mfma_f32_16x16x32_bf16 v[92:95], v[152:155], v[200:203], v[92:95]
	v_mfma_f32_16x16x32_bf16 v[88:91], v[160:163], v[200:203], v[88:91]
	v_mfma_f32_16x16x32_bf16 v[76:79], v[152:155], v[208:211], v[76:79]
	v_mfma_f32_16x16x32_bf16 v[72:75], v[160:163], v[208:211], v[72:75]
	v_mfma_f32_16x16x32_bf16 v[116:119], v[164:167], v[180:183], v[116:119]
	v_mfma_f32_16x16x32_bf16 v[112:115], v[172:175], v[180:183], v[112:115]
	v_mfma_f32_16x16x32_bf16 v[100:103], v[164:167], v[188:191], v[100:103]
	v_mfma_f32_16x16x32_bf16 v[96:99], v[172:175], v[188:191], v[96:99]
	v_mfma_f32_16x16x32_bf16 v[84:87], v[164:167], v[196:199], v[84:87]
	v_mfma_f32_16x16x32_bf16 v[80:83], v[172:175], v[196:199], v[80:83]
	v_mfma_f32_16x16x32_bf16 v[68:71], v[164:167], v[204:207], v[68:71]
	v_mfma_f32_16x16x32_bf16 v[64:67], v[172:175], v[204:207], v[64:67]
	v_mfma_f32_16x16x32_bf16 v[116:119], v[168:171], v[184:187], v[116:119]
	v_mfma_f32_16x16x32_bf16 v[112:115], v[176:179], v[184:187], v[112:115]
	v_mfma_f32_16x16x32_bf16 v[100:103], v[168:171], v[192:195], v[100:103]
	v_mfma_f32_16x16x32_bf16 v[96:99], v[176:179], v[192:195], v[96:99]
	v_mfma_f32_16x16x32_bf16 v[84:87], v[168:171], v[200:203], v[84:87]
	v_mfma_f32_16x16x32_bf16 v[80:83], v[176:179], v[200:203], v[80:83]
	v_mfma_f32_16x16x32_bf16 v[68:71], v[168:171], v[208:211], v[68:71]
	v_mfma_f32_16x16x32_bf16 v[64:67], v[176:179], v[208:211], v[64:67]
	s_setprio 0
	s_barrier
	s_setprio 2
	s_add_i32 s44, s65, s94
	v_lshl_add_u64 v[212:213], v[212:213], 0, s[16:17]
	s_mov_b32 m0, s44
	ds_read_b128 v[180:183], v151 offset:49152
	ds_read_b128 v[184:187], v151 offset:50176
	ds_read_b128 v[188:191], v151 offset:51200
	ds_read_b128 v[192:195], v151 offset:52224
	ds_read_b128 v[196:199], v151 offset:53248
	ds_read_b128 v[200:203], v151 offset:54272
	ds_read_b128 v[204:207], v151 offset:55296
	ds_read_b128 v[208:211], v151 offset:56320
	global_load_lds_dwordx4 v[212:213], off
	s_add_i32 m0, s44, 0x2000
	s_add_u32 s42, s42, 0x200080
	v_lshl_add_u64 v[212:213], v[214:215], 0, s[16:17]
	s_addc_u32 s43, s43, 0
	s_add_i32 s44, s66, s94
	global_load_lds_dwordx4 v[212:213], off
	v_lshl_add_u64 v[212:213], s[42:43], 0, v[128:129]
	s_mov_b32 m0, s44
	s_nop 0
	global_load_lds_dwordx4 v[212:213], off
	v_lshl_add_u64 v[212:213], s[42:43], 0, v[130:131]
	s_add_i32 m0, s44, 0x2000
	s_nop 0
	global_load_lds_dwordx4 v[212:213], off
	v_lshl_add_u64 v[212:213], v[216:217], 0, s[16:17]
	s_mov_b32 m0, s48
	s_nop 0
	global_load_lds_dwordx4 v[212:213], off
	v_lshl_add_u64 v[212:213], v[218:219], 0, s[16:17]
	s_mov_b32 m0, s49
	s_nop 0
	global_load_lds_dwordx4 v[212:213], off
	s_setprio 0
	s_waitcnt vmcnt(8)
	s_waitcnt lgkmcnt(0)
	s_barrier
	s_setprio 1
	s_waitcnt lgkmcnt(0)
	v_mfma_f32_16x16x32_bf16 v[60:63], v[140:143], v[180:183], v[60:63]
	v_mfma_f32_16x16x32_bf16 v[56:59], v[156:159], v[180:183], v[56:59]
	v_mfma_f32_16x16x32_bf16 v[44:47], v[140:143], v[188:191], v[44:47]
	v_mfma_f32_16x16x32_bf16 v[40:43], v[156:159], v[188:191], v[40:43]
	v_mfma_f32_16x16x32_bf16 v[28:31], v[140:143], v[196:199], v[28:31]
	v_mfma_f32_16x16x32_bf16 v[24:27], v[156:159], v[196:199], v[24:27]
	v_mfma_f32_16x16x32_bf16 v[12:15], v[140:143], v[204:207], v[12:15]
	v_mfma_f32_16x16x32_bf16 v[8:11], v[156:159], v[204:207], v[8:11]
	v_mfma_f32_16x16x32_bf16 v[60:63], v[152:155], v[184:187], v[60:63]
	v_mfma_f32_16x16x32_bf16 v[56:59], v[160:163], v[184:187], v[56:59]
	v_mfma_f32_16x16x32_bf16 v[44:47], v[152:155], v[192:195], v[44:47]
	v_mfma_f32_16x16x32_bf16 v[40:43], v[160:163], v[192:195], v[40:43]
	v_mfma_f32_16x16x32_bf16 v[28:31], v[152:155], v[200:203], v[28:31]
	v_mfma_f32_16x16x32_bf16 v[24:27], v[160:163], v[200:203], v[24:27]
	v_mfma_f32_16x16x32_bf16 v[12:15], v[152:155], v[208:211], v[12:15]
	v_mfma_f32_16x16x32_bf16 v[8:11], v[160:163], v[208:211], v[8:11]
	v_mfma_f32_16x16x32_bf16 v[52:55], v[164:167], v[180:183], v[52:55]
	v_mfma_f32_16x16x32_bf16 v[48:51], v[172:175], v[180:183], v[48:51]
	v_mfma_f32_16x16x32_bf16 v[36:39], v[164:167], v[188:191], v[36:39]
	v_mfma_f32_16x16x32_bf16 v[32:35], v[172:175], v[188:191], v[32:35]
	v_mfma_f32_16x16x32_bf16 v[20:23], v[164:167], v[196:199], v[20:23]
	v_mfma_f32_16x16x32_bf16 v[16:19], v[172:175], v[196:199], v[16:19]
	v_mfma_f32_16x16x32_bf16 v[4:7], v[164:167], v[204:207], v[4:7]
	v_mfma_f32_16x16x32_bf16 v[0:3], v[172:175], v[204:207], v[0:3]
	v_mfma_f32_16x16x32_bf16 v[52:55], v[168:171], v[184:187], v[52:55]
	v_mfma_f32_16x16x32_bf16 v[48:51], v[176:179], v[184:187], v[48:51]
	v_mfma_f32_16x16x32_bf16 v[36:39], v[168:171], v[192:195], v[36:39]
	v_mfma_f32_16x16x32_bf16 v[32:35], v[176:179], v[192:195], v[32:35]
	v_mfma_f32_16x16x32_bf16 v[20:23], v[168:171], v[200:203], v[20:23]
	v_mfma_f32_16x16x32_bf16 v[16:19], v[176:179], v[200:203], v[16:19]
	v_mfma_f32_16x16x32_bf16 v[4:7], v[168:171], v[208:211], v[4:7]
	v_mfma_f32_16x16x32_bf16 v[0:3], v[176:179], v[208:211], v[0:3]
	s_setprio 0
	s_barrier
	s_setprio 2
	s_add_i32 s64, s64, 2
	s_add_u32 s40, s40, 0x100
	s_addc_u32 s41, s41, 0
	s_add_u32 s62, s62, 0x100
	s_addc_u32 s63, s63, 0
	s_cmpk_gt_u32 s64, 0x7d
	s_cbranch_scc0 .LBB0_2917
	s_setprio 0
	s_and_b64 vcc, exec, s[58:59]
	s_cbranch_vccz .LBB0_2920
	s_barrier
